# GEMM K-loops: load segments run at raised priority and compute segments at base priority (swapped s_setprio), mid-cluster flips dropped, LDS-DMA loads use SGPR-base form (8 fewer 64-bit VALU adds per
# speedup vs baseline: 1.0156x; 1.0106x over previous
; __device__ __forceinline__ void rms_row_to_bf16(const float* xr, const float* g, bf16* orow, int lane) {
;     ...
;         const f32x4 g0 = *(const f32x4*)(g + j * 512 + lane * 8), g1 = *(const f32x4*)(g + j * 512 + lane * 8 + 4);
; __global__ void __launch_bounds__(NTHR, 2) fwd_megakernel(Args args) {
;     ...
;         for (int m = gw; m < M; m += NGW) {
;             const float* xr = (m < MP) ? x_prompt + (size_t)m * DM : x_sample + (size_t)(m - MP) * DM;
;             rms_row_to_bf16(xr, args.in[14], XN + (size_t)m * DM, lane);
;         }
.LBB0_239:
	s_or_b64 exec, exec, s[16:17]
	s_cmp_gt_i32 s86, 0x83ff
	s_cbranch_scc1 .LBB0_245
	v_mbcnt_lo_u32_b32 v1, -1, 0
	v_mbcnt_hi_u32_b32 v1, -1, v1
	v_and_b32_e32 v2, 64, v1
	v_add_u32_e32 v2, 64, v2
	v_xor_b32_e32 v3, 1, v1
	v_cmp_lt_i32_e32 vcc, v3, v2
	v_mov_b32_e32 v17, 0
	v_lshlrev_b32_e32 v16, 5, v164
	v_cndmask_b32_e32 v3, v1, v3, vcc
	v_lshlrev_b32_e32 v26, 2, v3
	v_xor_b32_e32 v3, 2, v1
	v_cmp_lt_i32_e32 vcc, v3, v2
	v_readlane_b32 s4, v240, 26
	s_ashr_i32 s87, s86, 31
	v_cndmask_b32_e32 v3, v1, v3, vcc
	v_lshlrev_b32_e32 v27, 2, v3
	v_xor_b32_e32 v3, 4, v1
	v_cmp_lt_i32_e32 vcc, v3, v2
	s_waitcnt lgkmcnt(0)
	v_lshl_add_u64 v[18:19], s[64:65], 0, v[16:17]
	v_lshlrev_b32_e32 v16, 4, v164
	v_cndmask_b32_e32 v3, v1, v3, vcc
	v_lshlrev_b32_e32 v28, 2, v3
	v_xor_b32_e32 v3, 8, v1
	v_cmp_lt_i32_e32 vcc, v3, v2
	v_readlane_b32 s5, v240, 27
	s_ashr_i32 s3, s2, 31
	v_cndmask_b32_e32 v3, v1, v3, vcc
	v_lshlrev_b32_e32 v29, 2, v3
	v_xor_b32_e32 v3, 16, v1
	v_cmp_lt_i32_e32 vcc, v3, v2
	s_lshl_b64 s[6:7], s[86:87], 13
	v_lshlrev_b32_e32 v0, 3, v164
	v_cndmask_b32_e32 v3, v1, v3, vcc
	v_lshlrev_b32_e32 v30, 2, v3
	v_xor_b32_e32 v3, 32, v1
	v_cmp_lt_i32_e32 vcc, v3, v2
	v_lshl_add_u64 v[20:21], s[4:5], 0, v[16:17]
	s_mov_b64 s[4:5], 0x1000
	v_cndmask_b32_e32 v1, v1, v3, vcc
	s_mov_b64 s[8:9], 0x1800
	s_add_u32 s12, s36, s6
	s_mov_b32 s1, 0
	v_lshlrev_b32_e32 v31, 2, v1
	v_lshl_add_u64 v[22:23], v[18:19], 0, s[4:5]
	v_lshl_add_u64 v[24:25], v[18:19], 0, s[8:9]
	s_addc_u32 s13, s37, s7
	s_lshl_b64 s[16:17], s[2:3], 13
	v_lshlrev_b32_e32 v16, 2, v0
	v_mov_b32_e32 v32, 0x358637bd
	s_mov_b32 s6, 0x800000
	s_mov_b64 s[18:19], s[86:87]
	global_load_dwordx4 v[170:173], v[18:19], off offset:16
	global_load_dwordx4 v[174:177], v[18:19], off
	global_load_dwordx4 v[178:181], v[18:19], off offset:2048
	global_load_dwordx4 v[182:185], v[18:19], off offset:2064
	global_load_dwordx4 v[186:189], v[22:23], off
	global_load_dwordx4 v[190:193], v[22:23], off offset:16
	global_load_dwordx4 v[194:197], v[24:25], off
	global_load_dwordx4 v[198:201], v[24:25], off offset:16
	s_branch .LBB0_242
; __device__ __forceinline__ unsigned pk2(float lo, float hi) { return pg8::cvt_pk_bf16(lo, hi); }
; __device__ __forceinline__ void rms_row_to_bf16(const float* xr, const float* g, bf16* orow, int lane) {
;     f32x4 v[8]; float s = 0.f;
; #pragma unroll
;     for (int j = 0; j < 4; ++j) { v[2 * j] = *(const f32x4*)(xr + j * 512 + lane * 8); v[2 * j + 1] = *(const f32x4*)(xr + j * 512 + lane * 8 + 4); }
; #pragma unroll
;     for (int j = 0; j < 8; ++j) s += (v[j].x * v[j].x + v[j].y * v[j].y) + (v[j].z * v[j].z + v[j].w * v[j].w);
;     const float rstd = rsqrtf(wave_sum(s) * (1.f / DM) + EPS);
; #pragma unroll
;     for (int j = 0; j < 4; ++j) {
;         const f32x4 g0 = *(const f32x4*)(g + j * 512 + lane * 8), g1 = *(const f32x4*)(g + j * 512 + lane * 8 + 4);
;         const f32x4 a = v[2 * j] * rstd * g0, b = v[2 * j + 1] * rstd * g1;
;         v4u o; o.x = pk2(a.x, a.y); o.y = pk2(a.z, a.w); o.z = pk2(b.x, b.y); o.w = pk2(b.z, b.w);
;         *(v4u*)(orow + j * 512 + lane * 8) = o;
;     }
.LBB0_241:
	v_lshl_add_u64 v[0:1], s[22:23], 0, v[16:17]
	global_load_dwordx4 v[34:37], v16, s[22:23]
	global_load_dwordx4 v[38:41], v16, s[22:23] offset:16
	global_load_dwordx4 v[42:45], v16, s[22:23] offset:2048
	global_load_dwordx4 v[46:49], v16, s[22:23] offset:2064
	v_add_co_u32_e32 v4, vcc, 0x1000, v0
	v_lshl_add_u64 v[2:3], v[0:1], 0, s[4:5]
	s_nop 0
	v_addc_co_u32_e32 v5, vcc, 0, v1, vcc
	global_load_dwordx4 v[12:15], v[4:5], off
	global_load_dwordx4 v[8:11], v[2:3], off offset:16
	v_lshl_add_u64 v[0:1], v[0:1], 0, s[8:9]
	global_load_dwordx4 v[0:3], v[0:1], off offset:16
	s_nop 0
	global_load_dwordx4 v[4:7], v[4:5], off offset:2048
	s_nop 0
	s_lshl_b64 s[20:21], s[20:21], 12
	s_add_u32 s18, s18, s2
	s_addc_u32 s19, s19, s3
	s_add_u32 s12, s12, s16
	s_addc_u32 s13, s13, s17
	s_cmp_lt_i32 s18, 0x8400
	s_waitcnt vmcnt(7)
	v_mov_b32_e32 v60, v35
	s_waitcnt vmcnt(6)
	v_mov_b32_e32 v61, v39
	v_mov_b32_e32 v64, v37
	v_mov_b32_e32 v65, v41
	v_mov_b32_e32 v58, v34
	v_mov_b32_e32 v59, v38
	v_mov_b32_e32 v62, v36
	v_mov_b32_e32 v63, v40
	s_waitcnt vmcnt(5)
	v_pk_mul_f32 v[66:67], v[44:45], v[44:45]
	v_pk_mul_f32 v[68:69], v[42:43], v[42:43]
	v_pk_mul_f32 v[60:61], v[60:61], v[60:61]
	v_pk_mul_f32 v[64:65], v[64:65], v[64:65]
	s_waitcnt vmcnt(4)
	v_mul_f32_e32 v70, v47, v47
	v_pk_mov_b32 v[74:75], v[68:69], v[66:67] op_sel:[1,0]
	v_mov_b32_e32 v69, v67
	v_pk_fma_f32 v[58:59], v[58:59], v[58:59], v[60:61]
	v_pk_fma_f32 v[60:61], v[62:63], v[62:63], v[64:65]
	v_mul_f32_e32 v72, v49, v49
	v_pk_fma_f32 v[66:67], v[46:47], v[46:47], v[70:71] op_sel_hi:[1,1,0]
	v_pk_add_f32 v[62:63], v[74:75], v[68:69]
	v_pk_add_f32 v[58:59], v[58:59], v[60:61]
	v_pk_fma_f32 v[70:71], v[48:49], v[48:49], v[72:73] op_sel_hi:[1,1,0]
	s_waitcnt vmcnt(3)
	v_mul_f32_e32 v33, v12, v12
	v_mul_f32_e32 v67, v13, v13
	v_mul_f32_e32 v69, v14, v14
	v_pk_add_f32 v[60:61], v[62:63], v[62:63] op_sel:[0,1] op_sel_hi:[1,0]
	v_pk_add_f32 v[58:59], v[58:59], v[58:59] op_sel:[0,1] op_sel_hi:[1,0]
	v_mul_f32_e32 v71, v15, v15
	s_waitcnt vmcnt(2)
	v_pk_mul_f32 v[62:63], v[10:11], v[10:11]
	v_pk_mul_f32 v[64:65], v[8:9], v[8:9]
	v_mov_b32_e32 v61, v67
	v_mov_b32_e32 v67, v69
	v_mov_b32_e32 v59, v33
	v_pk_mov_b32 v[74:75], v[64:65], v[62:63] op_sel:[1,0]
	v_mov_b32_e32 v65, v63
	v_pk_add_f32 v[66:67], v[66:67], v[70:71]
	v_pk_add_f32 v[58:59], v[58:59], v[60:61]
	s_waitcnt vmcnt(1)
	v_mul_f32_e32 v73, v0, v0
	s_waitcnt vmcnt(0)
	v_mul_f32_e32 v68, v5, v5
	v_mul_f32_e32 v72, v7, v7
	v_pk_add_f32 v[64:65], v[74:75], v[64:65]
	v_pk_add_f32 v[58:59], v[58:59], v[66:67]
	v_mul_f32_e32 v76, v1, v1
	v_mul_f32_e32 v77, v2, v2
	v_mul_f32_e32 v78, v3, v3
	v_pk_fma_f32 v[62:63], v[4:5], v[4:5], v[68:69] op_sel_hi:[1,1,0]
	v_pk_fma_f32 v[68:69], v[6:7], v[6:7], v[72:73] op_sel_hi:[1,1,0]
	v_pk_add_f32 v[60:61], v[64:65], v[64:65] op_sel:[0,1] op_sel_hi:[1,0]
	v_pk_add_f32 v[58:59], v[58:59], v[58:59] op_sel:[0,1] op_sel_hi:[1,0]
	v_mov_b32_e32 v63, v77
	v_mov_b32_e32 v69, v78
	v_mov_b32_e32 v61, v76
	v_mov_b32_e32 v59, v73
	v_pk_add_f32 v[62:63], v[62:63], v[68:69]
	v_pk_add_f32 v[58:59], v[58:59], v[60:61]
	s_nop 0
	v_pk_add_f32 v[58:59], v[58:59], v[62:63]
	s_nop 0
	v_add_f32_e32 v33, v58, v59
	ds_bpermute_b32 v58, v26, v33
	s_waitcnt lgkmcnt(0)
	v_add_f32_e32 v33, v33, v58
	ds_bpermute_b32 v58, v27, v33
	s_waitcnt lgkmcnt(0)
	v_add_f32_e32 v33, v33, v58
	ds_bpermute_b32 v58, v28, v33
	s_waitcnt lgkmcnt(0)
	v_add_f32_e32 v33, v33, v58
	ds_bpermute_b32 v58, v29, v33
	s_waitcnt lgkmcnt(0)
	v_add_f32_e32 v33, v33, v58
	ds_bpermute_b32 v58, v30, v33
	s_waitcnt lgkmcnt(0)
	v_add_f32_e32 v33, v33, v58
	ds_bpermute_b32 v58, v31, v33
	s_waitcnt lgkmcnt(0)
	v_add_f32_e32 v33, v33, v58
	v_fmamk_f32 v33, v33, 0x3a000000, v32
	v_mul_f32_e32 v58, 0x4b800000, v33
	v_cmp_gt_f32_e32 vcc, s6, v33
	s_nop 1
	v_cndmask_b32_e32 v33, v33, v58, vcc
	v_rsq_f32_e32 v33, v33
	v_lshl_add_u64 v[58:59], v[20:21], 0, s[20:21]
	v_mul_f32_e32 v60, 0x45800000, v33
	v_cndmask_b32_e32 v60, v33, v60, vcc
	v_pk_mul_f32 v[34:35], v[34:35], v[60:61] op_sel_hi:[1,0]
	v_pk_mul_f32 v[36:37], v[36:37], v[60:61] op_sel_hi:[1,0]
	v_pk_mul_f32 v[38:39], v[38:39], v[60:61] op_sel_hi:[1,0]
	v_pk_mul_f32 v[40:41], v[40:41], v[60:61] op_sel_hi:[1,0]
	s_waitcnt vmcnt(0)
	v_pk_mul_f32 v[36:37], v[176:177], v[36:37]
	v_pk_mul_f32 v[34:35], v[174:175], v[34:35]
	v_pk_mul_f32 v[40:41], v[172:173], v[40:41]
	v_pk_mul_f32 v[38:39], v[170:171], v[38:39]
	v_cvt_pk_bf16_f32 v34, v34, v35
	v_cvt_pk_bf16_f32 v35, v36, v37
	v_pk_mul_f32 v[42:43], v[42:43], v[60:61] op_sel_hi:[1,0]
	v_cvt_pk_bf16_f32 v36, v38, v39
	v_cvt_pk_bf16_f32 v37, v40, v41
	global_store_dwordx4 v[58:59], v[34:37], off
	v_pk_mul_f32 v[44:45], v[44:45], v[60:61] op_sel_hi:[1,0]
	v_pk_mul_f32 v[46:47], v[46:47], v[60:61] op_sel_hi:[1,0]
	v_pk_mul_f32 v[48:49], v[48:49], v[60:61] op_sel_hi:[1,0]
	v_pk_mul_f32 v[12:13], v[12:13], v[60:61] op_sel_hi:[1,0]
	v_pk_mul_f32 v[8:9], v[8:9], v[60:61] op_sel_hi:[1,0]
	v_pk_mul_f32 v[10:11], v[10:11], v[60:61] op_sel_hi:[1,0]
	v_pk_mul_f32 v[14:15], v[14:15], v[60:61] op_sel_hi:[1,0]
	v_pk_mul_f32 v[4:5], v[4:5], v[60:61] op_sel_hi:[1,0]
	v_pk_mul_f32 v[0:1], v[0:1], v[60:61] op_sel_hi:[1,0]
	v_pk_mul_f32 v[2:3], v[2:3], v[60:61] op_sel_hi:[1,0]
	v_pk_mul_f32 v[6:7], v[6:7], v[60:61] op_sel_hi:[1,0]
	v_pk_mul_f32 v[36:37], v[180:181], v[44:45]
	v_pk_mul_f32 v[34:35], v[178:179], v[42:43]
	v_pk_mul_f32 v[40:41], v[184:185], v[48:49]
	v_pk_mul_f32 v[38:39], v[182:183], v[46:47]
	v_cvt_pk_bf16_f32 v34, v34, v35
	v_cvt_pk_bf16_f32 v35, v36, v37
	s_nop 0
	v_cvt_pk_bf16_f32 v36, v38, v39
	v_cvt_pk_bf16_f32 v37, v40, v41
	global_store_dwordx4 v[58:59], v[34:37], off offset:1024
	s_nop 1
	v_pk_mul_f32 v[12:13], v[12:13], v[186:187]
	v_pk_mul_f32 v[34:35], v[10:11], v[192:193]
	v_pk_mul_f32 v[10:11], v[8:9], v[190:191]
	v_pk_mul_f32 v[14:15], v[14:15], v[188:189]
	v_cvt_pk_bf16_f32 v8, v12, v13
	s_nop 0
	v_cvt_pk_bf16_f32 v9, v14, v15
	v_cvt_pk_bf16_f32 v10, v10, v11
	v_cvt_pk_bf16_f32 v11, v34, v35
	global_store_dwordx4 v[58:59], v[8:11], off offset:2048
	s_nop 1
	v_pk_mul_f32 v[4:5], v[4:5], v[194:195]
	v_pk_mul_f32 v[8:9], v[2:3], v[200:201]
	v_pk_mul_f32 v[2:3], v[0:1], v[198:199]
	v_pk_mul_f32 v[6:7], v[6:7], v[196:197]
	v_cvt_pk_bf16_f32 v0, v4, v5
	s_nop 0
	v_cvt_pk_bf16_f32 v1, v6, v7
	v_cvt_pk_bf16_f32 v2, v2, v3
	v_cvt_pk_bf16_f32 v3, v8, v9
	global_store_dwordx4 v[58:59], v[0:3], off offset:3072
	s_cbranch_scc0 .LBB0_244

; #define PG8_STAGE(bufoff, gbase, voff) do { _Pragma("unroll") for (int _i = 0; _i < 2; ++_i) \
;         __builtin_amdgcn_global_load_lds((const unsigned*)((const char*)(gbase) + (voff)[_i]), (PG8_LAS unsigned*)(lds + (bufoff) + ldsw + _i * 8192), 16, 0, 0); } while (0)
; #define PG8_LDA(dst, b, h) do { _Pragma("unroll") for (int m = 0; m < 4; ++m) _Pragma("unroll") for (int k = 0; k < 2; ++k) dst[m][k] = *(const PG8_LAS bf16x8*)(lds + PG8_SA(b, h) + aoff + m * 2048 + k * 1024); } while (0)
; #define PG8_LDB(dst, b, h) do { _Pragma("unroll") for (int n = 0; n < 2; ++n) _Pragma("unroll") for (int k = 0; k < 2; ++k) dst[n][k] = *(const PG8_LAS bf16x8*)(lds + PG8_SB(b, h) + boff + n * 2048 + k * 1024); } while (0)
; #define PG8_MMA(ai, bj, At, Bt) do { __builtin_amdgcn_s_setprio(1); _Pragma("unroll") for (int m = 0; m < 4; ++m) _Pragma("unroll") for (int n = 0; n < 2; ++n) _Pragma("unroll") for (int k = 0; k < 2; ++k) \
;         acc[ai][bj][m][n] = __builtin_amdgcn_mfma_f32_16x16x32_bf16(Bt[n][k], At[m][k], acc[ai][bj][m][n], 0, 0, 0); __builtin_amdgcn_s_setprio(0); } while (0)
; #define PG8_WAIT_V(n) asm volatile("s_waitcnt vmcnt(" #n ")" ::: "memory")
; #define PG8_WAIT_L(n) asm volatile("s_waitcnt lgkmcnt(" #n ")" ::: "memory")
; template <class Epi, class Sched, bool ALIGN_EPI = false, bool SP2 = false>
; __device__ __forceinline__ void gemm_phase(PG8_LAS unsigned char* lds, const Gemm g, const Sched& S, const Epi& E) {
;     ...
;             const bool last = (t == nt - 2);
;             const char* a1 = cA + (size_t)(t + 1) * kstep;
;             const char* a2 = last ? nA : cA + (size_t)(t + 2) * kstep; const char* b2 = last ? nB : cB + (size_t)(t + 2) * kstep;
;             const char* a3 = a2 + kstep; const char* b3 = b2 + kstep;
;             if (last && has_next) S.a_ready(nxt);
;             if constexpr (SP2) {
;             PG8_LDB(B0, 0, 0); PG8_LDB(B1, 0, 1); PG8_SCHED; PG8_LDA(At, 0, 0); PG8_STAGE(PG8_SA(1, 1), a1 + hstepA, voffA);
;             PG8_WAIT_V(8); PG8_WAIT_L(0); PG8_BAR; PG8_MMA(0, 0, At, B0); PG8_MMA(0, 1, At, B1); PG8_BAR; PG8_SCHED;
;             PG8_LDA(At, 0, 1); PG8_STAGE(PG8_SB(0, 0), b2, voffB); PG8_STAGE(PG8_SB(0, 1), b2 + hstepB, voffB); PG8_STAGE(PG8_SA(0, 0), a2, voffA);
;             PG8_WAIT_V(8); PG8_WAIT_L(0); PG8_BAR; PG8_MMA(1, 0, At, B0); PG8_MMA(1, 1, At, B1); PG8_BAR; PG8_SCHED;
.LBB0_311:
	ds_read_b128 v[148:151], v176
	ds_read_b128 v[152:155], v176 offset:1024
	ds_read_b128 v[156:159], v176 offset:2048
	ds_read_b128 v[180:183], v176 offset:3072
	ds_read_b128 v[184:187], v177
	ds_read_b128 v[188:191], v177 offset:1024
	ds_read_b128 v[192:195], v177 offset:2048
	ds_read_b128 v[196:199], v177 offset:3072
	s_add_u32 s68, s6, 0xfff80080
	s_addc_u32 s69, s7, -1
	s_cmp_eq_u32 s78, 28
	s_cselect_b32 s71, s20, s69
	s_cselect_b32 s70, s33, s68
	s_cselect_b32 s69, s55, s77
	s_cselect_b32 s68, s61, s76
	s_add_i32 m0, s9, 0xc000
	ds_read_b128 v[200:203], v178
	ds_read_b128 v[204:207], v178 offset:1024
	ds_read_b128 v[208:211], v178 offset:2048
	ds_read_b128 v[212:215], v178 offset:3072
	ds_read_b128 v[216:219], v178 offset:4096
	ds_read_b128 v[220:223], v178 offset:5120
	ds_read_b128 v[224:227], v178 offset:6144
	ds_read_b128 v[228:231], v178 offset:7168
	global_load_lds_dwordx4 v140, s[6:7]
	s_add_i32 m0, s9, 0xe000
	s_nop 0
	global_load_lds_dwordx4 v142, s[6:7]
	s_waitcnt vmcnt(8)
	s_waitcnt lgkmcnt(0)
	s_barrier
	s_setprio 0
	s_waitcnt lgkmcnt(0)
	v_mfma_f32_16x16x32_bf16 v[124:127], v[148:151], v[200:203], v[124:127]
	v_mfma_f32_16x16x32_bf16 v[120:123], v[156:159], v[200:203], v[120:123]
	v_mfma_f32_16x16x32_bf16 v[108:111], v[148:151], v[208:211], v[108:111]
	v_mfma_f32_16x16x32_bf16 v[104:107], v[156:159], v[208:211], v[104:107]
	v_mfma_f32_16x16x32_bf16 v[92:95], v[148:151], v[216:219], v[92:95]
	v_mfma_f32_16x16x32_bf16 v[88:91], v[156:159], v[216:219], v[88:91]
	v_mfma_f32_16x16x32_bf16 v[76:79], v[148:151], v[224:227], v[76:79]
	v_mfma_f32_16x16x32_bf16 v[72:75], v[156:159], v[224:227], v[72:75]
	v_mfma_f32_16x16x32_bf16 v[124:127], v[152:155], v[204:207], v[124:127]
	v_mfma_f32_16x16x32_bf16 v[120:123], v[180:183], v[204:207], v[120:123]
	v_mfma_f32_16x16x32_bf16 v[108:111], v[152:155], v[212:215], v[108:111]
	v_mfma_f32_16x16x32_bf16 v[104:107], v[180:183], v[212:215], v[104:107]
	v_mfma_f32_16x16x32_bf16 v[92:95], v[152:155], v[220:223], v[92:95]
	v_mfma_f32_16x16x32_bf16 v[88:91], v[180:183], v[220:223], v[88:91]
	v_mfma_f32_16x16x32_bf16 v[76:79], v[152:155], v[228:231], v[76:79]
	v_mfma_f32_16x16x32_bf16 v[72:75], v[180:183], v[228:231], v[72:75]
	v_mfma_f32_16x16x32_bf16 v[116:119], v[184:187], v[200:203], v[116:119]
	v_mfma_f32_16x16x32_bf16 v[112:115], v[192:195], v[200:203], v[112:115]
	v_mfma_f32_16x16x32_bf16 v[100:103], v[184:187], v[208:211], v[100:103]
	v_mfma_f32_16x16x32_bf16 v[96:99], v[192:195], v[208:211], v[96:99]
	v_mfma_f32_16x16x32_bf16 v[84:87], v[184:187], v[216:219], v[84:87]
	v_mfma_f32_16x16x32_bf16 v[80:83], v[192:195], v[216:219], v[80:83]
	v_mfma_f32_16x16x32_bf16 v[68:71], v[184:187], v[224:227], v[68:71]
	v_mfma_f32_16x16x32_bf16 v[64:67], v[192:195], v[224:227], v[64:67]
	v_mfma_f32_16x16x32_bf16 v[116:119], v[188:191], v[204:207], v[116:119]
	v_mfma_f32_16x16x32_bf16 v[112:115], v[196:199], v[204:207], v[112:115]
	v_mfma_f32_16x16x32_bf16 v[100:103], v[188:191], v[212:215], v[100:103]
	v_mfma_f32_16x16x32_bf16 v[96:99], v[196:199], v[212:215], v[96:99]
	v_mfma_f32_16x16x32_bf16 v[84:87], v[188:191], v[220:223], v[84:87]
	v_mfma_f32_16x16x32_bf16 v[80:83], v[196:199], v[220:223], v[80:83]
	v_mfma_f32_16x16x32_bf16 v[68:71], v[188:191], v[228:231], v[68:71]
	v_mfma_f32_16x16x32_bf16 v[64:67], v[196:199], v[228:231], v[64:67]
	s_setprio 1
	s_barrier
	s_add_i32 s79, s72, s28
	v_lshl_add_u64 v[160:161], s[68:69], 0, v[130:131]
	s_mov_b32 m0, s79
	ds_read_b128 v[200:203], v178 offset:16384
	ds_read_b128 v[204:207], v178 offset:17408
	ds_read_b128 v[208:211], v178 offset:18432
	ds_read_b128 v[212:215], v178 offset:19456
	ds_read_b128 v[216:219], v178 offset:20480
	ds_read_b128 v[220:223], v178 offset:21504
	ds_read_b128 v[224:227], v178 offset:22528
	ds_read_b128 v[228:231], v178 offset:23552
	global_load_lds_dwordx4 v130, s[68:69]
	s_add_i32 m0, s79, 0x2000
	s_add_u32 s80, s68, 0x80000
	v_lshl_add_u64 v[232:233], s[68:69], 0, v[134:135]
	s_addc_u32 s81, s69, 0
	s_add_i32 s79, s73, s28
	global_load_lds_dwordx4 v134, s[68:69]
	s_mov_b32 m0, s79
	v_lshl_add_u64 v[236:237], s[70:71], 0, v[132:133]
	global_load_lds_dwordx4 v130, s[80:81]
	s_add_i32 m0, s79, 0x2000
	s_nop 0
	global_load_lds_dwordx4 v134, s[80:81]
	v_lshl_add_u64 v[234:235], s[70:71], 0, v[128:129]
	s_mov_b32 m0, s9
	s_nop 0
	global_load_lds_dwordx4 v128, s[70:71]
	s_mov_b32 m0, s19
	s_nop 0
	global_load_lds_dwordx4 v132, s[70:71]
	s_waitcnt vmcnt(8)
	s_waitcnt lgkmcnt(0)
	s_barrier
	s_setprio 0
	s_waitcnt lgkmcnt(0)
	v_mfma_f32_16x16x32_bf16 v[60:63], v[148:151], v[200:203], v[60:63]
	v_mfma_f32_16x16x32_bf16 v[56:59], v[156:159], v[200:203], v[56:59]
	v_mfma_f32_16x16x32_bf16 v[44:47], v[148:151], v[208:211], v[44:47]
	v_mfma_f32_16x16x32_bf16 v[40:43], v[156:159], v[208:211], v[40:43]
	v_mfma_f32_16x16x32_bf16 v[28:31], v[148:151], v[216:219], v[28:31]
	v_mfma_f32_16x16x32_bf16 v[24:27], v[156:159], v[216:219], v[24:27]
	v_mfma_f32_16x16x32_bf16 v[12:15], v[148:151], v[224:227], v[12:15]
	v_mfma_f32_16x16x32_bf16 v[8:11], v[156:159], v[224:227], v[8:11]
	v_mfma_f32_16x16x32_bf16 v[60:63], v[152:155], v[204:207], v[60:63]
	v_mfma_f32_16x16x32_bf16 v[56:59], v[180:183], v[204:207], v[56:59]
	v_mfma_f32_16x16x32_bf16 v[44:47], v[152:155], v[212:215], v[44:47]
	v_mfma_f32_16x16x32_bf16 v[40:43], v[180:183], v[212:215], v[40:43]
	v_mfma_f32_16x16x32_bf16 v[28:31], v[152:155], v[220:223], v[28:31]
	v_mfma_f32_16x16x32_bf16 v[24:27], v[180:183], v[220:223], v[24:27]
	v_mfma_f32_16x16x32_bf16 v[12:15], v[152:155], v[228:231], v[12:15]
	v_mfma_f32_16x16x32_bf16 v[8:11], v[180:183], v[228:231], v[8:11]
	v_mfma_f32_16x16x32_bf16 v[52:55], v[184:187], v[200:203], v[52:55]
	v_mfma_f32_16x16x32_bf16 v[48:51], v[192:195], v[200:203], v[48:51]
	v_mfma_f32_16x16x32_bf16 v[36:39], v[184:187], v[208:211], v[36:39]
	v_mfma_f32_16x16x32_bf16 v[32:35], v[192:195], v[208:211], v[32:35]
	v_mfma_f32_16x16x32_bf16 v[20:23], v[184:187], v[216:219], v[20:23]
	v_mfma_f32_16x16x32_bf16 v[16:19], v[192:195], v[216:219], v[16:19]
	v_mfma_f32_16x16x32_bf16 v[4:7], v[184:187], v[224:227], v[4:7]
	v_mfma_f32_16x16x32_bf16 v[0:3], v[192:195], v[224:227], v[0:3]
	v_mfma_f32_16x16x32_bf16 v[52:55], v[188:191], v[204:207], v[52:55]
	v_mfma_f32_16x16x32_bf16 v[48:51], v[196:199], v[204:207], v[48:51]
	v_mfma_f32_16x16x32_bf16 v[36:39], v[188:191], v[212:215], v[36:39]
	v_mfma_f32_16x16x32_bf16 v[32:35], v[196:199], v[212:215], v[32:35]
	v_mfma_f32_16x16x32_bf16 v[20:23], v[188:191], v[220:223], v[20:23]
	v_mfma_f32_16x16x32_bf16 v[16:19], v[196:199], v[220:223], v[16:19]
	v_mfma_f32_16x16x32_bf16 v[4:7], v[188:191], v[228:231], v[4:7]
	v_mfma_f32_16x16x32_bf16 v[0:3], v[196:199], v[228:231], v[0:3]
	s_setprio 1
	s_barrier
; #define PG8_STAGE(bufoff, gbase, voff) do { _Pragma("unroll") for (int _i = 0; _i < 2; ++_i) \
;         __builtin_amdgcn_global_load_lds((const unsigned*)((const char*)(gbase) + (voff)[_i]), (PG8_LAS unsigned*)(lds + (bufoff) + ldsw + _i * 8192), 16, 0, 0); } while (0)
; #define PG8_LDA(dst, b, h) do { _Pragma("unroll") for (int m = 0; m < 4; ++m) _Pragma("unroll") for (int k = 0; k < 2; ++k) dst[m][k] = *(const PG8_LAS bf16x8*)(lds + PG8_SA(b, h) + aoff + m * 2048 + k * 1024); } while (0)
; #define PG8_LDB(dst, b, h) do { _Pragma("unroll") for (int n = 0; n < 2; ++n) _Pragma("unroll") for (int k = 0; k < 2; ++k) dst[n][k] = *(const PG8_LAS bf16x8*)(lds + PG8_SB(b, h) + boff + n * 2048 + k * 1024); } while (0)
; #define PG8_MMA(ai, bj, At, Bt) do { __builtin_amdgcn_s_setprio(1); _Pragma("unroll") for (int m = 0; m < 4; ++m) _Pragma("unroll") for (int n = 0; n < 2; ++n) _Pragma("unroll") for (int k = 0; k < 2; ++k) \
;         acc[ai][bj][m][n] = __builtin_amdgcn_mfma_f32_16x16x32_bf16(Bt[n][k], At[m][k], acc[ai][bj][m][n], 0, 0, 0); __builtin_amdgcn_s_setprio(0); } while (0)
; #define PG8_WAIT_V(n) asm volatile("s_waitcnt vmcnt(" #n ")" ::: "memory")
; #define PG8_WAIT_L(n) asm volatile("s_waitcnt lgkmcnt(" #n ")" ::: "memory")
; #define PG8_BAR __builtin_amdgcn_s_barrier()
; #define PG8_SCHED __builtin_amdgcn_sched_barrier(0)
; template <class Epi, class Sched, bool ALIGN_EPI = false, bool SP2 = false>
; __device__ __forceinline__ void gemm_phase(PG8_LAS unsigned char* lds, const Gemm g, const Sched& S, const Epi& E) {
;     ...
;         for (int t = 0; t < nt; t += 2) {
;             const bool last = (t == nt - 2);
;             const char* a1 = cA + (size_t)(t + 1) * kstep;
;             const char* a2 = last ? nA : cA + (size_t)(t + 2) * kstep; const char* b2 = last ? nB : cB + (size_t)(t + 2) * kstep;
;     ...
;             PG8_LDB(B0, 1, 0); PG8_LDB(B1, 1, 1); PG8_SCHED; PG8_LDA(At, 1, 0); PG8_STAGE(PG8_SA(0, 1), a2 + hstepA, voffA);
;             PG8_WAIT_V(8); PG8_WAIT_L(0); PG8_BAR; PG8_MMA(0, 0, At, B0); PG8_MMA(0, 1, At, B1); PG8_BAR; PG8_SCHED;
;             PG8_LDA(At, 1, 1); PG8_STAGE(PG8_SB(1, 0), b3, voffB); PG8_STAGE(PG8_SB(1, 1), b3 + hstepB, voffB); PG8_STAGE(PG8_SA(1, 0), a3, voffA);
;             PG8_WAIT_V(8); PG8_WAIT_L(0); PG8_BAR; PG8_MMA(1, 0, At, B0); PG8_MMA(1, 1, At, B1); PG8_BAR; PG8_SCHED;
	s_add_i32 s79, 0, 0x18000
	v_add_u32_e32 v138, s79, v174
	s_add_i32 s80, 0, 0x1c000
	ds_read_b128 v[148:151], v138
	ds_read_b128 v[152:155], v138 offset:1024
	ds_read_b128 v[156:159], v138 offset:2048
	ds_read_b128 v[180:183], v138 offset:3072
	v_add_u32_e32 v138, s80, v174
	ds_read_b128 v[184:187], v138
	ds_read_b128 v[188:191], v138 offset:1024
	ds_read_b128 v[192:195], v138 offset:2048
	ds_read_b128 v[196:199], v138 offset:3072
	s_add_u32 s70, s70, 0x80000
	s_addc_u32 s71, s71, 0
	s_mov_b32 m0, s29
	ds_read_b128 v[200:203], v178 offset:32768
	ds_read_b128 v[204:207], v178 offset:33792
	ds_read_b128 v[208:211], v178 offset:34816
	ds_read_b128 v[212:215], v178 offset:35840
	ds_read_b128 v[216:219], v178 offset:36864
	ds_read_b128 v[220:223], v178 offset:37888
	ds_read_b128 v[224:227], v178 offset:38912
	ds_read_b128 v[228:231], v178 offset:39936
	global_load_lds_dwordx4 v128, s[70:71]
	s_mov_b32 m0, s30
	s_nop 0
	global_load_lds_dwordx4 v132, s[70:71]
	s_waitcnt vmcnt(8)
	s_waitcnt lgkmcnt(0)
	s_barrier
	s_setprio 0
	s_waitcnt lgkmcnt(0)
	v_mfma_f32_16x16x32_bf16 v[124:127], v[148:151], v[200:203], v[124:127]
	v_mfma_f32_16x16x32_bf16 v[120:123], v[156:159], v[200:203], v[120:123]
	v_mfma_f32_16x16x32_bf16 v[108:111], v[148:151], v[208:211], v[108:111]
	v_mfma_f32_16x16x32_bf16 v[104:107], v[156:159], v[208:211], v[104:107]
	v_mfma_f32_16x16x32_bf16 v[92:95], v[148:151], v[216:219], v[92:95]
	v_mfma_f32_16x16x32_bf16 v[88:91], v[156:159], v[216:219], v[88:91]
	v_mfma_f32_16x16x32_bf16 v[76:79], v[148:151], v[224:227], v[76:79]
	v_mfma_f32_16x16x32_bf16 v[72:75], v[156:159], v[224:227], v[72:75]
	v_mfma_f32_16x16x32_bf16 v[124:127], v[152:155], v[204:207], v[124:127]
	v_mfma_f32_16x16x32_bf16 v[120:123], v[180:183], v[204:207], v[120:123]
	v_mfma_f32_16x16x32_bf16 v[108:111], v[152:155], v[212:215], v[108:111]
	v_mfma_f32_16x16x32_bf16 v[104:107], v[180:183], v[212:215], v[104:107]
	v_mfma_f32_16x16x32_bf16 v[92:95], v[152:155], v[220:223], v[92:95]
	v_mfma_f32_16x16x32_bf16 v[88:91], v[180:183], v[220:223], v[88:91]
	v_mfma_f32_16x16x32_bf16 v[76:79], v[152:155], v[228:231], v[76:79]
	v_mfma_f32_16x16x32_bf16 v[72:75], v[180:183], v[228:231], v[72:75]
	v_mfma_f32_16x16x32_bf16 v[116:119], v[184:187], v[200:203], v[116:119]
	v_mfma_f32_16x16x32_bf16 v[112:115], v[192:195], v[200:203], v[112:115]
	v_mfma_f32_16x16x32_bf16 v[100:103], v[184:187], v[208:211], v[100:103]
	v_mfma_f32_16x16x32_bf16 v[96:99], v[192:195], v[208:211], v[96:99]
	v_mfma_f32_16x16x32_bf16 v[84:87], v[184:187], v[216:219], v[84:87]
	v_mfma_f32_16x16x32_bf16 v[80:83], v[192:195], v[216:219], v[80:83]
	v_mfma_f32_16x16x32_bf16 v[68:71], v[184:187], v[224:227], v[68:71]
	v_mfma_f32_16x16x32_bf16 v[64:67], v[192:195], v[224:227], v[64:67]
	v_mfma_f32_16x16x32_bf16 v[116:119], v[188:191], v[204:207], v[116:119]
	v_mfma_f32_16x16x32_bf16 v[112:115], v[196:199], v[204:207], v[112:115]
	v_mfma_f32_16x16x32_bf16 v[100:103], v[188:191], v[212:215], v[100:103]
	v_mfma_f32_16x16x32_bf16 v[96:99], v[196:199], v[212:215], v[96:99]
	v_mfma_f32_16x16x32_bf16 v[84:87], v[188:191], v[220:223], v[84:87]
	v_mfma_f32_16x16x32_bf16 v[80:83], v[196:199], v[220:223], v[80:83]
	v_mfma_f32_16x16x32_bf16 v[68:71], v[188:191], v[228:231], v[68:71]
	v_mfma_f32_16x16x32_bf16 v[64:67], v[196:199], v[228:231], v[64:67]
	s_setprio 1
	s_barrier
	s_add_i32 s70, s79, s28
	v_lshl_add_u64 v[160:161], v[160:161], 0, s[46:47]
	s_mov_b32 m0, s70
	ds_read_b128 v[200:203], v178 offset:49152
	ds_read_b128 v[204:207], v178 offset:50176
	ds_read_b128 v[208:211], v178 offset:51200
	ds_read_b128 v[212:215], v178 offset:52224
	ds_read_b128 v[216:219], v178 offset:53248
	ds_read_b128 v[220:223], v178 offset:54272
	ds_read_b128 v[224:227], v178 offset:55296
	ds_read_b128 v[228:231], v178 offset:56320
	global_load_lds_dwordx4 v[160:161], off
	s_add_i32 m0, s70, 0x2000
	s_add_u32 s68, s68, 0x80080
	v_lshl_add_u64 v[160:161], v[232:233], 0, s[46:47]
	s_addc_u32 s69, s69, 0
	s_add_i32 s70, s80, s28
	global_load_lds_dwordx4 v[160:161], off
	s_mov_b32 m0, s70
	s_nop 0
	global_load_lds_dwordx4 v130, s[68:69]
	s_add_i32 m0, s70, 0x2000
	s_nop 0
	global_load_lds_dwordx4 v134, s[68:69]
	v_lshl_add_u64 v[160:161], v[234:235], 0, s[46:47]
	s_mov_b32 m0, s34
	s_nop 0
	global_load_lds_dwordx4 v[160:161], off
	v_lshl_add_u64 v[160:161], v[236:237], 0, s[46:47]
	s_mov_b32 m0, s35
	s_nop 0
	global_load_lds_dwordx4 v[160:161], off
	s_waitcnt vmcnt(8)
	s_waitcnt lgkmcnt(0)
	s_barrier
	s_setprio 0
	s_waitcnt lgkmcnt(0)
	v_mfma_f32_16x16x32_bf16 v[60:63], v[148:151], v[200:203], v[60:63]
	v_mfma_f32_16x16x32_bf16 v[56:59], v[156:159], v[200:203], v[56:59]
	v_mfma_f32_16x16x32_bf16 v[44:47], v[148:151], v[208:211], v[44:47]
	v_mfma_f32_16x16x32_bf16 v[40:43], v[156:159], v[208:211], v[40:43]
	v_mfma_f32_16x16x32_bf16 v[28:31], v[148:151], v[216:219], v[28:31]
	v_mfma_f32_16x16x32_bf16 v[24:27], v[156:159], v[216:219], v[24:27]
	v_mfma_f32_16x16x32_bf16 v[12:15], v[148:151], v[224:227], v[12:15]
	v_mfma_f32_16x16x32_bf16 v[8:11], v[156:159], v[224:227], v[8:11]
	v_mfma_f32_16x16x32_bf16 v[60:63], v[152:155], v[204:207], v[60:63]
	v_mfma_f32_16x16x32_bf16 v[56:59], v[180:183], v[204:207], v[56:59]
	v_mfma_f32_16x16x32_bf16 v[44:47], v[152:155], v[212:215], v[44:47]
	v_mfma_f32_16x16x32_bf16 v[40:43], v[180:183], v[212:215], v[40:43]
	v_mfma_f32_16x16x32_bf16 v[28:31], v[152:155], v[220:223], v[28:31]
	v_mfma_f32_16x16x32_bf16 v[24:27], v[180:183], v[220:223], v[24:27]
	v_mfma_f32_16x16x32_bf16 v[12:15], v[152:155], v[228:231], v[12:15]
	v_mfma_f32_16x16x32_bf16 v[8:11], v[180:183], v[228:231], v[8:11]
	v_mfma_f32_16x16x32_bf16 v[52:55], v[184:187], v[200:203], v[52:55]
	v_mfma_f32_16x16x32_bf16 v[48:51], v[192:195], v[200:203], v[48:51]
	v_mfma_f32_16x16x32_bf16 v[36:39], v[184:187], v[208:211], v[36:39]
	v_mfma_f32_16x16x32_bf16 v[32:35], v[192:195], v[208:211], v[32:35]
	v_mfma_f32_16x16x32_bf16 v[20:23], v[184:187], v[216:219], v[20:23]
	v_mfma_f32_16x16x32_bf16 v[16:19], v[192:195], v[216:219], v[16:19]
	v_mfma_f32_16x16x32_bf16 v[4:7], v[184:187], v[224:227], v[4:7]
	v_mfma_f32_16x16x32_bf16 v[0:3], v[192:195], v[224:227], v[0:3]
	v_mfma_f32_16x16x32_bf16 v[52:55], v[188:191], v[204:207], v[52:55]
	v_mfma_f32_16x16x32_bf16 v[48:51], v[196:199], v[204:207], v[48:51]
	v_mfma_f32_16x16x32_bf16 v[36:39], v[188:191], v[212:215], v[36:39]
	v_mfma_f32_16x16x32_bf16 v[32:35], v[196:199], v[212:215], v[32:35]
	v_mfma_f32_16x16x32_bf16 v[20:23], v[188:191], v[220:223], v[20:23]
	v_mfma_f32_16x16x32_bf16 v[16:19], v[196:199], v[220:223], v[16:19]
	v_mfma_f32_16x16x32_bf16 v[4:7], v[188:191], v[228:231], v[4:7]
	v_mfma_f32_16x16x32_bf16 v[0:3], v[196:199], v[228:231], v[0:3]
	s_setprio 1
	s_barrier
	s_add_i32 s78, s78, 2
	s_add_u32 s6, s6, 0x100
	s_addc_u32 s7, s7, 0
	s_add_u32 s76, s76, 0x100
	s_addc_u32 s77, s77, 0
	s_cmp_gt_u32 s78, 29
	s_cbranch_scc0 .LBB0_311
	s_and_b64 vcc, exec, s[48:49]
	s_cbranch_vccz .LBB0_314
	s_barrier

; #define PG8_STAGE(bufoff, gbase, voff) do { _Pragma("unroll") for (int _i = 0; _i < 2; ++_i) \
;         __builtin_amdgcn_global_load_lds((const unsigned*)((const char*)(gbase) + (voff)[_i]), (PG8_LAS unsigned*)(lds + (bufoff) + ldsw + _i * 8192), 16, 0, 0); } while (0)
; #define PG8_LDA(dst, b, h) do { _Pragma("unroll") for (int m = 0; m < 4; ++m) _Pragma("unroll") for (int k = 0; k < 2; ++k) dst[m][k] = *(const PG8_LAS bf16x8*)(lds + PG8_SA(b, h) + aoff + m * 2048 + k * 1024); } while (0)
; #define PG8_LDB(dst, b, h) do { _Pragma("unroll") for (int n = 0; n < 2; ++n) _Pragma("unroll") for (int k = 0; k < 2; ++k) dst[n][k] = *(const PG8_LAS bf16x8*)(lds + PG8_SB(b, h) + boff + n * 2048 + k * 1024); } while (0)
; #define PG8_MMA(ai, bj, At, Bt) do { __builtin_amdgcn_s_setprio(1); _Pragma("unroll") for (int m = 0; m < 4; ++m) _Pragma("unroll") for (int n = 0; n < 2; ++n) _Pragma("unroll") for (int k = 0; k < 2; ++k) \
;         acc[ai][bj][m][n] = __builtin_amdgcn_mfma_f32_16x16x32_bf16(Bt[n][k], At[m][k], acc[ai][bj][m][n], 0, 0, 0); __builtin_amdgcn_s_setprio(0); } while (0)
; #define PG8_WAIT_V(n) asm volatile("s_waitcnt vmcnt(" #n ")" ::: "memory")
; #define PG8_WAIT_L(n) asm volatile("s_waitcnt lgkmcnt(" #n ")" ::: "memory")
; template <class Epi, class Sched, bool ALIGN_EPI = false, bool SP2 = false>
; __device__ __forceinline__ void gemm_phase(PG8_LAS unsigned char* lds, const Gemm g, const Sched& S, const Epi& E) {
;     ...
;             const bool last = (t == nt - 2);
;             const char* a1 = cA + (size_t)(t + 1) * kstep;
;             const char* a2 = last ? nA : cA + (size_t)(t + 2) * kstep; const char* b2 = last ? nB : cB + (size_t)(t + 2) * kstep;
;             const char* a3 = a2 + kstep; const char* b3 = b2 + kstep;
;             if (last && has_next) S.a_ready(nxt);
;             if constexpr (SP2) {
;             PG8_LDB(B0, 0, 0); PG8_LDB(B1, 0, 1); PG8_SCHED; PG8_LDA(At, 0, 0); PG8_STAGE(PG8_SA(1, 1), a1 + hstepA, voffA);
;             PG8_WAIT_V(8); PG8_WAIT_L(0); PG8_BAR; PG8_MMA(0, 0, At, B0); PG8_MMA(0, 1, At, B1); PG8_BAR; PG8_SCHED;
;             PG8_LDA(At, 0, 1); PG8_STAGE(PG8_SB(0, 0), b2, voffB); PG8_STAGE(PG8_SB(0, 1), b2 + hstepB, voffB); PG8_STAGE(PG8_SA(0, 0), a2, voffA);
;             PG8_WAIT_V(8); PG8_WAIT_L(0); PG8_BAR; PG8_MMA(1, 0, At, B0); PG8_MMA(1, 1, At, B1); PG8_BAR; PG8_SCHED;
.LBB0_497:
	ds_read_b128 v[146:149], v155
	ds_read_b128 v[158:161], v155 offset:1024
	ds_read_b128 v[168:171], v155 offset:2048
	ds_read_b128 v[172:175], v155 offset:3072
	ds_read_b128 v[176:179], v156
	ds_read_b128 v[180:183], v156 offset:1024
	ds_read_b128 v[184:187], v156 offset:2048
	ds_read_b128 v[188:191], v156 offset:3072
	s_add_u32 s41, s54, 0xfff80080
	s_addc_u32 s43, s55, -1
	s_cmp_eq_u32 s34, 28
	s_cselect_b32 s63, s7, s43
	s_cselect_b32 s62, s28, s41
	s_cselect_b32 s61, s29, s33
	s_cselect_b32 s60, s30, s31
	s_add_i32 m0, s69, 0xc000
	ds_read_b128 v[192:195], v157
	ds_read_b128 v[196:199], v157 offset:1024
	ds_read_b128 v[200:203], v157 offset:2048
	ds_read_b128 v[204:207], v157 offset:3072
	ds_read_b128 v[208:211], v157 offset:4096
	ds_read_b128 v[212:215], v157 offset:5120
	ds_read_b128 v[216:219], v157 offset:6144
	ds_read_b128 v[220:223], v157 offset:7168
	global_load_lds_dwordx4 v138, s[54:55]
	s_add_i32 m0, s69, 0xe000
	s_nop 0
	global_load_lds_dwordx4 v140, s[54:55]
	s_waitcnt vmcnt(8)
	s_waitcnt lgkmcnt(0)
	s_barrier
	s_setprio 0
	s_waitcnt lgkmcnt(0)
	v_mfma_f32_16x16x32_bf16 v[124:127], v[146:149], v[192:195], v[124:127]
	v_mfma_f32_16x16x32_bf16 v[120:123], v[168:171], v[192:195], v[120:123]
	v_mfma_f32_16x16x32_bf16 v[108:111], v[146:149], v[200:203], v[108:111]
	v_mfma_f32_16x16x32_bf16 v[104:107], v[168:171], v[200:203], v[104:107]
	v_mfma_f32_16x16x32_bf16 v[92:95], v[146:149], v[208:211], v[92:95]
	v_mfma_f32_16x16x32_bf16 v[88:91], v[168:171], v[208:211], v[88:91]
	v_mfma_f32_16x16x32_bf16 v[76:79], v[146:149], v[216:219], v[76:79]
	v_mfma_f32_16x16x32_bf16 v[72:75], v[168:171], v[216:219], v[72:75]
	v_mfma_f32_16x16x32_bf16 v[124:127], v[158:161], v[196:199], v[124:127]
	v_mfma_f32_16x16x32_bf16 v[120:123], v[172:175], v[196:199], v[120:123]
	v_mfma_f32_16x16x32_bf16 v[108:111], v[158:161], v[204:207], v[108:111]
	v_mfma_f32_16x16x32_bf16 v[104:107], v[172:175], v[204:207], v[104:107]
	v_mfma_f32_16x16x32_bf16 v[92:95], v[158:161], v[212:215], v[92:95]
	v_mfma_f32_16x16x32_bf16 v[88:91], v[172:175], v[212:215], v[88:91]
	v_mfma_f32_16x16x32_bf16 v[76:79], v[158:161], v[220:223], v[76:79]
	v_mfma_f32_16x16x32_bf16 v[72:75], v[172:175], v[220:223], v[72:75]
	v_mfma_f32_16x16x32_bf16 v[116:119], v[176:179], v[192:195], v[116:119]
	v_mfma_f32_16x16x32_bf16 v[112:115], v[184:187], v[192:195], v[112:115]
	v_mfma_f32_16x16x32_bf16 v[100:103], v[176:179], v[200:203], v[100:103]
	v_mfma_f32_16x16x32_bf16 v[96:99], v[184:187], v[200:203], v[96:99]
	v_mfma_f32_16x16x32_bf16 v[84:87], v[176:179], v[208:211], v[84:87]
	v_mfma_f32_16x16x32_bf16 v[80:83], v[184:187], v[208:211], v[80:83]
	v_mfma_f32_16x16x32_bf16 v[68:71], v[176:179], v[216:219], v[68:71]
	v_mfma_f32_16x16x32_bf16 v[64:67], v[184:187], v[216:219], v[64:67]
	v_mfma_f32_16x16x32_bf16 v[116:119], v[180:183], v[196:199], v[116:119]
	v_mfma_f32_16x16x32_bf16 v[112:115], v[188:191], v[196:199], v[112:115]
	v_mfma_f32_16x16x32_bf16 v[100:103], v[180:183], v[204:207], v[100:103]
	v_mfma_f32_16x16x32_bf16 v[96:99], v[188:191], v[204:207], v[96:99]
	v_mfma_f32_16x16x32_bf16 v[84:87], v[180:183], v[212:215], v[84:87]
	v_mfma_f32_16x16x32_bf16 v[80:83], v[188:191], v[212:215], v[80:83]
	v_mfma_f32_16x16x32_bf16 v[68:71], v[180:183], v[220:223], v[68:71]
	v_mfma_f32_16x16x32_bf16 v[64:67], v[188:191], v[220:223], v[64:67]
	s_setprio 1
	s_barrier
	s_add_i32 s41, s81, s68
	v_lshl_add_u64 v[150:151], s[60:61], 0, v[130:131]
	s_mov_b32 m0, s41
	ds_read_b128 v[192:195], v157 offset:16384
	ds_read_b128 v[196:199], v157 offset:17408
	ds_read_b128 v[200:203], v157 offset:18432
	ds_read_b128 v[204:207], v157 offset:19456
	ds_read_b128 v[208:211], v157 offset:20480
	ds_read_b128 v[212:215], v157 offset:21504
	ds_read_b128 v[216:219], v157 offset:22528
	ds_read_b128 v[220:223], v157 offset:23552
	global_load_lds_dwordx4 v130, s[60:61]
	s_add_i32 m0, s41, 0x2000
	s_add_u32 s84, s60, 0x80000
	v_lshl_add_u64 v[224:225], s[60:61], 0, v[134:135]
	s_addc_u32 s85, s61, 0
	s_add_i32 s41, s82, s68
	global_load_lds_dwordx4 v134, s[60:61]
	s_mov_b32 m0, s41
	v_lshl_add_u64 v[228:229], s[62:63], 0, v[132:133]
	global_load_lds_dwordx4 v130, s[84:85]
	s_add_i32 m0, s41, 0x2000
	s_nop 0
	global_load_lds_dwordx4 v134, s[84:85]
	v_lshl_add_u64 v[226:227], s[62:63], 0, v[128:129]
	s_mov_b32 m0, s69
	s_nop 0
	global_load_lds_dwordx4 v128, s[62:63]
	s_mov_b32 m0, s70
	s_nop 0
	global_load_lds_dwordx4 v132, s[62:63]
	s_waitcnt vmcnt(8)
	s_waitcnt lgkmcnt(0)
	s_barrier
	s_setprio 0
	s_waitcnt lgkmcnt(0)
	v_mfma_f32_16x16x32_bf16 v[60:63], v[146:149], v[192:195], v[60:63]
	v_mfma_f32_16x16x32_bf16 v[56:59], v[168:171], v[192:195], v[56:59]
	v_mfma_f32_16x16x32_bf16 v[44:47], v[146:149], v[200:203], v[44:47]
	v_mfma_f32_16x16x32_bf16 v[40:43], v[168:171], v[200:203], v[40:43]
	v_mfma_f32_16x16x32_bf16 v[28:31], v[146:149], v[208:211], v[28:31]
	v_mfma_f32_16x16x32_bf16 v[24:27], v[168:171], v[208:211], v[24:27]
	v_mfma_f32_16x16x32_bf16 v[12:15], v[146:149], v[216:219], v[12:15]
	v_mfma_f32_16x16x32_bf16 v[8:11], v[168:171], v[216:219], v[8:11]
	v_mfma_f32_16x16x32_bf16 v[60:63], v[158:161], v[196:199], v[60:63]
	v_mfma_f32_16x16x32_bf16 v[56:59], v[172:175], v[196:199], v[56:59]
	v_mfma_f32_16x16x32_bf16 v[44:47], v[158:161], v[204:207], v[44:47]
	v_mfma_f32_16x16x32_bf16 v[40:43], v[172:175], v[204:207], v[40:43]
	v_mfma_f32_16x16x32_bf16 v[28:31], v[158:161], v[212:215], v[28:31]
	v_mfma_f32_16x16x32_bf16 v[24:27], v[172:175], v[212:215], v[24:27]
	v_mfma_f32_16x16x32_bf16 v[12:15], v[158:161], v[220:223], v[12:15]
	v_mfma_f32_16x16x32_bf16 v[8:11], v[172:175], v[220:223], v[8:11]
	v_mfma_f32_16x16x32_bf16 v[52:55], v[176:179], v[192:195], v[52:55]
	v_mfma_f32_16x16x32_bf16 v[48:51], v[184:187], v[192:195], v[48:51]
	v_mfma_f32_16x16x32_bf16 v[36:39], v[176:179], v[200:203], v[36:39]
	v_mfma_f32_16x16x32_bf16 v[32:35], v[184:187], v[200:203], v[32:35]
	v_mfma_f32_16x16x32_bf16 v[20:23], v[176:179], v[208:211], v[20:23]
	v_mfma_f32_16x16x32_bf16 v[16:19], v[184:187], v[208:211], v[16:19]
	v_mfma_f32_16x16x32_bf16 v[4:7], v[176:179], v[216:219], v[4:7]
	v_mfma_f32_16x16x32_bf16 v[0:3], v[184:187], v[216:219], v[0:3]
	v_mfma_f32_16x16x32_bf16 v[52:55], v[180:183], v[196:199], v[52:55]
	v_mfma_f32_16x16x32_bf16 v[48:51], v[188:191], v[196:199], v[48:51]
	v_mfma_f32_16x16x32_bf16 v[36:39], v[180:183], v[204:207], v[36:39]
	v_mfma_f32_16x16x32_bf16 v[32:35], v[188:191], v[204:207], v[32:35]
	v_mfma_f32_16x16x32_bf16 v[20:23], v[180:183], v[212:215], v[20:23]
	v_mfma_f32_16x16x32_bf16 v[16:19], v[188:191], v[212:215], v[16:19]
	v_mfma_f32_16x16x32_bf16 v[4:7], v[180:183], v[220:223], v[4:7]
	v_mfma_f32_16x16x32_bf16 v[0:3], v[188:191], v[220:223], v[0:3]
	s_setprio 1
	s_barrier
; #define PG8_STAGE(bufoff, gbase, voff) do { _Pragma("unroll") for (int _i = 0; _i < 2; ++_i) \
;         __builtin_amdgcn_global_load_lds((const unsigned*)((const char*)(gbase) + (voff)[_i]), (PG8_LAS unsigned*)(lds + (bufoff) + ldsw + _i * 8192), 16, 0, 0); } while (0)
; #define PG8_LDA(dst, b, h) do { _Pragma("unroll") for (int m = 0; m < 4; ++m) _Pragma("unroll") for (int k = 0; k < 2; ++k) dst[m][k] = *(const PG8_LAS bf16x8*)(lds + PG8_SA(b, h) + aoff + m * 2048 + k * 1024); } while (0)
; #define PG8_LDB(dst, b, h) do { _Pragma("unroll") for (int n = 0; n < 2; ++n) _Pragma("unroll") for (int k = 0; k < 2; ++k) dst[n][k] = *(const PG8_LAS bf16x8*)(lds + PG8_SB(b, h) + boff + n * 2048 + k * 1024); } while (0)
; #define PG8_MMA(ai, bj, At, Bt) do { __builtin_amdgcn_s_setprio(1); _Pragma("unroll") for (int m = 0; m < 4; ++m) _Pragma("unroll") for (int n = 0; n < 2; ++n) _Pragma("unroll") for (int k = 0; k < 2; ++k) \
;         acc[ai][bj][m][n] = __builtin_amdgcn_mfma_f32_16x16x32_bf16(Bt[n][k], At[m][k], acc[ai][bj][m][n], 0, 0, 0); __builtin_amdgcn_s_setprio(0); } while (0)
; #define PG8_WAIT_V(n) asm volatile("s_waitcnt vmcnt(" #n ")" ::: "memory")
; #define PG8_WAIT_L(n) asm volatile("s_waitcnt lgkmcnt(" #n ")" ::: "memory")
; #define PG8_BAR __builtin_amdgcn_s_barrier()
; #define PG8_SCHED __builtin_amdgcn_sched_barrier(0)
; template <class Epi, class Sched, bool ALIGN_EPI = false, bool SP2 = false>
; __device__ __forceinline__ void gemm_phase(PG8_LAS unsigned char* lds, const Gemm g, const Sched& S, const Epi& E) {
;     ...
;         for (int t = 0; t < nt; t += 2) {
;             const bool last = (t == nt - 2);
;             const char* a1 = cA + (size_t)(t + 1) * kstep;
;             const char* a2 = last ? nA : cA + (size_t)(t + 2) * kstep; const char* b2 = last ? nB : cB + (size_t)(t + 2) * kstep;
;     ...
;             PG8_LDB(B0, 1, 0); PG8_LDB(B1, 1, 1); PG8_SCHED; PG8_LDA(At, 1, 0); PG8_STAGE(PG8_SA(0, 1), a2 + hstepA, voffA);
;             PG8_WAIT_V(8); PG8_WAIT_L(0); PG8_BAR; PG8_MMA(0, 0, At, B0); PG8_MMA(0, 1, At, B1); PG8_BAR; PG8_SCHED;
;             PG8_LDA(At, 1, 1); PG8_STAGE(PG8_SB(1, 0), b3, voffB); PG8_STAGE(PG8_SB(1, 1), b3 + hstepB, voffB); PG8_STAGE(PG8_SA(1, 0), a3, voffA);
;             PG8_WAIT_V(8); PG8_WAIT_L(0); PG8_BAR; PG8_MMA(1, 0, At, B0); PG8_MMA(1, 1, At, B1); PG8_BAR; PG8_SCHED;
	s_add_i32 s41, 0, 0x18000
	v_add_u32_e32 v136, s41, v153
	s_add_i32 s43, 0, 0x1c000
	ds_read_b128 v[146:149], v136
	ds_read_b128 v[158:161], v136 offset:1024
	ds_read_b128 v[168:171], v136 offset:2048
	ds_read_b128 v[172:175], v136 offset:3072
	v_add_u32_e32 v136, s43, v153
	ds_read_b128 v[176:179], v136
	ds_read_b128 v[180:183], v136 offset:1024
	ds_read_b128 v[184:187], v136 offset:2048
	ds_read_b128 v[188:191], v136 offset:3072
	s_add_u32 s62, s62, 0x80000
	s_addc_u32 s63, s63, 0
	s_mov_b32 m0, s71
	ds_read_b128 v[192:195], v157 offset:32768
	ds_read_b128 v[196:199], v157 offset:33792
	ds_read_b128 v[200:203], v157 offset:34816
	ds_read_b128 v[204:207], v157 offset:35840
	ds_read_b128 v[208:211], v157 offset:36864
	ds_read_b128 v[212:215], v157 offset:37888
	ds_read_b128 v[216:219], v157 offset:38912
	ds_read_b128 v[220:223], v157 offset:39936
	global_load_lds_dwordx4 v128, s[62:63]
	s_mov_b32 m0, s72
	s_nop 0
	global_load_lds_dwordx4 v132, s[62:63]
	s_waitcnt vmcnt(8)
	s_waitcnt lgkmcnt(0)
	s_barrier
	s_setprio 0
	s_waitcnt lgkmcnt(0)
	v_mfma_f32_16x16x32_bf16 v[124:127], v[146:149], v[192:195], v[124:127]
	v_mfma_f32_16x16x32_bf16 v[120:123], v[168:171], v[192:195], v[120:123]
	v_mfma_f32_16x16x32_bf16 v[108:111], v[146:149], v[200:203], v[108:111]
	v_mfma_f32_16x16x32_bf16 v[104:107], v[168:171], v[200:203], v[104:107]
	v_mfma_f32_16x16x32_bf16 v[92:95], v[146:149], v[208:211], v[92:95]
	v_mfma_f32_16x16x32_bf16 v[88:91], v[168:171], v[208:211], v[88:91]
	v_mfma_f32_16x16x32_bf16 v[76:79], v[146:149], v[216:219], v[76:79]
	v_mfma_f32_16x16x32_bf16 v[72:75], v[168:171], v[216:219], v[72:75]
	v_mfma_f32_16x16x32_bf16 v[124:127], v[158:161], v[196:199], v[124:127]
	v_mfma_f32_16x16x32_bf16 v[120:123], v[172:175], v[196:199], v[120:123]
	v_mfma_f32_16x16x32_bf16 v[108:111], v[158:161], v[204:207], v[108:111]
	v_mfma_f32_16x16x32_bf16 v[104:107], v[172:175], v[204:207], v[104:107]
	v_mfma_f32_16x16x32_bf16 v[92:95], v[158:161], v[212:215], v[92:95]
	v_mfma_f32_16x16x32_bf16 v[88:91], v[172:175], v[212:215], v[88:91]
	v_mfma_f32_16x16x32_bf16 v[76:79], v[158:161], v[220:223], v[76:79]
	v_mfma_f32_16x16x32_bf16 v[72:75], v[172:175], v[220:223], v[72:75]
	v_mfma_f32_16x16x32_bf16 v[116:119], v[176:179], v[192:195], v[116:119]
	v_mfma_f32_16x16x32_bf16 v[112:115], v[184:187], v[192:195], v[112:115]
	v_mfma_f32_16x16x32_bf16 v[100:103], v[176:179], v[200:203], v[100:103]
	v_mfma_f32_16x16x32_bf16 v[96:99], v[184:187], v[200:203], v[96:99]
	v_mfma_f32_16x16x32_bf16 v[84:87], v[176:179], v[208:211], v[84:87]
	v_mfma_f32_16x16x32_bf16 v[80:83], v[184:187], v[208:211], v[80:83]
	v_mfma_f32_16x16x32_bf16 v[68:71], v[176:179], v[216:219], v[68:71]
	v_mfma_f32_16x16x32_bf16 v[64:67], v[184:187], v[216:219], v[64:67]
	v_mfma_f32_16x16x32_bf16 v[116:119], v[180:183], v[196:199], v[116:119]
	v_mfma_f32_16x16x32_bf16 v[112:115], v[188:191], v[196:199], v[112:115]
	v_mfma_f32_16x16x32_bf16 v[100:103], v[180:183], v[204:207], v[100:103]
	v_mfma_f32_16x16x32_bf16 v[96:99], v[188:191], v[204:207], v[96:99]
	v_mfma_f32_16x16x32_bf16 v[84:87], v[180:183], v[212:215], v[84:87]
	v_mfma_f32_16x16x32_bf16 v[80:83], v[188:191], v[212:215], v[80:83]
	v_mfma_f32_16x16x32_bf16 v[68:71], v[180:183], v[220:223], v[68:71]
	v_mfma_f32_16x16x32_bf16 v[64:67], v[188:191], v[220:223], v[64:67]
	s_setprio 1
	s_barrier
	s_add_i32 s41, s41, s68
	v_lshl_add_u64 v[150:151], v[150:151], 0, s[20:21]
	s_mov_b32 m0, s41
	ds_read_b128 v[192:195], v157 offset:49152
	ds_read_b128 v[196:199], v157 offset:50176
	ds_read_b128 v[200:203], v157 offset:51200
	ds_read_b128 v[204:207], v157 offset:52224
	ds_read_b128 v[208:211], v157 offset:53248
	ds_read_b128 v[212:215], v157 offset:54272
	ds_read_b128 v[216:219], v157 offset:55296
	ds_read_b128 v[220:223], v157 offset:56320
	global_load_lds_dwordx4 v[150:151], off
	s_add_i32 m0, s41, 0x2000
	s_add_u32 s60, s60, 0x80080
	v_lshl_add_u64 v[150:151], v[224:225], 0, s[20:21]
	s_addc_u32 s61, s61, 0
	s_add_i32 s41, s43, s68
	global_load_lds_dwordx4 v[150:151], off
	s_mov_b32 m0, s41
	s_nop 0
	global_load_lds_dwordx4 v130, s[60:61]
	s_add_i32 m0, s41, 0x2000
	s_nop 0
	global_load_lds_dwordx4 v134, s[60:61]
	v_lshl_add_u64 v[150:151], v[226:227], 0, s[20:21]
	s_mov_b32 m0, s78
	s_nop 0
	global_load_lds_dwordx4 v[150:151], off
	v_lshl_add_u64 v[150:151], v[228:229], 0, s[20:21]
	s_mov_b32 m0, s79
	s_nop 0
	global_load_lds_dwordx4 v[150:151], off
	s_waitcnt vmcnt(8)
	s_waitcnt lgkmcnt(0)
	s_barrier
	s_setprio 0
	s_waitcnt lgkmcnt(0)
	v_mfma_f32_16x16x32_bf16 v[60:63], v[146:149], v[192:195], v[60:63]
	v_mfma_f32_16x16x32_bf16 v[56:59], v[168:171], v[192:195], v[56:59]
	v_mfma_f32_16x16x32_bf16 v[44:47], v[146:149], v[200:203], v[44:47]
	v_mfma_f32_16x16x32_bf16 v[40:43], v[168:171], v[200:203], v[40:43]
	v_mfma_f32_16x16x32_bf16 v[28:31], v[146:149], v[208:211], v[28:31]
	v_mfma_f32_16x16x32_bf16 v[24:27], v[168:171], v[208:211], v[24:27]
	v_mfma_f32_16x16x32_bf16 v[12:15], v[146:149], v[216:219], v[12:15]
	v_mfma_f32_16x16x32_bf16 v[8:11], v[168:171], v[216:219], v[8:11]
	v_mfma_f32_16x16x32_bf16 v[60:63], v[158:161], v[196:199], v[60:63]
	v_mfma_f32_16x16x32_bf16 v[56:59], v[172:175], v[196:199], v[56:59]
	v_mfma_f32_16x16x32_bf16 v[44:47], v[158:161], v[204:207], v[44:47]
	v_mfma_f32_16x16x32_bf16 v[40:43], v[172:175], v[204:207], v[40:43]
	v_mfma_f32_16x16x32_bf16 v[28:31], v[158:161], v[212:215], v[28:31]
	v_mfma_f32_16x16x32_bf16 v[24:27], v[172:175], v[212:215], v[24:27]
	v_mfma_f32_16x16x32_bf16 v[12:15], v[158:161], v[220:223], v[12:15]
	v_mfma_f32_16x16x32_bf16 v[8:11], v[172:175], v[220:223], v[8:11]
	v_mfma_f32_16x16x32_bf16 v[52:55], v[176:179], v[192:195], v[52:55]
	v_mfma_f32_16x16x32_bf16 v[48:51], v[184:187], v[192:195], v[48:51]
	v_mfma_f32_16x16x32_bf16 v[36:39], v[176:179], v[200:203], v[36:39]
	v_mfma_f32_16x16x32_bf16 v[32:35], v[184:187], v[200:203], v[32:35]
	v_mfma_f32_16x16x32_bf16 v[20:23], v[176:179], v[208:211], v[20:23]
	v_mfma_f32_16x16x32_bf16 v[16:19], v[184:187], v[208:211], v[16:19]
	v_mfma_f32_16x16x32_bf16 v[4:7], v[176:179], v[216:219], v[4:7]
	v_mfma_f32_16x16x32_bf16 v[0:3], v[184:187], v[216:219], v[0:3]
	v_mfma_f32_16x16x32_bf16 v[52:55], v[180:183], v[196:199], v[52:55]
	v_mfma_f32_16x16x32_bf16 v[48:51], v[188:191], v[196:199], v[48:51]
	v_mfma_f32_16x16x32_bf16 v[36:39], v[180:183], v[204:207], v[36:39]
	v_mfma_f32_16x16x32_bf16 v[32:35], v[188:191], v[204:207], v[32:35]
	v_mfma_f32_16x16x32_bf16 v[20:23], v[180:183], v[212:215], v[20:23]
	v_mfma_f32_16x16x32_bf16 v[16:19], v[188:191], v[212:215], v[16:19]
	v_mfma_f32_16x16x32_bf16 v[4:7], v[180:183], v[220:223], v[4:7]
	v_mfma_f32_16x16x32_bf16 v[0:3], v[188:191], v[220:223], v[0:3]
	s_setprio 1
	s_barrier
	s_add_i32 s34, s34, 2
	s_add_u32 s54, s54, 0x100
	s_addc_u32 s55, s55, 0
	s_add_u32 s31, s31, 0x100
	s_addc_u32 s33, s33, 0
	s_cmp_gt_u32 s34, 29
	s_cbranch_scc0 .LBB0_497
	s_and_b64 vcc, exec, s[22:23]
	s_cbranch_vccz .LBB0_500
	s_barrier

; #define PG8_STAGE(bufoff, gbase, voff) do { _Pragma("unroll") for (int _i = 0; _i < 2; ++_i) \
;         __builtin_amdgcn_global_load_lds((const unsigned*)((const char*)(gbase) + (voff)[_i]), (PG8_LAS unsigned*)(lds + (bufoff) + ldsw + _i * 8192), 16, 0, 0); } while (0)
; #define PG8_LDA(dst, b, h) do { _Pragma("unroll") for (int m = 0; m < 4; ++m) _Pragma("unroll") for (int k = 0; k < 2; ++k) dst[m][k] = *(const PG8_LAS bf16x8*)(lds + PG8_SA(b, h) + aoff + m * 2048 + k * 1024); } while (0)
; #define PG8_LDB(dst, b, h) do { _Pragma("unroll") for (int n = 0; n < 2; ++n) _Pragma("unroll") for (int k = 0; k < 2; ++k) dst[n][k] = *(const PG8_LAS bf16x8*)(lds + PG8_SB(b, h) + boff + n * 2048 + k * 1024); } while (0)
; #define PG8_MMA(ai, bj, At, Bt) do { __builtin_amdgcn_s_setprio(1); _Pragma("unroll") for (int m = 0; m < 4; ++m) _Pragma("unroll") for (int n = 0; n < 2; ++n) _Pragma("unroll") for (int k = 0; k < 2; ++k) \
;         acc[ai][bj][m][n] = __builtin_amdgcn_mfma_f32_16x16x32_bf16(Bt[n][k], At[m][k], acc[ai][bj][m][n], 0, 0, 0); __builtin_amdgcn_s_setprio(0); } while (0)
; #define PG8_WAIT_V(n) asm volatile("s_waitcnt vmcnt(" #n ")" ::: "memory")
; #define PG8_WAIT_L(n) asm volatile("s_waitcnt lgkmcnt(" #n ")" ::: "memory")
; template <class Epi, class Sched, bool ALIGN_EPI = false, bool SP2 = false>
; __device__ __forceinline__ void gemm_phase(PG8_LAS unsigned char* lds, const Gemm g, const Sched& S, const Epi& E) {
;     ...
;             const bool last = (t == nt - 2);
;             const char* a1 = cA + (size_t)(t + 1) * kstep;
;             const char* a2 = last ? nA : cA + (size_t)(t + 2) * kstep; const char* b2 = last ? nB : cB + (size_t)(t + 2) * kstep;
;             const char* a3 = a2 + kstep; const char* b3 = b2 + kstep;
;             if (last && has_next) S.a_ready(nxt);
;             if constexpr (SP2) {
;             PG8_LDB(B0, 0, 0); PG8_LDB(B1, 0, 1); PG8_SCHED; PG8_LDA(At, 0, 0); PG8_STAGE(PG8_SA(1, 1), a1 + hstepA, voffA);
;             PG8_WAIT_V(8); PG8_WAIT_L(0); PG8_BAR; PG8_MMA(0, 0, At, B0); PG8_MMA(0, 1, At, B1); PG8_BAR; PG8_SCHED;
;             PG8_LDA(At, 0, 1); PG8_STAGE(PG8_SB(0, 0), b2, voffB); PG8_STAGE(PG8_SB(0, 1), b2 + hstepB, voffB); PG8_STAGE(PG8_SA(0, 0), a2, voffA);
;             PG8_WAIT_V(8); PG8_WAIT_L(0); PG8_BAR; PG8_MMA(1, 0, At, B0); PG8_MMA(1, 1, At, B1); PG8_BAR; PG8_SCHED;
.LBB0_829:
	ds_read_b128 v[144:147], v153
	ds_read_b128 v[158:161], v153 offset:1024
	ds_read_b128 v[166:169], v153 offset:2048
	ds_read_b128 v[170:173], v153 offset:3072
	ds_read_b128 v[174:177], v154
	ds_read_b128 v[178:181], v154 offset:1024
	ds_read_b128 v[182:185], v154 offset:2048
	ds_read_b128 v[186:189], v154 offset:3072
	s_add_u32 s40, s0, 0xffdc0080
	s_addc_u32 s41, s1, -1
	s_cmp_eq_u32 s58, 12
	s_cselect_b32 s43, s21, s41
	s_cselect_b32 s42, s20, s40
	s_cselect_b32 s41, s19, s57
	s_cselect_b32 s40, s55, s56
	s_add_i32 m0, s33, 0xc000
	ds_read_b128 v[190:193], v155
	ds_read_b128 v[194:197], v155 offset:1024
	ds_read_b128 v[198:201], v155 offset:2048
	ds_read_b128 v[202:205], v155 offset:3072
	ds_read_b128 v[206:209], v155 offset:4096
	ds_read_b128 v[210:213], v155 offset:5120
	ds_read_b128 v[214:217], v155 offset:6144
	ds_read_b128 v[218:221], v155 offset:7168
	global_load_lds_dwordx4 v136, s[0:1]
	s_add_i32 m0, s33, 0xe000
	s_nop 0
	global_load_lds_dwordx4 v138, s[0:1]
	s_waitcnt vmcnt(8)
	s_waitcnt lgkmcnt(0)
	s_barrier
	s_setprio 0
	s_waitcnt lgkmcnt(0)
	v_mfma_f32_16x16x32_bf16 v[124:127], v[144:147], v[190:193], v[124:127]
	v_mfma_f32_16x16x32_bf16 v[120:123], v[166:169], v[190:193], v[120:123]
	v_mfma_f32_16x16x32_bf16 v[108:111], v[144:147], v[198:201], v[108:111]
	v_mfma_f32_16x16x32_bf16 v[104:107], v[166:169], v[198:201], v[104:107]
	v_mfma_f32_16x16x32_bf16 v[92:95], v[144:147], v[206:209], v[92:95]
	v_mfma_f32_16x16x32_bf16 v[88:91], v[166:169], v[206:209], v[88:91]
	v_mfma_f32_16x16x32_bf16 v[76:79], v[144:147], v[214:217], v[76:79]
	v_mfma_f32_16x16x32_bf16 v[72:75], v[166:169], v[214:217], v[72:75]
	v_mfma_f32_16x16x32_bf16 v[124:127], v[158:161], v[194:197], v[124:127]
	v_mfma_f32_16x16x32_bf16 v[120:123], v[170:173], v[194:197], v[120:123]
	v_mfma_f32_16x16x32_bf16 v[108:111], v[158:161], v[202:205], v[108:111]
	v_mfma_f32_16x16x32_bf16 v[104:107], v[170:173], v[202:205], v[104:107]
	v_mfma_f32_16x16x32_bf16 v[92:95], v[158:161], v[210:213], v[92:95]
	v_mfma_f32_16x16x32_bf16 v[88:91], v[170:173], v[210:213], v[88:91]
	v_mfma_f32_16x16x32_bf16 v[76:79], v[158:161], v[218:221], v[76:79]
	v_mfma_f32_16x16x32_bf16 v[72:75], v[170:173], v[218:221], v[72:75]
	v_mfma_f32_16x16x32_bf16 v[116:119], v[174:177], v[190:193], v[116:119]
	v_mfma_f32_16x16x32_bf16 v[112:115], v[182:185], v[190:193], v[112:115]
	v_mfma_f32_16x16x32_bf16 v[100:103], v[174:177], v[198:201], v[100:103]
	v_mfma_f32_16x16x32_bf16 v[96:99], v[182:185], v[198:201], v[96:99]
	v_mfma_f32_16x16x32_bf16 v[84:87], v[174:177], v[206:209], v[84:87]
	v_mfma_f32_16x16x32_bf16 v[80:83], v[182:185], v[206:209], v[80:83]
	v_mfma_f32_16x16x32_bf16 v[68:71], v[174:177], v[214:217], v[68:71]
	v_mfma_f32_16x16x32_bf16 v[64:67], v[182:185], v[214:217], v[64:67]
	v_mfma_f32_16x16x32_bf16 v[116:119], v[178:181], v[194:197], v[116:119]
	v_mfma_f32_16x16x32_bf16 v[112:115], v[186:189], v[194:197], v[112:115]
	v_mfma_f32_16x16x32_bf16 v[100:103], v[178:181], v[202:205], v[100:103]
	v_mfma_f32_16x16x32_bf16 v[96:99], v[186:189], v[202:205], v[96:99]
	v_mfma_f32_16x16x32_bf16 v[84:87], v[178:181], v[210:213], v[84:87]
	v_mfma_f32_16x16x32_bf16 v[80:83], v[186:189], v[210:213], v[80:83]
	v_mfma_f32_16x16x32_bf16 v[68:71], v[178:181], v[218:221], v[68:71]
	v_mfma_f32_16x16x32_bf16 v[64:67], v[186:189], v[218:221], v[64:67]
	s_setprio 1
	s_barrier
	s_add_i32 s59, s49, s30
	v_lshl_add_u64 v[148:149], s[40:41], 0, v[132:133]
	s_mov_b32 m0, s59
	ds_read_b128 v[190:193], v155 offset:16384
	ds_read_b128 v[194:197], v155 offset:17408
	ds_read_b128 v[198:201], v155 offset:18432
	ds_read_b128 v[202:205], v155 offset:19456
	ds_read_b128 v[206:209], v155 offset:20480
	ds_read_b128 v[210:213], v155 offset:21504
	ds_read_b128 v[214:217], v155 offset:22528
	ds_read_b128 v[218:221], v155 offset:23552
	global_load_lds_dwordx4 v132, s[40:41]
	s_add_i32 m0, s59, 0x2000
	s_add_u32 s60, s40, 0x40000
	v_lshl_add_u64 v[222:223], s[40:41], 0, v[128:129]
	s_addc_u32 s61, s41, 0
	s_add_i32 s59, s50, s30
	global_load_lds_dwordx4 v128, s[40:41]
	s_mov_b32 m0, s59
	v_lshl_add_u64 v[226:227], s[42:43], 0, v[130:131]
	global_load_lds_dwordx4 v132, s[60:61]
	s_add_i32 m0, s59, 0x2000
	s_nop 0
	global_load_lds_dwordx4 v128, s[60:61]
	v_lshl_add_u64 v[224:225], s[42:43], 0, v[134:135]
	s_mov_b32 m0, s33
	s_nop 0
	global_load_lds_dwordx4 v134, s[42:43]
	s_mov_b32 m0, s34
	s_nop 0
	global_load_lds_dwordx4 v130, s[42:43]
	s_waitcnt vmcnt(8)
	s_waitcnt lgkmcnt(0)
	s_barrier
	s_setprio 0
	s_waitcnt lgkmcnt(0)
	v_mfma_f32_16x16x32_bf16 v[60:63], v[144:147], v[190:193], v[60:63]
	v_mfma_f32_16x16x32_bf16 v[56:59], v[166:169], v[190:193], v[56:59]
	v_mfma_f32_16x16x32_bf16 v[44:47], v[144:147], v[198:201], v[44:47]
	v_mfma_f32_16x16x32_bf16 v[40:43], v[166:169], v[198:201], v[40:43]
	v_mfma_f32_16x16x32_bf16 v[28:31], v[144:147], v[206:209], v[28:31]
	v_mfma_f32_16x16x32_bf16 v[24:27], v[166:169], v[206:209], v[24:27]
	v_mfma_f32_16x16x32_bf16 v[12:15], v[144:147], v[214:217], v[12:15]
	v_mfma_f32_16x16x32_bf16 v[8:11], v[166:169], v[214:217], v[8:11]
	v_mfma_f32_16x16x32_bf16 v[60:63], v[158:161], v[194:197], v[60:63]
	v_mfma_f32_16x16x32_bf16 v[56:59], v[170:173], v[194:197], v[56:59]
	v_mfma_f32_16x16x32_bf16 v[44:47], v[158:161], v[202:205], v[44:47]
	v_mfma_f32_16x16x32_bf16 v[40:43], v[170:173], v[202:205], v[40:43]
	v_mfma_f32_16x16x32_bf16 v[28:31], v[158:161], v[210:213], v[28:31]
	v_mfma_f32_16x16x32_bf16 v[24:27], v[170:173], v[210:213], v[24:27]
	v_mfma_f32_16x16x32_bf16 v[12:15], v[158:161], v[218:221], v[12:15]
	v_mfma_f32_16x16x32_bf16 v[8:11], v[170:173], v[218:221], v[8:11]
	v_mfma_f32_16x16x32_bf16 v[52:55], v[174:177], v[190:193], v[52:55]
	v_mfma_f32_16x16x32_bf16 v[48:51], v[182:185], v[190:193], v[48:51]
	v_mfma_f32_16x16x32_bf16 v[36:39], v[174:177], v[198:201], v[36:39]
	v_mfma_f32_16x16x32_bf16 v[32:35], v[182:185], v[198:201], v[32:35]
	v_mfma_f32_16x16x32_bf16 v[20:23], v[174:177], v[206:209], v[20:23]
	v_mfma_f32_16x16x32_bf16 v[16:19], v[182:185], v[206:209], v[16:19]
	v_mfma_f32_16x16x32_bf16 v[4:7], v[174:177], v[214:217], v[4:7]
	v_mfma_f32_16x16x32_bf16 v[0:3], v[182:185], v[214:217], v[0:3]
	v_mfma_f32_16x16x32_bf16 v[52:55], v[178:181], v[194:197], v[52:55]
	v_mfma_f32_16x16x32_bf16 v[48:51], v[186:189], v[194:197], v[48:51]
	v_mfma_f32_16x16x32_bf16 v[36:39], v[178:181], v[202:205], v[36:39]
	v_mfma_f32_16x16x32_bf16 v[32:35], v[186:189], v[202:205], v[32:35]
	v_mfma_f32_16x16x32_bf16 v[20:23], v[178:181], v[210:213], v[20:23]
	v_mfma_f32_16x16x32_bf16 v[16:19], v[186:189], v[210:213], v[16:19]
	v_mfma_f32_16x16x32_bf16 v[4:7], v[178:181], v[218:221], v[4:7]
	v_mfma_f32_16x16x32_bf16 v[0:3], v[186:189], v[218:221], v[0:3]
	s_setprio 1
	s_barrier
; #define PG8_STAGE(bufoff, gbase, voff) do { _Pragma("unroll") for (int _i = 0; _i < 2; ++_i) \
;         __builtin_amdgcn_global_load_lds((const unsigned*)((const char*)(gbase) + (voff)[_i]), (PG8_LAS unsigned*)(lds + (bufoff) + ldsw + _i * 8192), 16, 0, 0); } while (0)
; #define PG8_LDA(dst, b, h) do { _Pragma("unroll") for (int m = 0; m < 4; ++m) _Pragma("unroll") for (int k = 0; k < 2; ++k) dst[m][k] = *(const PG8_LAS bf16x8*)(lds + PG8_SA(b, h) + aoff + m * 2048 + k * 1024); } while (0)
; #define PG8_LDB(dst, b, h) do { _Pragma("unroll") for (int n = 0; n < 2; ++n) _Pragma("unroll") for (int k = 0; k < 2; ++k) dst[n][k] = *(const PG8_LAS bf16x8*)(lds + PG8_SB(b, h) + boff + n * 2048 + k * 1024); } while (0)
; #define PG8_MMA(ai, bj, At, Bt) do { __builtin_amdgcn_s_setprio(1); _Pragma("unroll") for (int m = 0; m < 4; ++m) _Pragma("unroll") for (int n = 0; n < 2; ++n) _Pragma("unroll") for (int k = 0; k < 2; ++k) \
;         acc[ai][bj][m][n] = __builtin_amdgcn_mfma_f32_16x16x32_bf16(Bt[n][k], At[m][k], acc[ai][bj][m][n], 0, 0, 0); __builtin_amdgcn_s_setprio(0); } while (0)
; #define PG8_WAIT_V(n) asm volatile("s_waitcnt vmcnt(" #n ")" ::: "memory")
; #define PG8_WAIT_L(n) asm volatile("s_waitcnt lgkmcnt(" #n ")" ::: "memory")
; #define PG8_BAR __builtin_amdgcn_s_barrier()
; #define PG8_SCHED __builtin_amdgcn_sched_barrier(0)
; template <class Epi, class Sched, bool ALIGN_EPI = false, bool SP2 = false>
; __device__ __forceinline__ void gemm_phase(PG8_LAS unsigned char* lds, const Gemm g, const Sched& S, const Epi& E) {
;     ...
;             PG8_LDB(B0, 1, 0); PG8_LDB(B1, 1, 1); PG8_SCHED; PG8_LDA(At, 1, 0); PG8_STAGE(PG8_SA(0, 1), a2 + hstepA, voffA);
;             PG8_WAIT_V(8); PG8_WAIT_L(0); PG8_BAR; PG8_MMA(0, 0, At, B0); PG8_MMA(0, 1, At, B1); PG8_BAR; PG8_SCHED;
;             PG8_LDA(At, 1, 1); PG8_STAGE(PG8_SB(1, 0), b3, voffB); PG8_STAGE(PG8_SB(1, 1), b3 + hstepB, voffB); PG8_STAGE(PG8_SA(1, 0), a3, voffA);
;             PG8_WAIT_V(8); PG8_WAIT_L(0); PG8_BAR; PG8_MMA(1, 0, At, B0); PG8_MMA(1, 1, At, B1); PG8_BAR; PG8_SCHED;
	s_add_i32 s59, 0, 0x18000
	v_add_u32_e32 v157, s59, v151
	s_add_i32 s60, 0, 0x1c000
	ds_read_b128 v[144:147], v157
	ds_read_b128 v[158:161], v157 offset:1024
	ds_read_b128 v[166:169], v157 offset:2048
	ds_read_b128 v[170:173], v157 offset:3072
	v_add_u32_e32 v157, s60, v151
	ds_read_b128 v[174:177], v157
	ds_read_b128 v[178:181], v157 offset:1024
	ds_read_b128 v[182:185], v157 offset:2048
	ds_read_b128 v[186:189], v157 offset:3072
	s_add_u32 s42, s42, 0x240000
	s_addc_u32 s43, s43, 0
	s_mov_b32 m0, s35
	ds_read_b128 v[190:193], v155 offset:32768
	ds_read_b128 v[194:197], v155 offset:33792
	ds_read_b128 v[198:201], v155 offset:34816
	ds_read_b128 v[202:205], v155 offset:35840
	ds_read_b128 v[206:209], v155 offset:36864
	ds_read_b128 v[210:213], v155 offset:37888
	ds_read_b128 v[214:217], v155 offset:38912
	ds_read_b128 v[218:221], v155 offset:39936
	global_load_lds_dwordx4 v134, s[42:43]
	s_mov_b32 m0, s44
	s_nop 0
	global_load_lds_dwordx4 v130, s[42:43]
	s_waitcnt vmcnt(8)
	s_waitcnt lgkmcnt(0)
	s_barrier
	s_setprio 0
	s_waitcnt lgkmcnt(0)
	v_mfma_f32_16x16x32_bf16 v[124:127], v[144:147], v[190:193], v[124:127]
	v_mfma_f32_16x16x32_bf16 v[120:123], v[166:169], v[190:193], v[120:123]
	v_mfma_f32_16x16x32_bf16 v[108:111], v[144:147], v[198:201], v[108:111]
	v_mfma_f32_16x16x32_bf16 v[104:107], v[166:169], v[198:201], v[104:107]
	v_mfma_f32_16x16x32_bf16 v[92:95], v[144:147], v[206:209], v[92:95]
	v_mfma_f32_16x16x32_bf16 v[88:91], v[166:169], v[206:209], v[88:91]
	v_mfma_f32_16x16x32_bf16 v[76:79], v[144:147], v[214:217], v[76:79]
	v_mfma_f32_16x16x32_bf16 v[72:75], v[166:169], v[214:217], v[72:75]
	v_mfma_f32_16x16x32_bf16 v[124:127], v[158:161], v[194:197], v[124:127]
	v_mfma_f32_16x16x32_bf16 v[120:123], v[170:173], v[194:197], v[120:123]
	v_mfma_f32_16x16x32_bf16 v[108:111], v[158:161], v[202:205], v[108:111]
	v_mfma_f32_16x16x32_bf16 v[104:107], v[170:173], v[202:205], v[104:107]
	v_mfma_f32_16x16x32_bf16 v[92:95], v[158:161], v[210:213], v[92:95]
	v_mfma_f32_16x16x32_bf16 v[88:91], v[170:173], v[210:213], v[88:91]
	v_mfma_f32_16x16x32_bf16 v[76:79], v[158:161], v[218:221], v[76:79]
	v_mfma_f32_16x16x32_bf16 v[72:75], v[170:173], v[218:221], v[72:75]
	v_mfma_f32_16x16x32_bf16 v[116:119], v[174:177], v[190:193], v[116:119]
	v_mfma_f32_16x16x32_bf16 v[112:115], v[182:185], v[190:193], v[112:115]
	v_mfma_f32_16x16x32_bf16 v[100:103], v[174:177], v[198:201], v[100:103]
	v_mfma_f32_16x16x32_bf16 v[96:99], v[182:185], v[198:201], v[96:99]
	v_mfma_f32_16x16x32_bf16 v[84:87], v[174:177], v[206:209], v[84:87]
	v_mfma_f32_16x16x32_bf16 v[80:83], v[182:185], v[206:209], v[80:83]
	v_mfma_f32_16x16x32_bf16 v[68:71], v[174:177], v[214:217], v[68:71]
	v_mfma_f32_16x16x32_bf16 v[64:67], v[182:185], v[214:217], v[64:67]
	v_mfma_f32_16x16x32_bf16 v[116:119], v[178:181], v[194:197], v[116:119]
	v_mfma_f32_16x16x32_bf16 v[112:115], v[186:189], v[194:197], v[112:115]
	v_mfma_f32_16x16x32_bf16 v[100:103], v[178:181], v[202:205], v[100:103]
	v_mfma_f32_16x16x32_bf16 v[96:99], v[186:189], v[202:205], v[96:99]
	v_mfma_f32_16x16x32_bf16 v[84:87], v[178:181], v[210:213], v[84:87]
	v_mfma_f32_16x16x32_bf16 v[80:83], v[186:189], v[210:213], v[80:83]
	v_mfma_f32_16x16x32_bf16 v[68:71], v[178:181], v[218:221], v[68:71]
	v_mfma_f32_16x16x32_bf16 v[64:67], v[186:189], v[218:221], v[64:67]
	s_setprio 1
	s_barrier
	s_add_i32 s42, s59, s30
	v_lshl_add_u64 v[148:149], v[148:149], 0, s[10:11]
	s_mov_b32 m0, s42
	ds_read_b128 v[190:193], v155 offset:49152
	ds_read_b128 v[194:197], v155 offset:50176
	ds_read_b128 v[198:201], v155 offset:51200
	ds_read_b128 v[202:205], v155 offset:52224
	ds_read_b128 v[206:209], v155 offset:53248
	ds_read_b128 v[210:213], v155 offset:54272
	ds_read_b128 v[214:217], v155 offset:55296
	ds_read_b128 v[218:221], v155 offset:56320
	global_load_lds_dwordx4 v[148:149], off
	s_add_i32 m0, s42, 0x2000
	s_add_u32 s40, s40, 0x40080
	v_lshl_add_u64 v[148:149], v[222:223], 0, s[10:11]
	s_addc_u32 s41, s41, 0
	s_add_i32 s42, s60, s30
	global_load_lds_dwordx4 v[148:149], off
	s_mov_b32 m0, s42
	s_nop 0
	global_load_lds_dwordx4 v132, s[40:41]
	s_add_i32 m0, s42, 0x2000
	s_nop 0
	global_load_lds_dwordx4 v128, s[40:41]
	v_lshl_add_u64 v[148:149], v[224:225], 0, s[10:11]
	s_mov_b32 m0, s47
	s_nop 0
	global_load_lds_dwordx4 v[148:149], off
	v_lshl_add_u64 v[148:149], v[226:227], 0, s[10:11]
	s_mov_b32 m0, s48
	s_nop 0
	global_load_lds_dwordx4 v[148:149], off
	s_waitcnt vmcnt(8)
	s_waitcnt lgkmcnt(0)
	s_barrier
	s_setprio 0
	s_waitcnt lgkmcnt(0)
	v_mfma_f32_16x16x32_bf16 v[60:63], v[144:147], v[190:193], v[60:63]
	v_mfma_f32_16x16x32_bf16 v[56:59], v[166:169], v[190:193], v[56:59]
	v_mfma_f32_16x16x32_bf16 v[44:47], v[144:147], v[198:201], v[44:47]
	v_mfma_f32_16x16x32_bf16 v[40:43], v[166:169], v[198:201], v[40:43]
	v_mfma_f32_16x16x32_bf16 v[28:31], v[144:147], v[206:209], v[28:31]
	v_mfma_f32_16x16x32_bf16 v[24:27], v[166:169], v[206:209], v[24:27]
	v_mfma_f32_16x16x32_bf16 v[12:15], v[144:147], v[214:217], v[12:15]
	v_mfma_f32_16x16x32_bf16 v[8:11], v[166:169], v[214:217], v[8:11]
	v_mfma_f32_16x16x32_bf16 v[60:63], v[158:161], v[194:197], v[60:63]
	v_mfma_f32_16x16x32_bf16 v[56:59], v[170:173], v[194:197], v[56:59]
	v_mfma_f32_16x16x32_bf16 v[44:47], v[158:161], v[202:205], v[44:47]
	v_mfma_f32_16x16x32_bf16 v[40:43], v[170:173], v[202:205], v[40:43]
	v_mfma_f32_16x16x32_bf16 v[28:31], v[158:161], v[210:213], v[28:31]
	v_mfma_f32_16x16x32_bf16 v[24:27], v[170:173], v[210:213], v[24:27]
	v_mfma_f32_16x16x32_bf16 v[12:15], v[158:161], v[218:221], v[12:15]
	v_mfma_f32_16x16x32_bf16 v[8:11], v[170:173], v[218:221], v[8:11]
	v_mfma_f32_16x16x32_bf16 v[52:55], v[174:177], v[190:193], v[52:55]
	v_mfma_f32_16x16x32_bf16 v[48:51], v[182:185], v[190:193], v[48:51]
	v_mfma_f32_16x16x32_bf16 v[36:39], v[174:177], v[198:201], v[36:39]
	v_mfma_f32_16x16x32_bf16 v[32:35], v[182:185], v[198:201], v[32:35]
	v_mfma_f32_16x16x32_bf16 v[20:23], v[174:177], v[206:209], v[20:23]
	v_mfma_f32_16x16x32_bf16 v[16:19], v[182:185], v[206:209], v[16:19]
	v_mfma_f32_16x16x32_bf16 v[4:7], v[174:177], v[214:217], v[4:7]
	v_mfma_f32_16x16x32_bf16 v[0:3], v[182:185], v[214:217], v[0:3]
	v_mfma_f32_16x16x32_bf16 v[52:55], v[178:181], v[194:197], v[52:55]
	v_mfma_f32_16x16x32_bf16 v[48:51], v[186:189], v[194:197], v[48:51]
	v_mfma_f32_16x16x32_bf16 v[36:39], v[178:181], v[202:205], v[36:39]
	v_mfma_f32_16x16x32_bf16 v[32:35], v[186:189], v[202:205], v[32:35]
	v_mfma_f32_16x16x32_bf16 v[20:23], v[178:181], v[210:213], v[20:23]
	v_mfma_f32_16x16x32_bf16 v[16:19], v[186:189], v[210:213], v[16:19]
	v_mfma_f32_16x16x32_bf16 v[4:7], v[178:181], v[218:221], v[4:7]
	v_mfma_f32_16x16x32_bf16 v[0:3], v[186:189], v[218:221], v[0:3]
	s_setprio 1
	s_barrier
	s_add_i32 s58, s58, 2
	s_add_u32 s0, s0, 0x100
	s_addc_u32 s1, s1, 0
	s_add_u32 s56, s56, 0x100
	s_addc_u32 s57, s57, 0
	s_cmp_gt_u32 s58, 13
	s_cbranch_scc0 .LBB0_829
	s_and_b64 vcc, exec, s[16:17]
	s_cbranch_vccz .LBB0_832
	s_barrier

; #define PG8_STAGE(bufoff, gbase, voff) do { _Pragma("unroll") for (int _i = 0; _i < 2; ++_i) \
;         __builtin_amdgcn_global_load_lds((const unsigned*)((const char*)(gbase) + (voff)[_i]), (PG8_LAS unsigned*)(lds + (bufoff) + ldsw + _i * 8192), 16, 0, 0); } while (0)
; #define PG8_LDA(dst, b, h) do { _Pragma("unroll") for (int m = 0; m < 4; ++m) _Pragma("unroll") for (int k = 0; k < 2; ++k) dst[m][k] = *(const PG8_LAS bf16x8*)(lds + PG8_SA(b, h) + aoff + m * 2048 + k * 1024); } while (0)
; #define PG8_LDB(dst, b, h) do { _Pragma("unroll") for (int n = 0; n < 2; ++n) _Pragma("unroll") for (int k = 0; k < 2; ++k) dst[n][k] = *(const PG8_LAS bf16x8*)(lds + PG8_SB(b, h) + boff + n * 2048 + k * 1024); } while (0)
; #define PG8_MMA(ai, bj, At, Bt) do { __builtin_amdgcn_s_setprio(1); _Pragma("unroll") for (int m = 0; m < 4; ++m) _Pragma("unroll") for (int n = 0; n < 2; ++n) _Pragma("unroll") for (int k = 0; k < 2; ++k) \
;         acc[ai][bj][m][n] = __builtin_amdgcn_mfma_f32_16x16x32_bf16(Bt[n][k], At[m][k], acc[ai][bj][m][n], 0, 0, 0); __builtin_amdgcn_s_setprio(0); } while (0)
; #define PG8_WAIT_V(n) asm volatile("s_waitcnt vmcnt(" #n ")" ::: "memory")
; #define PG8_WAIT_L(n) asm volatile("s_waitcnt lgkmcnt(" #n ")" ::: "memory")
; template <class Epi, class Sched, bool ALIGN_EPI = false, bool SP2 = false>
; __device__ __forceinline__ void gemm_phase(PG8_LAS unsigned char* lds, const Gemm g, const Sched& S, const Epi& E) {
;     ...
;             const bool last = (t == nt - 2);
;             const char* a1 = cA + (size_t)(t + 1) * kstep;
;             const char* a2 = last ? nA : cA + (size_t)(t + 2) * kstep; const char* b2 = last ? nB : cB + (size_t)(t + 2) * kstep;
;             const char* a3 = a2 + kstep; const char* b3 = b2 + kstep;
;             if (last && has_next) S.a_ready(nxt);
;             if constexpr (SP2) {
;             PG8_LDB(B0, 0, 0); PG8_LDB(B1, 0, 1); PG8_SCHED; PG8_LDA(At, 0, 0); PG8_STAGE(PG8_SA(1, 1), a1 + hstepA, voffA);
;             PG8_WAIT_V(8); PG8_WAIT_L(0); PG8_BAR; PG8_MMA(0, 0, At, B0); PG8_MMA(0, 1, At, B1); PG8_BAR; PG8_SCHED;
;             PG8_LDA(At, 0, 1); PG8_STAGE(PG8_SB(0, 0), b2, voffB); PG8_STAGE(PG8_SB(0, 1), b2 + hstepB, voffB); PG8_STAGE(PG8_SA(0, 0), a2, voffA);
;             PG8_WAIT_V(8); PG8_WAIT_L(0); PG8_BAR; PG8_MMA(1, 0, At, B0); PG8_MMA(1, 1, At, B1); PG8_BAR; PG8_SCHED;
.LBB0_848:
	ds_read_b128 v[144:147], v155
	ds_read_b128 v[148:151], v155 offset:1024
	ds_read_b128 v[166:169], v155 offset:2048
	ds_read_b128 v[170:173], v155 offset:3072
	ds_read_b128 v[174:177], v156
	ds_read_b128 v[178:181], v156 offset:1024
	ds_read_b128 v[182:185], v156 offset:2048
	ds_read_b128 v[186:189], v156 offset:3072
	s_add_u32 s42, s0, 0xffdc0080
	s_addc_u32 s43, s1, -1
	s_cmp_eq_u32 s58, 12
	s_cselect_b32 s45, s23, s43
	s_cselect_b32 s44, s22, s42
	s_cselect_b32 s43, s21, s34
	s_cselect_b32 s42, s30, s31
	s_add_i32 m0, s46, 0xc000
	ds_read_b128 v[190:193], v157
	ds_read_b128 v[194:197], v157 offset:1024
	ds_read_b128 v[198:201], v157 offset:2048
	ds_read_b128 v[202:205], v157 offset:3072
	ds_read_b128 v[206:209], v157 offset:4096
	ds_read_b128 v[210:213], v157 offset:5120
	ds_read_b128 v[214:217], v157 offset:6144
	ds_read_b128 v[218:221], v157 offset:7168
	global_load_lds_dwordx4 v136, s[0:1]
	s_add_i32 m0, s46, 0xe000
	s_nop 0
	global_load_lds_dwordx4 v138, s[0:1]
	s_waitcnt vmcnt(8)
	s_waitcnt lgkmcnt(0)
	s_barrier
	s_setprio 0
	s_waitcnt lgkmcnt(0)
	v_mfma_f32_16x16x32_bf16 v[124:127], v[144:147], v[190:193], v[124:127]
	v_mfma_f32_16x16x32_bf16 v[120:123], v[166:169], v[190:193], v[120:123]
	v_mfma_f32_16x16x32_bf16 v[108:111], v[144:147], v[198:201], v[108:111]
	v_mfma_f32_16x16x32_bf16 v[104:107], v[166:169], v[198:201], v[104:107]
	v_mfma_f32_16x16x32_bf16 v[92:95], v[144:147], v[206:209], v[92:95]
	v_mfma_f32_16x16x32_bf16 v[88:91], v[166:169], v[206:209], v[88:91]
	v_mfma_f32_16x16x32_bf16 v[76:79], v[144:147], v[214:217], v[76:79]
	v_mfma_f32_16x16x32_bf16 v[72:75], v[166:169], v[214:217], v[72:75]
	v_mfma_f32_16x16x32_bf16 v[124:127], v[148:151], v[194:197], v[124:127]
	v_mfma_f32_16x16x32_bf16 v[120:123], v[170:173], v[194:197], v[120:123]
	v_mfma_f32_16x16x32_bf16 v[108:111], v[148:151], v[202:205], v[108:111]
	v_mfma_f32_16x16x32_bf16 v[104:107], v[170:173], v[202:205], v[104:107]
	v_mfma_f32_16x16x32_bf16 v[92:95], v[148:151], v[210:213], v[92:95]
	v_mfma_f32_16x16x32_bf16 v[88:91], v[170:173], v[210:213], v[88:91]
	v_mfma_f32_16x16x32_bf16 v[76:79], v[148:151], v[218:221], v[76:79]
	v_mfma_f32_16x16x32_bf16 v[72:75], v[170:173], v[218:221], v[72:75]
	v_mfma_f32_16x16x32_bf16 v[116:119], v[174:177], v[190:193], v[116:119]
	v_mfma_f32_16x16x32_bf16 v[112:115], v[182:185], v[190:193], v[112:115]
	v_mfma_f32_16x16x32_bf16 v[100:103], v[174:177], v[198:201], v[100:103]
	v_mfma_f32_16x16x32_bf16 v[96:99], v[182:185], v[198:201], v[96:99]
	v_mfma_f32_16x16x32_bf16 v[84:87], v[174:177], v[206:209], v[84:87]
	v_mfma_f32_16x16x32_bf16 v[80:83], v[182:185], v[206:209], v[80:83]
	v_mfma_f32_16x16x32_bf16 v[68:71], v[174:177], v[214:217], v[68:71]
	v_mfma_f32_16x16x32_bf16 v[64:67], v[182:185], v[214:217], v[64:67]
	v_mfma_f32_16x16x32_bf16 v[116:119], v[178:181], v[194:197], v[116:119]
	v_mfma_f32_16x16x32_bf16 v[112:115], v[186:189], v[194:197], v[112:115]
	v_mfma_f32_16x16x32_bf16 v[100:103], v[178:181], v[202:205], v[100:103]
	v_mfma_f32_16x16x32_bf16 v[96:99], v[186:189], v[202:205], v[96:99]
	v_mfma_f32_16x16x32_bf16 v[84:87], v[178:181], v[210:213], v[84:87]
	v_mfma_f32_16x16x32_bf16 v[80:83], v[186:189], v[210:213], v[80:83]
	v_mfma_f32_16x16x32_bf16 v[68:71], v[178:181], v[218:221], v[68:71]
	v_mfma_f32_16x16x32_bf16 v[64:67], v[186:189], v[218:221], v[64:67]
	s_setprio 1
	s_barrier
	s_add_i32 s59, s54, s33
	v_lshl_add_u64 v[160:161], s[42:43], 0, v[132:133]
	s_mov_b32 m0, s59
	ds_read_b128 v[190:193], v157 offset:16384
	ds_read_b128 v[194:197], v157 offset:17408
	ds_read_b128 v[198:201], v157 offset:18432
	ds_read_b128 v[202:205], v157 offset:19456
	ds_read_b128 v[206:209], v157 offset:20480
	ds_read_b128 v[210:213], v157 offset:21504
	ds_read_b128 v[214:217], v157 offset:22528
	ds_read_b128 v[218:221], v157 offset:23552
	global_load_lds_dwordx4 v132, s[42:43]
	s_add_i32 m0, s59, 0x2000
	s_add_u32 s60, s42, 0x40000
	v_lshl_add_u64 v[222:223], s[42:43], 0, v[128:129]
	s_addc_u32 s61, s43, 0
	s_add_i32 s59, s55, s33
	global_load_lds_dwordx4 v128, s[42:43]
	s_mov_b32 m0, s59
	v_lshl_add_u64 v[226:227], s[44:45], 0, v[130:131]
	global_load_lds_dwordx4 v132, s[60:61]
	s_add_i32 m0, s59, 0x2000
	s_nop 0
	global_load_lds_dwordx4 v128, s[60:61]
	v_lshl_add_u64 v[224:225], s[44:45], 0, v[134:135]
	s_mov_b32 m0, s46
	s_nop 0
	global_load_lds_dwordx4 v134, s[44:45]
	s_mov_b32 m0, s47
	s_nop 0
	global_load_lds_dwordx4 v130, s[44:45]
	s_waitcnt vmcnt(8)
	s_waitcnt lgkmcnt(0)
	s_barrier
	s_setprio 0
	s_waitcnt lgkmcnt(0)
	v_mfma_f32_16x16x32_bf16 v[60:63], v[144:147], v[190:193], v[60:63]
	v_mfma_f32_16x16x32_bf16 v[56:59], v[166:169], v[190:193], v[56:59]
	v_mfma_f32_16x16x32_bf16 v[44:47], v[144:147], v[198:201], v[44:47]
	v_mfma_f32_16x16x32_bf16 v[40:43], v[166:169], v[198:201], v[40:43]
	v_mfma_f32_16x16x32_bf16 v[28:31], v[144:147], v[206:209], v[28:31]
	v_mfma_f32_16x16x32_bf16 v[24:27], v[166:169], v[206:209], v[24:27]
	v_mfma_f32_16x16x32_bf16 v[12:15], v[144:147], v[214:217], v[12:15]
	v_mfma_f32_16x16x32_bf16 v[8:11], v[166:169], v[214:217], v[8:11]
	v_mfma_f32_16x16x32_bf16 v[60:63], v[148:151], v[194:197], v[60:63]
	v_mfma_f32_16x16x32_bf16 v[56:59], v[170:173], v[194:197], v[56:59]
	v_mfma_f32_16x16x32_bf16 v[44:47], v[148:151], v[202:205], v[44:47]
	v_mfma_f32_16x16x32_bf16 v[40:43], v[170:173], v[202:205], v[40:43]
	v_mfma_f32_16x16x32_bf16 v[28:31], v[148:151], v[210:213], v[28:31]
	v_mfma_f32_16x16x32_bf16 v[24:27], v[170:173], v[210:213], v[24:27]
	v_mfma_f32_16x16x32_bf16 v[12:15], v[148:151], v[218:221], v[12:15]
	v_mfma_f32_16x16x32_bf16 v[8:11], v[170:173], v[218:221], v[8:11]
	v_mfma_f32_16x16x32_bf16 v[52:55], v[174:177], v[190:193], v[52:55]
	v_mfma_f32_16x16x32_bf16 v[48:51], v[182:185], v[190:193], v[48:51]
	v_mfma_f32_16x16x32_bf16 v[36:39], v[174:177], v[198:201], v[36:39]
	v_mfma_f32_16x16x32_bf16 v[32:35], v[182:185], v[198:201], v[32:35]
	v_mfma_f32_16x16x32_bf16 v[20:23], v[174:177], v[206:209], v[20:23]
	v_mfma_f32_16x16x32_bf16 v[16:19], v[182:185], v[206:209], v[16:19]
	v_mfma_f32_16x16x32_bf16 v[4:7], v[174:177], v[214:217], v[4:7]
	v_mfma_f32_16x16x32_bf16 v[0:3], v[182:185], v[214:217], v[0:3]
	v_mfma_f32_16x16x32_bf16 v[52:55], v[178:181], v[194:197], v[52:55]
	v_mfma_f32_16x16x32_bf16 v[48:51], v[186:189], v[194:197], v[48:51]
	v_mfma_f32_16x16x32_bf16 v[36:39], v[178:181], v[202:205], v[36:39]
	v_mfma_f32_16x16x32_bf16 v[32:35], v[186:189], v[202:205], v[32:35]
	v_mfma_f32_16x16x32_bf16 v[20:23], v[178:181], v[210:213], v[20:23]
	v_mfma_f32_16x16x32_bf16 v[16:19], v[186:189], v[210:213], v[16:19]
	v_mfma_f32_16x16x32_bf16 v[4:7], v[178:181], v[218:221], v[4:7]
	v_mfma_f32_16x16x32_bf16 v[0:3], v[186:189], v[218:221], v[0:3]
	s_setprio 1
	s_barrier
; #define PG8_STAGE(bufoff, gbase, voff) do { _Pragma("unroll") for (int _i = 0; _i < 2; ++_i) \
;         __builtin_amdgcn_global_load_lds((const unsigned*)((const char*)(gbase) + (voff)[_i]), (PG8_LAS unsigned*)(lds + (bufoff) + ldsw + _i * 8192), 16, 0, 0); } while (0)
; #define PG8_LDA(dst, b, h) do { _Pragma("unroll") for (int m = 0; m < 4; ++m) _Pragma("unroll") for (int k = 0; k < 2; ++k) dst[m][k] = *(const PG8_LAS bf16x8*)(lds + PG8_SA(b, h) + aoff + m * 2048 + k * 1024); } while (0)
; #define PG8_LDB(dst, b, h) do { _Pragma("unroll") for (int n = 0; n < 2; ++n) _Pragma("unroll") for (int k = 0; k < 2; ++k) dst[n][k] = *(const PG8_LAS bf16x8*)(lds + PG8_SB(b, h) + boff + n * 2048 + k * 1024); } while (0)
; #define PG8_MMA(ai, bj, At, Bt) do { __builtin_amdgcn_s_setprio(1); _Pragma("unroll") for (int m = 0; m < 4; ++m) _Pragma("unroll") for (int n = 0; n < 2; ++n) _Pragma("unroll") for (int k = 0; k < 2; ++k) \
;         acc[ai][bj][m][n] = __builtin_amdgcn_mfma_f32_16x16x32_bf16(Bt[n][k], At[m][k], acc[ai][bj][m][n], 0, 0, 0); __builtin_amdgcn_s_setprio(0); } while (0)
; #define PG8_WAIT_V(n) asm volatile("s_waitcnt vmcnt(" #n ")" ::: "memory")
; #define PG8_WAIT_L(n) asm volatile("s_waitcnt lgkmcnt(" #n ")" ::: "memory")
; #define PG8_BAR __builtin_amdgcn_s_barrier()
; #define PG8_SCHED __builtin_amdgcn_sched_barrier(0)
; template <class Epi, class Sched, bool ALIGN_EPI = false, bool SP2 = false>
; __device__ __forceinline__ void gemm_phase(PG8_LAS unsigned char* lds, const Gemm g, const Sched& S, const Epi& E) {
;     ...
;             PG8_LDB(B0, 1, 0); PG8_LDB(B1, 1, 1); PG8_SCHED; PG8_LDA(At, 1, 0); PG8_STAGE(PG8_SA(0, 1), a2 + hstepA, voffA);
;             PG8_WAIT_V(8); PG8_WAIT_L(0); PG8_BAR; PG8_MMA(0, 0, At, B0); PG8_MMA(0, 1, At, B1); PG8_BAR; PG8_SCHED;
;             PG8_LDA(At, 1, 1); PG8_STAGE(PG8_SB(1, 0), b3, voffB); PG8_STAGE(PG8_SB(1, 1), b3 + hstepB, voffB); PG8_STAGE(PG8_SA(1, 0), a3, voffA);
;             PG8_WAIT_V(8); PG8_WAIT_L(0); PG8_BAR; PG8_MMA(1, 0, At, B0); PG8_MMA(1, 1, At, B1); PG8_BAR; PG8_SCHED;
	s_add_i32 s59, 0, 0x18000
	v_add_u32_e32 v159, s59, v153
	s_add_i32 s60, 0, 0x1c000
	ds_read_b128 v[144:147], v159
	ds_read_b128 v[148:151], v159 offset:1024
	ds_read_b128 v[166:169], v159 offset:2048
	ds_read_b128 v[170:173], v159 offset:3072
	v_add_u32_e32 v159, s60, v153
	ds_read_b128 v[174:177], v159
	ds_read_b128 v[178:181], v159 offset:1024
	ds_read_b128 v[182:185], v159 offset:2048
	ds_read_b128 v[186:189], v159 offset:3072
	s_add_u32 s44, s44, 0x240000
	s_addc_u32 s45, s45, 0
	s_mov_b32 m0, s48
	ds_read_b128 v[190:193], v157 offset:32768
	ds_read_b128 v[194:197], v157 offset:33792
	ds_read_b128 v[198:201], v157 offset:34816
	ds_read_b128 v[202:205], v157 offset:35840
	ds_read_b128 v[206:209], v157 offset:36864
	ds_read_b128 v[210:213], v157 offset:37888
	ds_read_b128 v[214:217], v157 offset:38912
	ds_read_b128 v[218:221], v157 offset:39936
	global_load_lds_dwordx4 v134, s[44:45]
	s_mov_b32 m0, s49
	s_nop 0
	global_load_lds_dwordx4 v130, s[44:45]
	s_waitcnt vmcnt(8)
	s_waitcnt lgkmcnt(0)
	s_barrier
	s_setprio 0
	s_waitcnt lgkmcnt(0)
	v_mfma_f32_16x16x32_bf16 v[124:127], v[144:147], v[190:193], v[124:127]
	v_mfma_f32_16x16x32_bf16 v[120:123], v[166:169], v[190:193], v[120:123]
	v_mfma_f32_16x16x32_bf16 v[108:111], v[144:147], v[198:201], v[108:111]
	v_mfma_f32_16x16x32_bf16 v[104:107], v[166:169], v[198:201], v[104:107]
	v_mfma_f32_16x16x32_bf16 v[92:95], v[144:147], v[206:209], v[92:95]
	v_mfma_f32_16x16x32_bf16 v[88:91], v[166:169], v[206:209], v[88:91]
	v_mfma_f32_16x16x32_bf16 v[76:79], v[144:147], v[214:217], v[76:79]
	v_mfma_f32_16x16x32_bf16 v[72:75], v[166:169], v[214:217], v[72:75]
	v_mfma_f32_16x16x32_bf16 v[124:127], v[148:151], v[194:197], v[124:127]
	v_mfma_f32_16x16x32_bf16 v[120:123], v[170:173], v[194:197], v[120:123]
	v_mfma_f32_16x16x32_bf16 v[108:111], v[148:151], v[202:205], v[108:111]
	v_mfma_f32_16x16x32_bf16 v[104:107], v[170:173], v[202:205], v[104:107]
	v_mfma_f32_16x16x32_bf16 v[92:95], v[148:151], v[210:213], v[92:95]
	v_mfma_f32_16x16x32_bf16 v[88:91], v[170:173], v[210:213], v[88:91]
	v_mfma_f32_16x16x32_bf16 v[76:79], v[148:151], v[218:221], v[76:79]
	v_mfma_f32_16x16x32_bf16 v[72:75], v[170:173], v[218:221], v[72:75]
	v_mfma_f32_16x16x32_bf16 v[116:119], v[174:177], v[190:193], v[116:119]
	v_mfma_f32_16x16x32_bf16 v[112:115], v[182:185], v[190:193], v[112:115]
	v_mfma_f32_16x16x32_bf16 v[100:103], v[174:177], v[198:201], v[100:103]
	v_mfma_f32_16x16x32_bf16 v[96:99], v[182:185], v[198:201], v[96:99]
	v_mfma_f32_16x16x32_bf16 v[84:87], v[174:177], v[206:209], v[84:87]
	v_mfma_f32_16x16x32_bf16 v[80:83], v[182:185], v[206:209], v[80:83]
	v_mfma_f32_16x16x32_bf16 v[68:71], v[174:177], v[214:217], v[68:71]
	v_mfma_f32_16x16x32_bf16 v[64:67], v[182:185], v[214:217], v[64:67]
	v_mfma_f32_16x16x32_bf16 v[116:119], v[178:181], v[194:197], v[116:119]
	v_mfma_f32_16x16x32_bf16 v[112:115], v[186:189], v[194:197], v[112:115]
	v_mfma_f32_16x16x32_bf16 v[100:103], v[178:181], v[202:205], v[100:103]
	v_mfma_f32_16x16x32_bf16 v[96:99], v[186:189], v[202:205], v[96:99]
	v_mfma_f32_16x16x32_bf16 v[84:87], v[178:181], v[210:213], v[84:87]
	v_mfma_f32_16x16x32_bf16 v[80:83], v[186:189], v[210:213], v[80:83]
	v_mfma_f32_16x16x32_bf16 v[68:71], v[178:181], v[218:221], v[68:71]
	v_mfma_f32_16x16x32_bf16 v[64:67], v[186:189], v[218:221], v[64:67]
	s_setprio 1
	s_barrier
	s_add_i32 s44, s59, s33
	v_lshl_add_u64 v[160:161], v[160:161], 0, s[16:17]
	s_mov_b32 m0, s44
	ds_read_b128 v[190:193], v157 offset:49152
	ds_read_b128 v[194:197], v157 offset:50176
	ds_read_b128 v[198:201], v157 offset:51200
	ds_read_b128 v[202:205], v157 offset:52224
	ds_read_b128 v[206:209], v157 offset:53248
	ds_read_b128 v[210:213], v157 offset:54272
	ds_read_b128 v[214:217], v157 offset:55296
	ds_read_b128 v[218:221], v157 offset:56320
	global_load_lds_dwordx4 v[160:161], off
	s_add_i32 m0, s44, 0x2000
	s_add_u32 s42, s42, 0x40080
	v_lshl_add_u64 v[160:161], v[222:223], 0, s[16:17]
	s_addc_u32 s43, s43, 0
	s_add_i32 s44, s60, s33
	global_load_lds_dwordx4 v[160:161], off
	s_mov_b32 m0, s44
	s_nop 0
	global_load_lds_dwordx4 v132, s[42:43]
	s_add_i32 m0, s44, 0x2000
	s_nop 0
	global_load_lds_dwordx4 v128, s[42:43]
	v_lshl_add_u64 v[160:161], v[224:225], 0, s[16:17]
	s_mov_b32 m0, s52
	s_nop 0
	global_load_lds_dwordx4 v[160:161], off
	v_lshl_add_u64 v[160:161], v[226:227], 0, s[16:17]
	s_mov_b32 m0, s53
	s_nop 0
	global_load_lds_dwordx4 v[160:161], off
	s_waitcnt vmcnt(8)
	s_waitcnt lgkmcnt(0)
	s_barrier
	s_setprio 0
	s_waitcnt lgkmcnt(0)
	v_mfma_f32_16x16x32_bf16 v[60:63], v[144:147], v[190:193], v[60:63]
	v_mfma_f32_16x16x32_bf16 v[56:59], v[166:169], v[190:193], v[56:59]
	v_mfma_f32_16x16x32_bf16 v[44:47], v[144:147], v[198:201], v[44:47]
	v_mfma_f32_16x16x32_bf16 v[40:43], v[166:169], v[198:201], v[40:43]
	v_mfma_f32_16x16x32_bf16 v[28:31], v[144:147], v[206:209], v[28:31]
	v_mfma_f32_16x16x32_bf16 v[24:27], v[166:169], v[206:209], v[24:27]
	v_mfma_f32_16x16x32_bf16 v[12:15], v[144:147], v[214:217], v[12:15]
	v_mfma_f32_16x16x32_bf16 v[8:11], v[166:169], v[214:217], v[8:11]
	v_mfma_f32_16x16x32_bf16 v[60:63], v[148:151], v[194:197], v[60:63]
	v_mfma_f32_16x16x32_bf16 v[56:59], v[170:173], v[194:197], v[56:59]
	v_mfma_f32_16x16x32_bf16 v[44:47], v[148:151], v[202:205], v[44:47]
	v_mfma_f32_16x16x32_bf16 v[40:43], v[170:173], v[202:205], v[40:43]
	v_mfma_f32_16x16x32_bf16 v[28:31], v[148:151], v[210:213], v[28:31]
	v_mfma_f32_16x16x32_bf16 v[24:27], v[170:173], v[210:213], v[24:27]
	v_mfma_f32_16x16x32_bf16 v[12:15], v[148:151], v[218:221], v[12:15]
	v_mfma_f32_16x16x32_bf16 v[8:11], v[170:173], v[218:221], v[8:11]
	v_mfma_f32_16x16x32_bf16 v[52:55], v[174:177], v[190:193], v[52:55]
	v_mfma_f32_16x16x32_bf16 v[48:51], v[182:185], v[190:193], v[48:51]
	v_mfma_f32_16x16x32_bf16 v[36:39], v[174:177], v[198:201], v[36:39]
	v_mfma_f32_16x16x32_bf16 v[32:35], v[182:185], v[198:201], v[32:35]
	v_mfma_f32_16x16x32_bf16 v[20:23], v[174:177], v[206:209], v[20:23]
	v_mfma_f32_16x16x32_bf16 v[16:19], v[182:185], v[206:209], v[16:19]
	v_mfma_f32_16x16x32_bf16 v[4:7], v[174:177], v[214:217], v[4:7]
	v_mfma_f32_16x16x32_bf16 v[0:3], v[182:185], v[214:217], v[0:3]
	v_mfma_f32_16x16x32_bf16 v[52:55], v[178:181], v[194:197], v[52:55]
	v_mfma_f32_16x16x32_bf16 v[48:51], v[186:189], v[194:197], v[48:51]
	v_mfma_f32_16x16x32_bf16 v[36:39], v[178:181], v[202:205], v[36:39]
	v_mfma_f32_16x16x32_bf16 v[32:35], v[186:189], v[202:205], v[32:35]
	v_mfma_f32_16x16x32_bf16 v[20:23], v[178:181], v[210:213], v[20:23]
	v_mfma_f32_16x16x32_bf16 v[16:19], v[186:189], v[210:213], v[16:19]
	v_mfma_f32_16x16x32_bf16 v[4:7], v[178:181], v[218:221], v[4:7]
	v_mfma_f32_16x16x32_bf16 v[0:3], v[186:189], v[218:221], v[0:3]
	s_setprio 1
	s_barrier
	s_add_i32 s58, s58, 2
	s_add_u32 s0, s0, 0x100
	s_addc_u32 s1, s1, 0
	s_add_u32 s31, s31, 0x100
	s_addc_u32 s34, s34, 0
	s_cmp_gt_u32 s58, 13
	s_cbranch_scc0 .LBB0_848
	s_and_b64 vcc, exec, s[18:19]
	s_cbranch_vccz .LBB0_851
	s_barrier

; #define PG8_STAGE(bufoff, gbase, voff) do { _Pragma("unroll") for (int _i = 0; _i < 2; ++_i) \
;         __builtin_amdgcn_global_load_lds((const unsigned*)((const char*)(gbase) + (voff)[_i]), (PG8_LAS unsigned*)(lds + (bufoff) + ldsw + _i * 8192), 16, 0, 0); } while (0)
; #define PG8_LDA(dst, b, h) do { _Pragma("unroll") for (int m = 0; m < 4; ++m) _Pragma("unroll") for (int k = 0; k < 2; ++k) dst[m][k] = *(const PG8_LAS bf16x8*)(lds + PG8_SA(b, h) + aoff + m * 2048 + k * 1024); } while (0)
; #define PG8_LDB(dst, b, h) do { _Pragma("unroll") for (int n = 0; n < 2; ++n) _Pragma("unroll") for (int k = 0; k < 2; ++k) dst[n][k] = *(const PG8_LAS bf16x8*)(lds + PG8_SB(b, h) + boff + n * 2048 + k * 1024); } while (0)
; #define PG8_MMA(ai, bj, At, Bt) do { __builtin_amdgcn_s_setprio(1); _Pragma("unroll") for (int m = 0; m < 4; ++m) _Pragma("unroll") for (int n = 0; n < 2; ++n) _Pragma("unroll") for (int k = 0; k < 2; ++k) \
;         acc[ai][bj][m][n] = __builtin_amdgcn_mfma_f32_16x16x32_bf16(Bt[n][k], At[m][k], acc[ai][bj][m][n], 0, 0, 0); __builtin_amdgcn_s_setprio(0); } while (0)
; #define PG8_WAIT_V(n) asm volatile("s_waitcnt vmcnt(" #n ")" ::: "memory")
; #define PG8_WAIT_L(n) asm volatile("s_waitcnt lgkmcnt(" #n ")" ::: "memory")
; template <class Epi, class Sched, bool ALIGN_EPI = false, bool SP2 = false>
; __device__ __forceinline__ void gemm_phase(PG8_LAS unsigned char* lds, const Gemm g, const Sched& S, const Epi& E) {
;     ...
;             const bool last = (t == nt - 2);
;             const char* a1 = cA + (size_t)(t + 1) * kstep;
;             const char* a2 = last ? nA : cA + (size_t)(t + 2) * kstep; const char* b2 = last ? nB : cB + (size_t)(t + 2) * kstep;
;             const char* a3 = a2 + kstep; const char* b3 = b2 + kstep;
;             if (last && has_next) S.a_ready(nxt);
;             if constexpr (SP2) {
;             PG8_LDB(B0, 0, 0); PG8_LDB(B1, 0, 1); PG8_SCHED; PG8_LDA(At, 0, 0); PG8_STAGE(PG8_SA(1, 1), a1 + hstepA, voffA);
;             PG8_WAIT_V(8); PG8_WAIT_L(0); PG8_BAR; PG8_MMA(0, 0, At, B0); PG8_MMA(0, 1, At, B1); PG8_BAR; PG8_SCHED;
;             PG8_LDA(At, 0, 1); PG8_STAGE(PG8_SB(0, 0), b2, voffB); PG8_STAGE(PG8_SB(0, 1), b2 + hstepB, voffB); PG8_STAGE(PG8_SA(0, 0), a2, voffA);
;             PG8_WAIT_V(8); PG8_WAIT_L(0); PG8_BAR; PG8_MMA(1, 0, At, B0); PG8_MMA(1, 1, At, B1); PG8_BAR; PG8_SCHED;
.LBB0_927:
	ds_read_b128 v[156:159], v153
	ds_read_b128 v[166:169], v153 offset:1024
	ds_read_b128 v[170:173], v153 offset:2048
	ds_read_b128 v[174:177], v153 offset:3072
	ds_read_b128 v[178:181], v154
	ds_read_b128 v[182:185], v154 offset:1024
	ds_read_b128 v[186:189], v154 offset:2048
	ds_read_b128 v[190:193], v154 offset:3072
	s_add_u32 s54, s52, 0xfff80080
	s_addc_u32 s55, s53, -1
	s_cmp_eq_u32 s71, 28
	s_cselect_b32 s57, s45, s55
	s_cselect_b32 s56, s65, s54
	s_cselect_b32 s55, s43, s70
	s_cselect_b32 s54, s68, s69
	s_add_i32 m0, s29, 0xc000
	ds_read_b128 v[194:197], v155
	ds_read_b128 v[198:201], v155 offset:1024
	ds_read_b128 v[202:205], v155 offset:2048
	ds_read_b128 v[206:209], v155 offset:3072
	ds_read_b128 v[210:213], v155 offset:4096
	ds_read_b128 v[214:217], v155 offset:5120
	ds_read_b128 v[218:221], v155 offset:6144
	ds_read_b128 v[222:225], v155 offset:7168
	global_load_lds_dwordx4 v136, s[52:53]
	s_add_i32 m0, s29, 0xe000
	s_nop 0
	global_load_lds_dwordx4 v138, s[52:53]
	s_waitcnt vmcnt(8)
	s_waitcnt lgkmcnt(0)
	s_barrier
	s_setprio 0
	s_waitcnt lgkmcnt(0)
	v_mfma_f32_16x16x32_bf16 v[124:127], v[156:159], v[194:197], v[124:127]
	v_mfma_f32_16x16x32_bf16 v[120:123], v[170:173], v[194:197], v[120:123]
	v_mfma_f32_16x16x32_bf16 v[116:119], v[156:159], v[202:205], v[116:119]
	v_mfma_f32_16x16x32_bf16 v[108:111], v[170:173], v[202:205], v[108:111]
	v_mfma_f32_16x16x32_bf16 v[100:103], v[156:159], v[210:213], v[100:103]
	v_mfma_f32_16x16x32_bf16 v[92:95], v[170:173], v[210:213], v[92:95]
	v_mfma_f32_16x16x32_bf16 v[84:87], v[156:159], v[218:221], v[84:87]
	v_mfma_f32_16x16x32_bf16 v[76:79], v[170:173], v[218:221], v[76:79]
	v_mfma_f32_16x16x32_bf16 v[124:127], v[166:169], v[198:201], v[124:127]
	v_mfma_f32_16x16x32_bf16 v[120:123], v[174:177], v[198:201], v[120:123]
	v_mfma_f32_16x16x32_bf16 v[116:119], v[166:169], v[206:209], v[116:119]
	v_mfma_f32_16x16x32_bf16 v[108:111], v[174:177], v[206:209], v[108:111]
	v_mfma_f32_16x16x32_bf16 v[100:103], v[166:169], v[214:217], v[100:103]
	v_mfma_f32_16x16x32_bf16 v[92:95], v[174:177], v[214:217], v[92:95]
	v_mfma_f32_16x16x32_bf16 v[84:87], v[166:169], v[222:225], v[84:87]
	v_mfma_f32_16x16x32_bf16 v[76:79], v[174:177], v[222:225], v[76:79]
	v_mfma_f32_16x16x32_bf16 v[112:115], v[178:181], v[194:197], v[112:115]
	v_mfma_f32_16x16x32_bf16 v[104:107], v[186:189], v[194:197], v[104:107]
	v_mfma_f32_16x16x32_bf16 v[96:99], v[178:181], v[202:205], v[96:99]
	v_mfma_f32_16x16x32_bf16 v[88:91], v[186:189], v[202:205], v[88:91]
	v_mfma_f32_16x16x32_bf16 v[80:83], v[178:181], v[210:213], v[80:83]
	v_mfma_f32_16x16x32_bf16 v[72:75], v[186:189], v[210:213], v[72:75]
	v_mfma_f32_16x16x32_bf16 v[68:71], v[178:181], v[218:221], v[68:71]
	v_mfma_f32_16x16x32_bf16 v[64:67], v[186:189], v[218:221], v[64:67]
	v_mfma_f32_16x16x32_bf16 v[112:115], v[182:185], v[198:201], v[112:115]
	v_mfma_f32_16x16x32_bf16 v[104:107], v[190:193], v[198:201], v[104:107]
	v_mfma_f32_16x16x32_bf16 v[96:99], v[182:185], v[206:209], v[96:99]
	v_mfma_f32_16x16x32_bf16 v[88:91], v[190:193], v[206:209], v[88:91]
	v_mfma_f32_16x16x32_bf16 v[80:83], v[182:185], v[214:217], v[80:83]
	v_mfma_f32_16x16x32_bf16 v[72:75], v[190:193], v[214:217], v[72:75]
	v_mfma_f32_16x16x32_bf16 v[68:71], v[182:185], v[222:225], v[68:71]
	v_mfma_f32_16x16x32_bf16 v[64:67], v[190:193], v[222:225], v[64:67]
	s_setprio 1
	s_barrier
	s_add_i32 s72, s58, s28
	v_lshl_add_u64 v[144:145], s[54:55], 0, v[130:131]
	s_mov_b32 m0, s72
	ds_read_b128 v[194:197], v155 offset:16384
	ds_read_b128 v[198:201], v155 offset:17408
	ds_read_b128 v[202:205], v155 offset:18432
	ds_read_b128 v[206:209], v155 offset:19456
	ds_read_b128 v[210:213], v155 offset:20480
	ds_read_b128 v[214:217], v155 offset:21504
	ds_read_b128 v[218:221], v155 offset:22528
	ds_read_b128 v[222:225], v155 offset:23552
	global_load_lds_dwordx4 v130, s[54:55]
	s_add_i32 m0, s72, 0x2000
	s_add_u32 s72, s54, 0x80000
	v_lshl_add_u64 v[160:161], s[54:55], 0, v[134:135]
	s_addc_u32 s73, s55, 0
	s_add_i32 s74, s59, s28
	global_load_lds_dwordx4 v134, s[54:55]
	s_mov_b32 m0, s74
	v_lshl_add_u64 v[228:229], s[56:57], 0, v[132:133]
	global_load_lds_dwordx4 v130, s[72:73]
	s_add_i32 m0, s74, 0x2000
	s_nop 0
	global_load_lds_dwordx4 v134, s[72:73]
	v_lshl_add_u64 v[226:227], s[56:57], 0, v[128:129]
	s_mov_b32 m0, s29
	s_nop 0
	global_load_lds_dwordx4 v128, s[56:57]
	s_mov_b32 m0, s30
	s_nop 0
	global_load_lds_dwordx4 v132, s[56:57]
	s_waitcnt vmcnt(8)
	s_waitcnt lgkmcnt(0)
	s_barrier
	s_setprio 0
	s_waitcnt lgkmcnt(0)
	v_mfma_f32_16x16x32_bf16 v[60:63], v[156:159], v[194:197], v[60:63]
	v_mfma_f32_16x16x32_bf16 v[56:59], v[170:173], v[194:197], v[56:59]
	v_mfma_f32_16x16x32_bf16 v[52:55], v[156:159], v[202:205], v[52:55]
	v_mfma_f32_16x16x32_bf16 v[44:47], v[170:173], v[202:205], v[44:47]
	v_mfma_f32_16x16x32_bf16 v[36:39], v[156:159], v[210:213], v[36:39]
	v_mfma_f32_16x16x32_bf16 v[28:31], v[170:173], v[210:213], v[28:31]
	v_mfma_f32_16x16x32_bf16 v[20:23], v[156:159], v[218:221], v[20:23]
	v_mfma_f32_16x16x32_bf16 v[12:15], v[170:173], v[218:221], v[12:15]
	v_mfma_f32_16x16x32_bf16 v[60:63], v[166:169], v[198:201], v[60:63]
	v_mfma_f32_16x16x32_bf16 v[56:59], v[174:177], v[198:201], v[56:59]
	v_mfma_f32_16x16x32_bf16 v[52:55], v[166:169], v[206:209], v[52:55]
	v_mfma_f32_16x16x32_bf16 v[44:47], v[174:177], v[206:209], v[44:47]
	v_mfma_f32_16x16x32_bf16 v[36:39], v[166:169], v[214:217], v[36:39]
	v_mfma_f32_16x16x32_bf16 v[28:31], v[174:177], v[214:217], v[28:31]
	v_mfma_f32_16x16x32_bf16 v[20:23], v[166:169], v[222:225], v[20:23]
	v_mfma_f32_16x16x32_bf16 v[12:15], v[174:177], v[222:225], v[12:15]
	v_mfma_f32_16x16x32_bf16 v[48:51], v[178:181], v[194:197], v[48:51]
	v_mfma_f32_16x16x32_bf16 v[40:43], v[186:189], v[194:197], v[40:43]
	v_mfma_f32_16x16x32_bf16 v[32:35], v[178:181], v[202:205], v[32:35]
	v_mfma_f32_16x16x32_bf16 v[24:27], v[186:189], v[202:205], v[24:27]
	v_mfma_f32_16x16x32_bf16 v[16:19], v[178:181], v[210:213], v[16:19]
	v_mfma_f32_16x16x32_bf16 v[8:11], v[186:189], v[210:213], v[8:11]
	v_mfma_f32_16x16x32_bf16 v[4:7], v[178:181], v[218:221], v[4:7]
	v_mfma_f32_16x16x32_bf16 v[0:3], v[186:189], v[218:221], v[0:3]
	v_mfma_f32_16x16x32_bf16 v[48:51], v[182:185], v[198:201], v[48:51]
	v_mfma_f32_16x16x32_bf16 v[40:43], v[190:193], v[198:201], v[40:43]
	v_mfma_f32_16x16x32_bf16 v[32:35], v[182:185], v[206:209], v[32:35]
	v_mfma_f32_16x16x32_bf16 v[24:27], v[190:193], v[206:209], v[24:27]
	v_mfma_f32_16x16x32_bf16 v[16:19], v[182:185], v[214:217], v[16:19]
	v_mfma_f32_16x16x32_bf16 v[8:11], v[190:193], v[214:217], v[8:11]
	v_mfma_f32_16x16x32_bf16 v[4:7], v[182:185], v[222:225], v[4:7]
	v_mfma_f32_16x16x32_bf16 v[0:3], v[190:193], v[222:225], v[0:3]
	s_setprio 1
	s_barrier
; #define PG8_STAGE(bufoff, gbase, voff) do { _Pragma("unroll") for (int _i = 0; _i < 2; ++_i) \
;         __builtin_amdgcn_global_load_lds((const unsigned*)((const char*)(gbase) + (voff)[_i]), (PG8_LAS unsigned*)(lds + (bufoff) + ldsw + _i * 8192), 16, 0, 0); } while (0)
; #define PG8_LDA(dst, b, h) do { _Pragma("unroll") for (int m = 0; m < 4; ++m) _Pragma("unroll") for (int k = 0; k < 2; ++k) dst[m][k] = *(const PG8_LAS bf16x8*)(lds + PG8_SA(b, h) + aoff + m * 2048 + k * 1024); } while (0)
; #define PG8_LDB(dst, b, h) do { _Pragma("unroll") for (int n = 0; n < 2; ++n) _Pragma("unroll") for (int k = 0; k < 2; ++k) dst[n][k] = *(const PG8_LAS bf16x8*)(lds + PG8_SB(b, h) + boff + n * 2048 + k * 1024); } while (0)
; #define PG8_MMA(ai, bj, At, Bt) do { __builtin_amdgcn_s_setprio(1); _Pragma("unroll") for (int m = 0; m < 4; ++m) _Pragma("unroll") for (int n = 0; n < 2; ++n) _Pragma("unroll") for (int k = 0; k < 2; ++k) \
;         acc[ai][bj][m][n] = __builtin_amdgcn_mfma_f32_16x16x32_bf16(Bt[n][k], At[m][k], acc[ai][bj][m][n], 0, 0, 0); __builtin_amdgcn_s_setprio(0); } while (0)
; #define PG8_WAIT_V(n) asm volatile("s_waitcnt vmcnt(" #n ")" ::: "memory")
; #define PG8_WAIT_L(n) asm volatile("s_waitcnt lgkmcnt(" #n ")" ::: "memory")
; #define PG8_BAR __builtin_amdgcn_s_barrier()
; #define PG8_SCHED __builtin_amdgcn_sched_barrier(0)
; template <class Epi, class Sched, bool ALIGN_EPI = false, bool SP2 = false>
; __device__ __forceinline__ void gemm_phase(PG8_LAS unsigned char* lds, const Gemm g, const Sched& S, const Epi& E) {
;     ...
;             PG8_LDB(B0, 1, 0); PG8_LDB(B1, 1, 1); PG8_SCHED; PG8_LDA(At, 1, 0); PG8_STAGE(PG8_SA(0, 1), a2 + hstepA, voffA);
;             PG8_WAIT_V(8); PG8_WAIT_L(0); PG8_BAR; PG8_MMA(0, 0, At, B0); PG8_MMA(0, 1, At, B1); PG8_BAR; PG8_SCHED;
;             PG8_LDA(At, 1, 1); PG8_STAGE(PG8_SB(1, 0), b3, voffB); PG8_STAGE(PG8_SB(1, 1), b3 + hstepB, voffB); PG8_STAGE(PG8_SA(1, 0), a3, voffA);
;             PG8_WAIT_V(8); PG8_WAIT_L(0); PG8_BAR; PG8_MMA(1, 0, At, B0); PG8_MMA(1, 1, At, B1); PG8_BAR; PG8_SCHED;
	s_add_i32 s72, 0, 0x18000
	v_add_u32_e32 v163, s72, v151
	s_add_i32 s73, 0, 0x1c000
	ds_read_b128 v[156:159], v163
	ds_read_b128 v[166:169], v163 offset:1024
	ds_read_b128 v[170:173], v163 offset:2048
	ds_read_b128 v[174:177], v163 offset:3072
	v_add_u32_e32 v163, s73, v151
	ds_read_b128 v[178:181], v163
	ds_read_b128 v[182:185], v163 offset:1024
	ds_read_b128 v[186:189], v163 offset:2048
	ds_read_b128 v[190:193], v163 offset:3072
	s_add_u32 s56, s56, 0x80000
	s_addc_u32 s57, s57, 0
	s_mov_b32 m0, s31
	ds_read_b128 v[194:197], v155 offset:32768
	ds_read_b128 v[198:201], v155 offset:33792
	ds_read_b128 v[202:205], v155 offset:34816
	ds_read_b128 v[206:209], v155 offset:35840
	ds_read_b128 v[210:213], v155 offset:36864
	ds_read_b128 v[214:217], v155 offset:37888
	ds_read_b128 v[218:221], v155 offset:38912
	ds_read_b128 v[222:225], v155 offset:39936
	global_load_lds_dwordx4 v128, s[56:57]
	s_mov_b32 m0, s33
	s_nop 0
	global_load_lds_dwordx4 v132, s[56:57]
	s_waitcnt vmcnt(8)
	s_waitcnt lgkmcnt(0)
	s_barrier
	s_setprio 0
	s_waitcnt lgkmcnt(0)
	v_mfma_f32_16x16x32_bf16 v[124:127], v[156:159], v[194:197], v[124:127]
	v_mfma_f32_16x16x32_bf16 v[120:123], v[170:173], v[194:197], v[120:123]
	v_mfma_f32_16x16x32_bf16 v[116:119], v[156:159], v[202:205], v[116:119]
	v_mfma_f32_16x16x32_bf16 v[108:111], v[170:173], v[202:205], v[108:111]
	v_mfma_f32_16x16x32_bf16 v[100:103], v[156:159], v[210:213], v[100:103]
	v_mfma_f32_16x16x32_bf16 v[92:95], v[170:173], v[210:213], v[92:95]
	v_mfma_f32_16x16x32_bf16 v[84:87], v[156:159], v[218:221], v[84:87]
	v_mfma_f32_16x16x32_bf16 v[76:79], v[170:173], v[218:221], v[76:79]
	v_mfma_f32_16x16x32_bf16 v[124:127], v[166:169], v[198:201], v[124:127]
	v_mfma_f32_16x16x32_bf16 v[120:123], v[174:177], v[198:201], v[120:123]
	v_mfma_f32_16x16x32_bf16 v[116:119], v[166:169], v[206:209], v[116:119]
	v_mfma_f32_16x16x32_bf16 v[108:111], v[174:177], v[206:209], v[108:111]
	v_mfma_f32_16x16x32_bf16 v[100:103], v[166:169], v[214:217], v[100:103]
	v_mfma_f32_16x16x32_bf16 v[92:95], v[174:177], v[214:217], v[92:95]
	v_mfma_f32_16x16x32_bf16 v[84:87], v[166:169], v[222:225], v[84:87]
	v_mfma_f32_16x16x32_bf16 v[76:79], v[174:177], v[222:225], v[76:79]
	v_mfma_f32_16x16x32_bf16 v[112:115], v[178:181], v[194:197], v[112:115]
	v_mfma_f32_16x16x32_bf16 v[104:107], v[186:189], v[194:197], v[104:107]
	v_mfma_f32_16x16x32_bf16 v[96:99], v[178:181], v[202:205], v[96:99]
	v_mfma_f32_16x16x32_bf16 v[88:91], v[186:189], v[202:205], v[88:91]
	v_mfma_f32_16x16x32_bf16 v[80:83], v[178:181], v[210:213], v[80:83]
	v_mfma_f32_16x16x32_bf16 v[72:75], v[186:189], v[210:213], v[72:75]
	v_mfma_f32_16x16x32_bf16 v[68:71], v[178:181], v[218:221], v[68:71]
	v_mfma_f32_16x16x32_bf16 v[64:67], v[186:189], v[218:221], v[64:67]
	v_mfma_f32_16x16x32_bf16 v[112:115], v[182:185], v[198:201], v[112:115]
	v_mfma_f32_16x16x32_bf16 v[104:107], v[190:193], v[198:201], v[104:107]
	v_mfma_f32_16x16x32_bf16 v[96:99], v[182:185], v[206:209], v[96:99]
	v_mfma_f32_16x16x32_bf16 v[88:91], v[190:193], v[206:209], v[88:91]
	v_mfma_f32_16x16x32_bf16 v[80:83], v[182:185], v[214:217], v[80:83]
	v_mfma_f32_16x16x32_bf16 v[72:75], v[190:193], v[214:217], v[72:75]
	v_mfma_f32_16x16x32_bf16 v[68:71], v[182:185], v[222:225], v[68:71]
	v_mfma_f32_16x16x32_bf16 v[64:67], v[190:193], v[222:225], v[64:67]
	s_setprio 1
	s_barrier
	s_add_i32 s56, s72, s28
	v_lshl_add_u64 v[144:145], v[144:145], 0, s[16:17]
	s_mov_b32 m0, s56
	ds_read_b128 v[194:197], v155 offset:49152
	ds_read_b128 v[198:201], v155 offset:50176
	ds_read_b128 v[202:205], v155 offset:51200
	ds_read_b128 v[206:209], v155 offset:52224
	ds_read_b128 v[210:213], v155 offset:53248
	ds_read_b128 v[214:217], v155 offset:54272
	ds_read_b128 v[218:221], v155 offset:55296
	ds_read_b128 v[222:225], v155 offset:56320
	global_load_lds_dwordx4 v[144:145], off
	s_add_i32 m0, s56, 0x2000
	s_add_u32 s54, s54, 0x80080
	v_lshl_add_u64 v[144:145], v[160:161], 0, s[16:17]
	s_addc_u32 s55, s55, 0
	s_add_i32 s56, s73, s28
	global_load_lds_dwordx4 v[144:145], off
	s_mov_b32 m0, s56
	s_nop 0
	global_load_lds_dwordx4 v130, s[54:55]
	s_add_i32 m0, s56, 0x2000
	s_nop 0
	global_load_lds_dwordx4 v134, s[54:55]
	v_lshl_add_u64 v[144:145], v[226:227], 0, s[16:17]
	s_mov_b32 m0, s35
	s_nop 0
	global_load_lds_dwordx4 v[144:145], off
	v_lshl_add_u64 v[144:145], v[228:229], 0, s[16:17]
	s_mov_b32 m0, s51
	s_nop 0
	global_load_lds_dwordx4 v[144:145], off
	s_waitcnt vmcnt(8)
	s_waitcnt lgkmcnt(0)
	s_barrier
	s_setprio 0
	s_waitcnt lgkmcnt(0)
	v_mfma_f32_16x16x32_bf16 v[60:63], v[156:159], v[194:197], v[60:63]
	v_mfma_f32_16x16x32_bf16 v[56:59], v[170:173], v[194:197], v[56:59]
	v_mfma_f32_16x16x32_bf16 v[52:55], v[156:159], v[202:205], v[52:55]
	v_mfma_f32_16x16x32_bf16 v[44:47], v[170:173], v[202:205], v[44:47]
	v_mfma_f32_16x16x32_bf16 v[36:39], v[156:159], v[210:213], v[36:39]
	v_mfma_f32_16x16x32_bf16 v[28:31], v[170:173], v[210:213], v[28:31]
	v_mfma_f32_16x16x32_bf16 v[20:23], v[156:159], v[218:221], v[20:23]
	v_mfma_f32_16x16x32_bf16 v[12:15], v[170:173], v[218:221], v[12:15]
	v_mfma_f32_16x16x32_bf16 v[60:63], v[166:169], v[198:201], v[60:63]
	v_mfma_f32_16x16x32_bf16 v[56:59], v[174:177], v[198:201], v[56:59]
	v_mfma_f32_16x16x32_bf16 v[52:55], v[166:169], v[206:209], v[52:55]
	v_mfma_f32_16x16x32_bf16 v[44:47], v[174:177], v[206:209], v[44:47]
	v_mfma_f32_16x16x32_bf16 v[36:39], v[166:169], v[214:217], v[36:39]
	v_mfma_f32_16x16x32_bf16 v[28:31], v[174:177], v[214:217], v[28:31]
	v_mfma_f32_16x16x32_bf16 v[20:23], v[166:169], v[222:225], v[20:23]
	v_mfma_f32_16x16x32_bf16 v[12:15], v[174:177], v[222:225], v[12:15]
	v_mfma_f32_16x16x32_bf16 v[48:51], v[178:181], v[194:197], v[48:51]
	v_mfma_f32_16x16x32_bf16 v[40:43], v[186:189], v[194:197], v[40:43]
	v_mfma_f32_16x16x32_bf16 v[32:35], v[178:181], v[202:205], v[32:35]
	v_mfma_f32_16x16x32_bf16 v[24:27], v[186:189], v[202:205], v[24:27]
	v_mfma_f32_16x16x32_bf16 v[16:19], v[178:181], v[210:213], v[16:19]
	v_mfma_f32_16x16x32_bf16 v[8:11], v[186:189], v[210:213], v[8:11]
	v_mfma_f32_16x16x32_bf16 v[4:7], v[178:181], v[218:221], v[4:7]
	v_mfma_f32_16x16x32_bf16 v[0:3], v[186:189], v[218:221], v[0:3]
	v_mfma_f32_16x16x32_bf16 v[48:51], v[182:185], v[198:201], v[48:51]
	v_mfma_f32_16x16x32_bf16 v[40:43], v[190:193], v[198:201], v[40:43]
	v_mfma_f32_16x16x32_bf16 v[32:35], v[182:185], v[206:209], v[32:35]
	v_mfma_f32_16x16x32_bf16 v[24:27], v[190:193], v[206:209], v[24:27]
	v_mfma_f32_16x16x32_bf16 v[16:19], v[182:185], v[214:217], v[16:19]
	v_mfma_f32_16x16x32_bf16 v[8:11], v[190:193], v[214:217], v[8:11]
	v_mfma_f32_16x16x32_bf16 v[4:7], v[182:185], v[222:225], v[4:7]
	v_mfma_f32_16x16x32_bf16 v[0:3], v[190:193], v[222:225], v[0:3]
	s_setprio 1
	s_barrier
	s_add_i32 s71, s71, 2
	s_add_u32 s52, s52, 0x100
	s_addc_u32 s53, s53, 0
	s_add_u32 s69, s69, 0x100
	s_addc_u32 s70, s70, 0
	s_cmp_gt_u32 s71, 29
	s_cbranch_scc0 .LBB0_927
	s_and_b64 vcc, exec, s[18:19]
	s_cbranch_vccz .LBB0_930
	s_barrier

; #define PG8_STAGE(bufoff, gbase, voff) do { _Pragma("unroll") for (int _i = 0; _i < 2; ++_i) \
;         __builtin_amdgcn_global_load_lds((const unsigned*)((const char*)(gbase) + (voff)[_i]), (PG8_LAS unsigned*)(lds + (bufoff) + ldsw + _i * 8192), 16, 0, 0); } while (0)
; #define PG8_LDA(dst, b, h) do { _Pragma("unroll") for (int m = 0; m < 4; ++m) _Pragma("unroll") for (int k = 0; k < 2; ++k) dst[m][k] = *(const PG8_LAS bf16x8*)(lds + PG8_SA(b, h) + aoff + m * 2048 + k * 1024); } while (0)
; #define PG8_LDB(dst, b, h) do { _Pragma("unroll") for (int n = 0; n < 2; ++n) _Pragma("unroll") for (int k = 0; k < 2; ++k) dst[n][k] = *(const PG8_LAS bf16x8*)(lds + PG8_SB(b, h) + boff + n * 2048 + k * 1024); } while (0)
; #define PG8_MMA(ai, bj, At, Bt) do { __builtin_amdgcn_s_setprio(1); _Pragma("unroll") for (int m = 0; m < 4; ++m) _Pragma("unroll") for (int n = 0; n < 2; ++n) _Pragma("unroll") for (int k = 0; k < 2; ++k) \
;         acc[ai][bj][m][n] = __builtin_amdgcn_mfma_f32_16x16x32_bf16(Bt[n][k], At[m][k], acc[ai][bj][m][n], 0, 0, 0); __builtin_amdgcn_s_setprio(0); } while (0)
; #define PG8_WAIT_V(n) asm volatile("s_waitcnt vmcnt(" #n ")" ::: "memory")
; #define PG8_WAIT_L(n) asm volatile("s_waitcnt lgkmcnt(" #n ")" ::: "memory")
; template <class Epi, class Sched, bool ALIGN_EPI = false, bool SP2 = false>
; __device__ __forceinline__ void gemm_phase(PG8_LAS unsigned char* lds, const Gemm g, const Sched& S, const Epi& E) {
;     ...
;             const bool last = (t == nt - 2);
;             const char* a1 = cA + (size_t)(t + 1) * kstep;
;             const char* a2 = last ? nA : cA + (size_t)(t + 2) * kstep; const char* b2 = last ? nB : cB + (size_t)(t + 2) * kstep;
;             const char* a3 = a2 + kstep; const char* b3 = b2 + kstep;
;             if (last && has_next) S.a_ready(nxt);
;             if constexpr (SP2) {
;             PG8_LDB(B0, 0, 0); PG8_LDB(B1, 0, 1); PG8_SCHED; PG8_LDA(At, 0, 0); PG8_STAGE(PG8_SA(1, 1), a1 + hstepA, voffA);
;             PG8_WAIT_V(8); PG8_WAIT_L(0); PG8_BAR; PG8_MMA(0, 0, At, B0); PG8_MMA(0, 1, At, B1); PG8_BAR; PG8_SCHED;
;             PG8_LDA(At, 0, 1); PG8_STAGE(PG8_SB(0, 0), b2, voffB); PG8_STAGE(PG8_SB(0, 1), b2 + hstepB, voffB); PG8_STAGE(PG8_SA(0, 0), a2, voffA);
;             PG8_WAIT_V(8); PG8_WAIT_L(0); PG8_BAR; PG8_MMA(1, 0, At, B0); PG8_MMA(1, 1, At, B1); PG8_BAR; PG8_SCHED;
.LBB0_947:
	s_add_u32 s45, s50, s19
	s_addc_u32 s47, s51, 0
	s_add_u32 s49, s45, 0x100
	s_addc_u32 s60, s47, 0
	s_and_b64 s[58:59], s[56:57], exec
	s_cselect_b32 s61, s1, s60
	s_cselect_b32 s60, s0, s49
	s_add_u32 s19, s42, s19
	s_addc_u32 s49, s43, 0
	s_add_u32 s19, s19, 0x100
	s_addc_u32 s49, s49, 0
	s_and_b64 s[56:57], s[56:57], exec
	s_cselect_b32 s63, s53, s49
	s_cselect_b32 s62, s52, s19
	s_add_u32 s68, s45, 0x80080
	ds_read_b128 v[146:149], v143
	ds_read_b128 v[150:153], v143 offset:1024
	ds_read_b128 v[154:157], v143 offset:2048
	ds_read_b128 v[158:161], v143 offset:3072
	ds_read_b128 v[166:169], v144
	ds_read_b128 v[170:173], v144 offset:1024
	ds_read_b128 v[174:177], v144 offset:2048
	ds_read_b128 v[178:181], v144 offset:3072
	s_addc_u32 s69, s47, 0
	s_add_u32 s64, s62, 0x80000
	s_addc_u32 s65, s63, 0
	s_add_i32 s79, s71, s30
	s_add_i32 s78, s79, 0x2000
	s_add_i32 s77, 0, 0x18000
	s_add_i32 s76, 0, 0x1c000
	s_add_u32 s58, s60, 0x80000
	s_addc_u32 s59, s61, 0
	s_add_i32 s49, s77, s30
	s_add_i32 s45, s49, 0x2000
	s_add_u32 s56, s62, 0x80080
	s_addc_u32 s57, s63, 0
	s_add_i32 s47, s76, s30
	s_add_i32 s19, s47, 0x2000
	s_mov_b32 m0, s72
	ds_read_b128 v[182:185], v145
	ds_read_b128 v[186:189], v145 offset:1024
	ds_read_b128 v[190:193], v145 offset:2048
	ds_read_b128 v[194:197], v145 offset:3072
	ds_read_b128 v[198:201], v145 offset:4096
	ds_read_b128 v[202:205], v145 offset:5120
	ds_read_b128 v[206:209], v145 offset:6144
	ds_read_b128 v[210:213], v145 offset:7168
	global_load_lds_dwordx4 v128, s[68:69]
	s_mov_b32 m0, s73
	s_nop 0
	global_load_lds_dwordx4 v132, s[68:69]
	s_waitcnt vmcnt(8)
	s_waitcnt lgkmcnt(0)
	s_barrier
	s_setprio 0
	s_waitcnt lgkmcnt(0)
	v_mfma_f32_16x16x32_bf16 v[124:127], v[146:149], v[182:185], v[124:127]
	v_mfma_f32_16x16x32_bf16 v[120:123], v[154:157], v[182:185], v[120:123]
	v_mfma_f32_16x16x32_bf16 v[116:119], v[146:149], v[190:193], v[116:119]
	v_mfma_f32_16x16x32_bf16 v[112:115], v[154:157], v[190:193], v[112:115]
	v_mfma_f32_16x16x32_bf16 v[100:103], v[146:149], v[198:201], v[100:103]
	v_mfma_f32_16x16x32_bf16 v[96:99], v[154:157], v[198:201], v[96:99]
	v_mfma_f32_16x16x32_bf16 v[84:87], v[146:149], v[206:209], v[84:87]
	v_mfma_f32_16x16x32_bf16 v[80:83], v[154:157], v[206:209], v[80:83]
	v_mfma_f32_16x16x32_bf16 v[124:127], v[150:153], v[186:189], v[124:127]
	v_mfma_f32_16x16x32_bf16 v[120:123], v[158:161], v[186:189], v[120:123]
	v_mfma_f32_16x16x32_bf16 v[116:119], v[150:153], v[194:197], v[116:119]
	v_mfma_f32_16x16x32_bf16 v[112:115], v[158:161], v[194:197], v[112:115]
	v_mfma_f32_16x16x32_bf16 v[100:103], v[150:153], v[202:205], v[100:103]
	v_mfma_f32_16x16x32_bf16 v[96:99], v[158:161], v[202:205], v[96:99]
	v_mfma_f32_16x16x32_bf16 v[84:87], v[150:153], v[210:213], v[84:87]
	v_mfma_f32_16x16x32_bf16 v[80:83], v[158:161], v[210:213], v[80:83]
	v_mfma_f32_16x16x32_bf16 v[108:111], v[166:169], v[182:185], v[108:111]
	v_mfma_f32_16x16x32_bf16 v[104:107], v[174:177], v[182:185], v[104:107]
	v_mfma_f32_16x16x32_bf16 v[92:95], v[166:169], v[190:193], v[92:95]
	v_mfma_f32_16x16x32_bf16 v[88:91], v[174:177], v[190:193], v[88:91]
	v_mfma_f32_16x16x32_bf16 v[76:79], v[166:169], v[198:201], v[76:79]
	v_mfma_f32_16x16x32_bf16 v[72:75], v[174:177], v[198:201], v[72:75]
	v_mfma_f32_16x16x32_bf16 v[68:71], v[166:169], v[206:209], v[68:71]
	v_mfma_f32_16x16x32_bf16 v[64:67], v[174:177], v[206:209], v[64:67]
	v_mfma_f32_16x16x32_bf16 v[108:111], v[170:173], v[186:189], v[108:111]
	v_mfma_f32_16x16x32_bf16 v[104:107], v[178:181], v[186:189], v[104:107]
	v_mfma_f32_16x16x32_bf16 v[92:95], v[170:173], v[194:197], v[92:95]
	v_mfma_f32_16x16x32_bf16 v[88:91], v[178:181], v[194:197], v[88:91]
	v_mfma_f32_16x16x32_bf16 v[76:79], v[170:173], v[202:205], v[76:79]
	v_mfma_f32_16x16x32_bf16 v[72:75], v[178:181], v[202:205], v[72:75]
	v_mfma_f32_16x16x32_bf16 v[68:71], v[170:173], v[210:213], v[68:71]
	v_mfma_f32_16x16x32_bf16 v[64:67], v[178:181], v[210:213], v[64:67]
	s_setprio 1
	s_barrier
	s_mov_b32 m0, s74
	v_lshl_add_u64 v[214:215], s[62:63], 0, v[130:131]
	ds_read_b128 v[182:185], v145 offset:16384
	ds_read_b128 v[186:189], v145 offset:17408
	ds_read_b128 v[190:193], v145 offset:18432
	ds_read_b128 v[194:197], v145 offset:19456
	ds_read_b128 v[198:201], v145 offset:20480
	ds_read_b128 v[202:205], v145 offset:21504
	ds_read_b128 v[206:209], v145 offset:22528
	ds_read_b128 v[210:213], v145 offset:23552
	global_load_lds_dwordx4 v130, s[62:63]
	v_lshl_add_u64 v[216:217], s[62:63], 0, v[134:135]
	s_mov_b32 m0, s75
	s_nop 0
	global_load_lds_dwordx4 v134, s[62:63]
	s_mov_b32 m0, s79
	v_lshl_add_u64 v[220:221], s[60:61], 0, v[132:133]
	global_load_lds_dwordx4 v130, s[64:65]
	s_mov_b32 m0, s78
	s_nop 0
	global_load_lds_dwordx4 v134, s[64:65]
	v_lshl_add_u64 v[218:219], s[60:61], 0, v[128:129]
	s_mov_b32 m0, s21
	s_nop 0
	global_load_lds_dwordx4 v128, s[60:61]
	s_mov_b32 m0, s23
	s_nop 0
	global_load_lds_dwordx4 v132, s[60:61]
	s_waitcnt vmcnt(8)
	s_waitcnt lgkmcnt(0)
	s_barrier
; #define PG8_STAGE(bufoff, gbase, voff) do { _Pragma("unroll") for (int _i = 0; _i < 2; ++_i) \
;         __builtin_amdgcn_global_load_lds((const unsigned*)((const char*)(gbase) + (voff)[_i]), (PG8_LAS unsigned*)(lds + (bufoff) + ldsw + _i * 8192), 16, 0, 0); } while (0)
; #define PG8_LDA(dst, b, h) do { _Pragma("unroll") for (int m = 0; m < 4; ++m) _Pragma("unroll") for (int k = 0; k < 2; ++k) dst[m][k] = *(const PG8_LAS bf16x8*)(lds + PG8_SA(b, h) + aoff + m * 2048 + k * 1024); } while (0)
; #define PG8_LDB(dst, b, h) do { _Pragma("unroll") for (int n = 0; n < 2; ++n) _Pragma("unroll") for (int k = 0; k < 2; ++k) dst[n][k] = *(const PG8_LAS bf16x8*)(lds + PG8_SB(b, h) + boff + n * 2048 + k * 1024); } while (0)
; #define PG8_MMA(ai, bj, At, Bt) do { __builtin_amdgcn_s_setprio(1); _Pragma("unroll") for (int m = 0; m < 4; ++m) _Pragma("unroll") for (int n = 0; n < 2; ++n) _Pragma("unroll") for (int k = 0; k < 2; ++k) \
;         acc[ai][bj][m][n] = __builtin_amdgcn_mfma_f32_16x16x32_bf16(Bt[n][k], At[m][k], acc[ai][bj][m][n], 0, 0, 0); __builtin_amdgcn_s_setprio(0); } while (0)
; #define PG8_WAIT_V(n) asm volatile("s_waitcnt vmcnt(" #n ")" ::: "memory")
; #define PG8_WAIT_L(n) asm volatile("s_waitcnt lgkmcnt(" #n ")" ::: "memory")
; #define PG8_BAR __builtin_amdgcn_s_barrier()
; #define PG8_SCHED __builtin_amdgcn_sched_barrier(0)
; template <class Epi, class Sched, bool ALIGN_EPI = false, bool SP2 = false>
; __device__ __forceinline__ void gemm_phase(PG8_LAS unsigned char* lds, const Gemm g, const Sched& S, const Epi& E) {
;     ...
;             PG8_WAIT_V(8); PG8_WAIT_L(0); PG8_BAR; PG8_MMA(1, 0, At, B0); PG8_MMA(1, 1, At, B1); PG8_BAR; PG8_SCHED;
;             PG8_LDB(B0, 1, 0); PG8_LDB(B1, 1, 1); PG8_SCHED; PG8_LDA(At, 1, 0); PG8_STAGE(PG8_SA(0, 1), a2 + hstepA, voffA);
;             PG8_WAIT_V(8); PG8_WAIT_L(0); PG8_BAR; PG8_MMA(0, 0, At, B0); PG8_MMA(0, 1, At, B1); PG8_BAR; PG8_SCHED;
	s_setprio 0
	s_waitcnt lgkmcnt(0)
	v_mfma_f32_16x16x32_bf16 v[60:63], v[146:149], v[182:185], v[60:63]
	v_mfma_f32_16x16x32_bf16 v[56:59], v[154:157], v[182:185], v[56:59]
	v_mfma_f32_16x16x32_bf16 v[52:55], v[146:149], v[190:193], v[52:55]
	v_mfma_f32_16x16x32_bf16 v[48:51], v[154:157], v[190:193], v[48:51]
	v_mfma_f32_16x16x32_bf16 v[36:39], v[146:149], v[198:201], v[36:39]
	v_mfma_f32_16x16x32_bf16 v[32:35], v[154:157], v[198:201], v[32:35]
	v_mfma_f32_16x16x32_bf16 v[20:23], v[146:149], v[206:209], v[20:23]
	v_mfma_f32_16x16x32_bf16 v[16:19], v[154:157], v[206:209], v[16:19]
	v_mfma_f32_16x16x32_bf16 v[60:63], v[150:153], v[186:189], v[60:63]
	v_mfma_f32_16x16x32_bf16 v[56:59], v[158:161], v[186:189], v[56:59]
	v_mfma_f32_16x16x32_bf16 v[52:55], v[150:153], v[194:197], v[52:55]
	v_mfma_f32_16x16x32_bf16 v[48:51], v[158:161], v[194:197], v[48:51]
	v_mfma_f32_16x16x32_bf16 v[36:39], v[150:153], v[202:205], v[36:39]
	v_mfma_f32_16x16x32_bf16 v[32:35], v[158:161], v[202:205], v[32:35]
	v_mfma_f32_16x16x32_bf16 v[20:23], v[150:153], v[210:213], v[20:23]
	v_mfma_f32_16x16x32_bf16 v[16:19], v[158:161], v[210:213], v[16:19]
	v_mfma_f32_16x16x32_bf16 v[44:47], v[166:169], v[182:185], v[44:47]
	v_mfma_f32_16x16x32_bf16 v[40:43], v[174:177], v[182:185], v[40:43]
	v_mfma_f32_16x16x32_bf16 v[28:31], v[166:169], v[190:193], v[28:31]
	v_mfma_f32_16x16x32_bf16 v[24:27], v[174:177], v[190:193], v[24:27]
	v_mfma_f32_16x16x32_bf16 v[12:15], v[166:169], v[198:201], v[12:15]
	v_mfma_f32_16x16x32_bf16 v[8:11], v[174:177], v[198:201], v[8:11]
	v_mfma_f32_16x16x32_bf16 v[4:7], v[166:169], v[206:209], v[4:7]
	v_mfma_f32_16x16x32_bf16 v[0:3], v[174:177], v[206:209], v[0:3]
	v_mfma_f32_16x16x32_bf16 v[44:47], v[170:173], v[186:189], v[44:47]
	v_mfma_f32_16x16x32_bf16 v[40:43], v[178:181], v[186:189], v[40:43]
	v_mfma_f32_16x16x32_bf16 v[28:31], v[170:173], v[194:197], v[28:31]
	v_mfma_f32_16x16x32_bf16 v[24:27], v[178:181], v[194:197], v[24:27]
	v_mfma_f32_16x16x32_bf16 v[12:15], v[170:173], v[202:205], v[12:15]
	v_mfma_f32_16x16x32_bf16 v[8:11], v[178:181], v[202:205], v[8:11]
	v_mfma_f32_16x16x32_bf16 v[4:7], v[170:173], v[210:213], v[4:7]
	v_mfma_f32_16x16x32_bf16 v[0:3], v[178:181], v[210:213], v[0:3]
	s_setprio 1
	s_barrier
	v_add_u32_e32 v158, s77, v141
	v_add_u32_e32 v163, s76, v141
	ds_read_b128 v[146:149], v158
	ds_read_b128 v[150:153], v158 offset:1024
	ds_read_b128 v[154:157], v158 offset:2048
	ds_read_b128 v[158:161], v158 offset:3072
	ds_read_b128 v[166:169], v163
	ds_read_b128 v[170:173], v163 offset:1024
	ds_read_b128 v[174:177], v163 offset:2048
	ds_read_b128 v[178:181], v163 offset:3072
	s_mov_b32 m0, s31
	ds_read_b128 v[182:185], v145 offset:32768
	ds_read_b128 v[186:189], v145 offset:33792
	ds_read_b128 v[190:193], v145 offset:34816
	ds_read_b128 v[194:197], v145 offset:35840
	ds_read_b128 v[198:201], v145 offset:36864
	ds_read_b128 v[202:205], v145 offset:37888
	ds_read_b128 v[206:209], v145 offset:38912
	ds_read_b128 v[210:213], v145 offset:39936
	global_load_lds_dwordx4 v128, s[58:59]
	s_mov_b32 m0, s33
	s_nop 0
	global_load_lds_dwordx4 v132, s[58:59]
	s_waitcnt vmcnt(8)
	s_waitcnt lgkmcnt(0)
	s_barrier
	s_setprio 0
	s_waitcnt lgkmcnt(0)
	v_mfma_f32_16x16x32_bf16 v[124:127], v[146:149], v[182:185], v[124:127]
	v_mfma_f32_16x16x32_bf16 v[120:123], v[154:157], v[182:185], v[120:123]
	v_mfma_f32_16x16x32_bf16 v[116:119], v[146:149], v[190:193], v[116:119]
	v_mfma_f32_16x16x32_bf16 v[112:115], v[154:157], v[190:193], v[112:115]
	v_mfma_f32_16x16x32_bf16 v[100:103], v[146:149], v[198:201], v[100:103]
	v_mfma_f32_16x16x32_bf16 v[96:99], v[154:157], v[198:201], v[96:99]
	v_mfma_f32_16x16x32_bf16 v[84:87], v[146:149], v[206:209], v[84:87]
	v_mfma_f32_16x16x32_bf16 v[80:83], v[154:157], v[206:209], v[80:83]
	v_mfma_f32_16x16x32_bf16 v[124:127], v[150:153], v[186:189], v[124:127]
	v_mfma_f32_16x16x32_bf16 v[120:123], v[158:161], v[186:189], v[120:123]
	v_mfma_f32_16x16x32_bf16 v[116:119], v[150:153], v[194:197], v[116:119]
	v_mfma_f32_16x16x32_bf16 v[112:115], v[158:161], v[194:197], v[112:115]
	v_mfma_f32_16x16x32_bf16 v[100:103], v[150:153], v[202:205], v[100:103]
	v_mfma_f32_16x16x32_bf16 v[96:99], v[158:161], v[202:205], v[96:99]
	v_mfma_f32_16x16x32_bf16 v[84:87], v[150:153], v[210:213], v[84:87]
	v_mfma_f32_16x16x32_bf16 v[80:83], v[158:161], v[210:213], v[80:83]
	v_mfma_f32_16x16x32_bf16 v[108:111], v[166:169], v[182:185], v[108:111]
	v_mfma_f32_16x16x32_bf16 v[104:107], v[174:177], v[182:185], v[104:107]
	v_mfma_f32_16x16x32_bf16 v[92:95], v[166:169], v[190:193], v[92:95]
	v_mfma_f32_16x16x32_bf16 v[88:91], v[174:177], v[190:193], v[88:91]
	v_mfma_f32_16x16x32_bf16 v[76:79], v[166:169], v[198:201], v[76:79]
	v_mfma_f32_16x16x32_bf16 v[72:75], v[174:177], v[198:201], v[72:75]
	v_mfma_f32_16x16x32_bf16 v[68:71], v[166:169], v[206:209], v[68:71]
	v_mfma_f32_16x16x32_bf16 v[64:67], v[174:177], v[206:209], v[64:67]
	v_mfma_f32_16x16x32_bf16 v[108:111], v[170:173], v[186:189], v[108:111]
	v_mfma_f32_16x16x32_bf16 v[104:107], v[178:181], v[186:189], v[104:107]
	v_mfma_f32_16x16x32_bf16 v[92:95], v[170:173], v[194:197], v[92:95]
	v_mfma_f32_16x16x32_bf16 v[88:91], v[178:181], v[194:197], v[88:91]
	v_mfma_f32_16x16x32_bf16 v[76:79], v[170:173], v[202:205], v[76:79]
	v_mfma_f32_16x16x32_bf16 v[72:75], v[178:181], v[202:205], v[72:75]
	v_mfma_f32_16x16x32_bf16 v[68:71], v[170:173], v[210:213], v[68:71]
	v_mfma_f32_16x16x32_bf16 v[64:67], v[178:181], v[210:213], v[64:67]
	s_setprio 1
	s_barrier
; #define PG8_STAGE(bufoff, gbase, voff) do { _Pragma("unroll") for (int _i = 0; _i < 2; ++_i) \
;         __builtin_amdgcn_global_load_lds((const unsigned*)((const char*)(gbase) + (voff)[_i]), (PG8_LAS unsigned*)(lds + (bufoff) + ldsw + _i * 8192), 16, 0, 0); } while (0)
; #define PG8_LDA(dst, b, h) do { _Pragma("unroll") for (int m = 0; m < 4; ++m) _Pragma("unroll") for (int k = 0; k < 2; ++k) dst[m][k] = *(const PG8_LAS bf16x8*)(lds + PG8_SA(b, h) + aoff + m * 2048 + k * 1024); } while (0)
; #define PG8_MMA(ai, bj, At, Bt) do { __builtin_amdgcn_s_setprio(1); _Pragma("unroll") for (int m = 0; m < 4; ++m) _Pragma("unroll") for (int n = 0; n < 2; ++n) _Pragma("unroll") for (int k = 0; k < 2; ++k) \
;         acc[ai][bj][m][n] = __builtin_amdgcn_mfma_f32_16x16x32_bf16(Bt[n][k], At[m][k], acc[ai][bj][m][n], 0, 0, 0); __builtin_amdgcn_s_setprio(0); } while (0)
; #define PG8_WAIT_V(n) asm volatile("s_waitcnt vmcnt(" #n ")" ::: "memory")
; #define PG8_WAIT_L(n) asm volatile("s_waitcnt lgkmcnt(" #n ")" ::: "memory")
; #define PG8_BAR __builtin_amdgcn_s_barrier()
; #define PG8_SCHED __builtin_amdgcn_sched_barrier(0)
; template <class Epi, class Sched, bool ALIGN_EPI = false, bool SP2 = false>
; __device__ __forceinline__ void gemm_phase(PG8_LAS unsigned char* lds, const Gemm g, const Sched& S, const Epi& E) {
;     ...
;             PG8_LDA(At, 1, 1); PG8_STAGE(PG8_SB(1, 0), b3, voffB); PG8_STAGE(PG8_SB(1, 1), b3 + hstepB, voffB); PG8_STAGE(PG8_SA(1, 0), a3, voffA);
;             PG8_WAIT_V(8); PG8_WAIT_L(0); PG8_BAR; PG8_MMA(1, 0, At, B0); PG8_MMA(1, 1, At, B1); PG8_BAR; PG8_SCHED;
	s_mov_b32 m0, s49
	v_lshl_add_u64 v[214:215], v[214:215], 0, s[16:17]
	ds_read_b128 v[182:185], v145 offset:49152
	ds_read_b128 v[186:189], v145 offset:50176
	ds_read_b128 v[190:193], v145 offset:51200
	ds_read_b128 v[194:197], v145 offset:52224
	ds_read_b128 v[198:201], v145 offset:53248
	ds_read_b128 v[202:205], v145 offset:54272
	ds_read_b128 v[206:209], v145 offset:55296
	ds_read_b128 v[210:213], v145 offset:56320
	global_load_lds_dwordx4 v[214:215], off
	v_lshl_add_u64 v[214:215], v[216:217], 0, s[16:17]
	s_mov_b32 m0, s45
	s_nop 0
	global_load_lds_dwordx4 v[214:215], off
	s_mov_b32 m0, s47
	s_nop 0
	global_load_lds_dwordx4 v130, s[56:57]
	s_mov_b32 m0, s19
	s_nop 0
	global_load_lds_dwordx4 v134, s[56:57]
	v_lshl_add_u64 v[214:215], v[218:219], 0, s[16:17]
	s_mov_b32 m0, s35
	s_nop 0
	global_load_lds_dwordx4 v[214:215], off
	v_lshl_add_u64 v[214:215], v[220:221], 0, s[16:17]
	s_mov_b32 m0, s70
	s_nop 0
	global_load_lds_dwordx4 v[214:215], off
	s_waitcnt vmcnt(8)
	s_waitcnt lgkmcnt(0)
	s_barrier
	s_setprio 0
	s_waitcnt lgkmcnt(0)
	v_mfma_f32_16x16x32_bf16 v[60:63], v[146:149], v[182:185], v[60:63]
	v_mfma_f32_16x16x32_bf16 v[56:59], v[154:157], v[182:185], v[56:59]
	v_mfma_f32_16x16x32_bf16 v[52:55], v[146:149], v[190:193], v[52:55]
	v_mfma_f32_16x16x32_bf16 v[48:51], v[154:157], v[190:193], v[48:51]
	v_mfma_f32_16x16x32_bf16 v[36:39], v[146:149], v[198:201], v[36:39]
	v_mfma_f32_16x16x32_bf16 v[32:35], v[154:157], v[198:201], v[32:35]
	v_mfma_f32_16x16x32_bf16 v[20:23], v[146:149], v[206:209], v[20:23]
	v_mfma_f32_16x16x32_bf16 v[16:19], v[154:157], v[206:209], v[16:19]
	v_mfma_f32_16x16x32_bf16 v[60:63], v[150:153], v[186:189], v[60:63]
	v_mfma_f32_16x16x32_bf16 v[56:59], v[158:161], v[186:189], v[56:59]
	v_mfma_f32_16x16x32_bf16 v[52:55], v[150:153], v[194:197], v[52:55]
	v_mfma_f32_16x16x32_bf16 v[48:51], v[158:161], v[194:197], v[48:51]
	v_mfma_f32_16x16x32_bf16 v[36:39], v[150:153], v[202:205], v[36:39]
	v_mfma_f32_16x16x32_bf16 v[32:35], v[158:161], v[202:205], v[32:35]
	v_mfma_f32_16x16x32_bf16 v[20:23], v[150:153], v[210:213], v[20:23]
	v_mfma_f32_16x16x32_bf16 v[16:19], v[158:161], v[210:213], v[16:19]
	v_mfma_f32_16x16x32_bf16 v[44:47], v[166:169], v[182:185], v[44:47]
	v_mfma_f32_16x16x32_bf16 v[40:43], v[174:177], v[182:185], v[40:43]
	v_mfma_f32_16x16x32_bf16 v[28:31], v[166:169], v[190:193], v[28:31]
	v_mfma_f32_16x16x32_bf16 v[24:27], v[174:177], v[190:193], v[24:27]
	v_mfma_f32_16x16x32_bf16 v[12:15], v[166:169], v[198:201], v[12:15]
	v_mfma_f32_16x16x32_bf16 v[8:11], v[174:177], v[198:201], v[8:11]
	v_mfma_f32_16x16x32_bf16 v[4:7], v[166:169], v[206:209], v[4:7]
	v_mfma_f32_16x16x32_bf16 v[0:3], v[174:177], v[206:209], v[0:3]
	v_mfma_f32_16x16x32_bf16 v[44:47], v[170:173], v[186:189], v[44:47]
	v_mfma_f32_16x16x32_bf16 v[40:43], v[178:181], v[186:189], v[40:43]
	v_mfma_f32_16x16x32_bf16 v[28:31], v[170:173], v[194:197], v[28:31]
	v_mfma_f32_16x16x32_bf16 v[24:27], v[178:181], v[194:197], v[24:27]
	v_mfma_f32_16x16x32_bf16 v[12:15], v[170:173], v[202:205], v[12:15]
	v_mfma_f32_16x16x32_bf16 v[8:11], v[178:181], v[202:205], v[8:11]
	v_mfma_f32_16x16x32_bf16 v[4:7], v[170:173], v[210:213], v[4:7]
	v_mfma_f32_16x16x32_bf16 v[0:3], v[178:181], v[210:213], v[0:3]
	s_setprio 1
	s_barrier
	s_movk_i32 s19, 0x100
	s_andn2_b64 vcc, exec, s[54:55]
	s_mov_b64 s[56:57], -1
	s_mov_b64 s[54:55], 0
	s_cbranch_vccz .LBB0_947
	s_and_b64 vcc, exec, s[40:41]
	s_cbranch_vccz .LBB0_950
	s_barrier

; #define PG8_STAGE(bufoff, gbase, voff) do { _Pragma("unroll") for (int _i = 0; _i < 2; ++_i) \
;         __builtin_amdgcn_global_load_lds((const unsigned*)((const char*)(gbase) + (voff)[_i]), (PG8_LAS unsigned*)(lds + (bufoff) + ldsw + _i * 8192), 16, 0, 0); } while (0)
; #define PG8_LDA(dst, b, h) do { _Pragma("unroll") for (int m = 0; m < 4; ++m) _Pragma("unroll") for (int k = 0; k < 2; ++k) dst[m][k] = *(const PG8_LAS bf16x8*)(lds + PG8_SA(b, h) + aoff + m * 2048 + k * 1024); } while (0)
; #define PG8_LDB(dst, b, h) do { _Pragma("unroll") for (int n = 0; n < 2; ++n) _Pragma("unroll") for (int k = 0; k < 2; ++k) dst[n][k] = *(const PG8_LAS bf16x8*)(lds + PG8_SB(b, h) + boff + n * 2048 + k * 1024); } while (0)
; #define PG8_MMA(ai, bj, At, Bt) do { __builtin_amdgcn_s_setprio(1); _Pragma("unroll") for (int m = 0; m < 4; ++m) _Pragma("unroll") for (int n = 0; n < 2; ++n) _Pragma("unroll") for (int k = 0; k < 2; ++k) \
;         acc[ai][bj][m][n] = __builtin_amdgcn_mfma_f32_16x16x32_bf16(Bt[n][k], At[m][k], acc[ai][bj][m][n], 0, 0, 0); __builtin_amdgcn_s_setprio(0); } while (0)
; #define PG8_WAIT_V(n) asm volatile("s_waitcnt vmcnt(" #n ")" ::: "memory")
; #define PG8_WAIT_L(n) asm volatile("s_waitcnt lgkmcnt(" #n ")" ::: "memory")
; template <class Epi, class Sched, bool ALIGN_EPI = false, bool SP2 = false>
; __device__ __forceinline__ void gemm_phase(PG8_LAS unsigned char* lds, const Gemm g, const Sched& S, const Epi& E) {
;     ...
;             const bool last = (t == nt - 2);
;             const char* a1 = cA + (size_t)(t + 1) * kstep;
;             const char* a2 = last ? nA : cA + (size_t)(t + 2) * kstep; const char* b2 = last ? nB : cB + (size_t)(t + 2) * kstep;
;             const char* a3 = a2 + kstep; const char* b3 = b2 + kstep;
;             if (last && has_next) S.a_ready(nxt);
;             if constexpr (SP2) {
;             PG8_LDB(B0, 0, 0); PG8_LDB(B1, 0, 1); PG8_SCHED; PG8_LDA(At, 0, 0); PG8_STAGE(PG8_SA(1, 1), a1 + hstepA, voffA);
;             PG8_WAIT_V(8); PG8_WAIT_L(0); PG8_BAR; PG8_MMA(0, 0, At, B0); PG8_MMA(0, 1, At, B1); PG8_BAR; PG8_SCHED;
;             PG8_LDA(At, 0, 1); PG8_STAGE(PG8_SB(0, 0), b2, voffB); PG8_STAGE(PG8_SB(0, 1), b2 + hstepB, voffB); PG8_STAGE(PG8_SA(0, 0), a2, voffA);
;             PG8_WAIT_V(8); PG8_WAIT_L(0); PG8_BAR; PG8_MMA(1, 0, At, B0); PG8_MMA(1, 1, At, B1); PG8_BAR; PG8_SCHED;
.LBB0_1082:
	ds_read_b128 v[150:153], v147
	ds_read_b128 v[154:157], v147 offset:1024
	ds_read_b128 v[158:161], v147 offset:2048
	ds_read_b128 v[166:169], v147 offset:3072
	ds_read_b128 v[170:173], v148
	ds_read_b128 v[174:177], v148 offset:1024
	ds_read_b128 v[178:181], v148 offset:2048
	ds_read_b128 v[182:185], v148 offset:3072
	s_add_u32 s50, s48, 0xfff80080
	s_addc_u32 s51, s49, -1
	s_cmp_eq_u32 s66, 28
	s_cselect_b32 s53, s41, s51
	s_cselect_b32 s52, s62, s50
	s_cselect_b32 s51, s39, s65
	s_cselect_b32 s50, s63, s64
	s_add_i32 m0, s30, 0xc000
	ds_read_b128 v[186:189], v149
	ds_read_b128 v[190:193], v149 offset:1024
	ds_read_b128 v[194:197], v149 offset:2048
	ds_read_b128 v[198:201], v149 offset:3072
	ds_read_b128 v[202:205], v149 offset:4096
	ds_read_b128 v[206:209], v149 offset:5120
	ds_read_b128 v[210:213], v149 offset:6144
	ds_read_b128 v[214:217], v149 offset:7168
	global_load_lds_dwordx4 v136, s[48:49]
	s_add_i32 m0, s30, 0xe000
	s_nop 0
	global_load_lds_dwordx4 v138, s[48:49]
	s_waitcnt vmcnt(8)
	s_waitcnt lgkmcnt(0)
	s_barrier
	s_setprio 0
	s_waitcnt lgkmcnt(0)
	v_mfma_f32_16x16x32_bf16 v[124:127], v[150:153], v[186:189], v[124:127]
	v_mfma_f32_16x16x32_bf16 v[120:123], v[158:161], v[186:189], v[120:123]
	v_mfma_f32_16x16x32_bf16 v[112:115], v[150:153], v[194:197], v[112:115]
	v_mfma_f32_16x16x32_bf16 v[104:107], v[158:161], v[194:197], v[104:107]
	v_mfma_f32_16x16x32_bf16 v[96:99], v[150:153], v[202:205], v[96:99]
	v_mfma_f32_16x16x32_bf16 v[88:91], v[158:161], v[202:205], v[88:91]
	v_mfma_f32_16x16x32_bf16 v[80:83], v[150:153], v[210:213], v[80:83]
	v_mfma_f32_16x16x32_bf16 v[72:75], v[158:161], v[210:213], v[72:75]
	v_mfma_f32_16x16x32_bf16 v[124:127], v[154:157], v[190:193], v[124:127]
	v_mfma_f32_16x16x32_bf16 v[120:123], v[166:169], v[190:193], v[120:123]
	v_mfma_f32_16x16x32_bf16 v[112:115], v[154:157], v[198:201], v[112:115]
	v_mfma_f32_16x16x32_bf16 v[104:107], v[166:169], v[198:201], v[104:107]
	v_mfma_f32_16x16x32_bf16 v[96:99], v[154:157], v[206:209], v[96:99]
	v_mfma_f32_16x16x32_bf16 v[88:91], v[166:169], v[206:209], v[88:91]
	v_mfma_f32_16x16x32_bf16 v[80:83], v[154:157], v[214:217], v[80:83]
	v_mfma_f32_16x16x32_bf16 v[72:75], v[166:169], v[214:217], v[72:75]
	v_mfma_f32_16x16x32_bf16 v[116:119], v[170:173], v[186:189], v[116:119]
	v_mfma_f32_16x16x32_bf16 v[108:111], v[178:181], v[186:189], v[108:111]
	v_mfma_f32_16x16x32_bf16 v[100:103], v[170:173], v[194:197], v[100:103]
	v_mfma_f32_16x16x32_bf16 v[92:95], v[178:181], v[194:197], v[92:95]
	v_mfma_f32_16x16x32_bf16 v[84:87], v[170:173], v[202:205], v[84:87]
	v_mfma_f32_16x16x32_bf16 v[76:79], v[178:181], v[202:205], v[76:79]
	v_mfma_f32_16x16x32_bf16 v[68:71], v[170:173], v[210:213], v[68:71]
	v_mfma_f32_16x16x32_bf16 v[64:67], v[178:181], v[210:213], v[64:67]
	v_mfma_f32_16x16x32_bf16 v[116:119], v[174:177], v[190:193], v[116:119]
	v_mfma_f32_16x16x32_bf16 v[108:111], v[182:185], v[190:193], v[108:111]
	v_mfma_f32_16x16x32_bf16 v[100:103], v[174:177], v[198:201], v[100:103]
	v_mfma_f32_16x16x32_bf16 v[92:95], v[182:185], v[198:201], v[92:95]
	v_mfma_f32_16x16x32_bf16 v[84:87], v[174:177], v[206:209], v[84:87]
	v_mfma_f32_16x16x32_bf16 v[76:79], v[182:185], v[206:209], v[76:79]
	v_mfma_f32_16x16x32_bf16 v[68:71], v[174:177], v[214:217], v[68:71]
	v_mfma_f32_16x16x32_bf16 v[64:67], v[182:185], v[214:217], v[64:67]
	s_setprio 1
	s_barrier
	s_add_i32 s67, s55, s28
	v_lshl_add_u64 v[218:219], s[50:51], 0, v[132:133]
	s_mov_b32 m0, s67
	ds_read_b128 v[186:189], v149 offset:16384
	ds_read_b128 v[190:193], v149 offset:17408
	ds_read_b128 v[194:197], v149 offset:18432
	ds_read_b128 v[198:201], v149 offset:19456
	ds_read_b128 v[202:205], v149 offset:20480
	ds_read_b128 v[206:209], v149 offset:21504
	ds_read_b128 v[210:213], v149 offset:22528
	ds_read_b128 v[214:217], v149 offset:23552
	global_load_lds_dwordx4 v132, s[50:51]
	s_add_i32 m0, s67, 0x2000
	s_add_u32 s68, s50, 0x80000
	v_lshl_add_u64 v[220:221], s[50:51], 0, v[128:129]
	s_addc_u32 s69, s51, 0
	s_add_i32 s67, s56, s28
	global_load_lds_dwordx4 v128, s[50:51]
	s_mov_b32 m0, s67
	v_lshl_add_u64 v[224:225], s[52:53], 0, v[130:131]
	global_load_lds_dwordx4 v132, s[68:69]
	s_add_i32 m0, s67, 0x2000
	s_nop 0
	global_load_lds_dwordx4 v128, s[68:69]
	v_lshl_add_u64 v[222:223], s[52:53], 0, v[134:135]
	s_mov_b32 m0, s30
	s_nop 0
	global_load_lds_dwordx4 v134, s[52:53]
	s_mov_b32 m0, s31
	s_nop 0
	global_load_lds_dwordx4 v130, s[52:53]
	s_waitcnt vmcnt(8)
	s_waitcnt lgkmcnt(0)
	s_barrier
	s_setprio 0
	s_waitcnt lgkmcnt(0)
	v_mfma_f32_16x16x32_bf16 v[60:63], v[150:153], v[186:189], v[60:63]
	v_mfma_f32_16x16x32_bf16 v[56:59], v[158:161], v[186:189], v[56:59]
	v_mfma_f32_16x16x32_bf16 v[48:51], v[150:153], v[194:197], v[48:51]
	v_mfma_f32_16x16x32_bf16 v[40:43], v[158:161], v[194:197], v[40:43]
	v_mfma_f32_16x16x32_bf16 v[32:35], v[150:153], v[202:205], v[32:35]
	v_mfma_f32_16x16x32_bf16 v[24:27], v[158:161], v[202:205], v[24:27]
	v_mfma_f32_16x16x32_bf16 v[16:19], v[150:153], v[210:213], v[16:19]
	v_mfma_f32_16x16x32_bf16 v[8:11], v[158:161], v[210:213], v[8:11]
	v_mfma_f32_16x16x32_bf16 v[60:63], v[154:157], v[190:193], v[60:63]
	v_mfma_f32_16x16x32_bf16 v[56:59], v[166:169], v[190:193], v[56:59]
	v_mfma_f32_16x16x32_bf16 v[48:51], v[154:157], v[198:201], v[48:51]
	v_mfma_f32_16x16x32_bf16 v[40:43], v[166:169], v[198:201], v[40:43]
	v_mfma_f32_16x16x32_bf16 v[32:35], v[154:157], v[206:209], v[32:35]
	v_mfma_f32_16x16x32_bf16 v[24:27], v[166:169], v[206:209], v[24:27]
	v_mfma_f32_16x16x32_bf16 v[16:19], v[154:157], v[214:217], v[16:19]
	v_mfma_f32_16x16x32_bf16 v[8:11], v[166:169], v[214:217], v[8:11]
	v_mfma_f32_16x16x32_bf16 v[52:55], v[170:173], v[186:189], v[52:55]
	v_mfma_f32_16x16x32_bf16 v[44:47], v[178:181], v[186:189], v[44:47]
	v_mfma_f32_16x16x32_bf16 v[36:39], v[170:173], v[194:197], v[36:39]
	v_mfma_f32_16x16x32_bf16 v[28:31], v[178:181], v[194:197], v[28:31]
	v_mfma_f32_16x16x32_bf16 v[20:23], v[170:173], v[202:205], v[20:23]
	v_mfma_f32_16x16x32_bf16 v[12:15], v[178:181], v[202:205], v[12:15]
	v_mfma_f32_16x16x32_bf16 v[4:7], v[170:173], v[210:213], v[4:7]
	v_mfma_f32_16x16x32_bf16 v[0:3], v[178:181], v[210:213], v[0:3]
	v_mfma_f32_16x16x32_bf16 v[52:55], v[174:177], v[190:193], v[52:55]
	v_mfma_f32_16x16x32_bf16 v[44:47], v[182:185], v[190:193], v[44:47]
	v_mfma_f32_16x16x32_bf16 v[36:39], v[174:177], v[198:201], v[36:39]
	v_mfma_f32_16x16x32_bf16 v[28:31], v[182:185], v[198:201], v[28:31]
	v_mfma_f32_16x16x32_bf16 v[20:23], v[174:177], v[206:209], v[20:23]
	v_mfma_f32_16x16x32_bf16 v[12:15], v[182:185], v[206:209], v[12:15]
	v_mfma_f32_16x16x32_bf16 v[4:7], v[174:177], v[214:217], v[4:7]
	v_mfma_f32_16x16x32_bf16 v[0:3], v[182:185], v[214:217], v[0:3]
	s_setprio 1
	s_barrier
; #define PG8_STAGE(bufoff, gbase, voff) do { _Pragma("unroll") for (int _i = 0; _i < 2; ++_i) \
;         __builtin_amdgcn_global_load_lds((const unsigned*)((const char*)(gbase) + (voff)[_i]), (PG8_LAS unsigned*)(lds + (bufoff) + ldsw + _i * 8192), 16, 0, 0); } while (0)
; #define PG8_LDA(dst, b, h) do { _Pragma("unroll") for (int m = 0; m < 4; ++m) _Pragma("unroll") for (int k = 0; k < 2; ++k) dst[m][k] = *(const PG8_LAS bf16x8*)(lds + PG8_SA(b, h) + aoff + m * 2048 + k * 1024); } while (0)
; #define PG8_LDB(dst, b, h) do { _Pragma("unroll") for (int n = 0; n < 2; ++n) _Pragma("unroll") for (int k = 0; k < 2; ++k) dst[n][k] = *(const PG8_LAS bf16x8*)(lds + PG8_SB(b, h) + boff + n * 2048 + k * 1024); } while (0)
; #define PG8_MMA(ai, bj, At, Bt) do { __builtin_amdgcn_s_setprio(1); _Pragma("unroll") for (int m = 0; m < 4; ++m) _Pragma("unroll") for (int n = 0; n < 2; ++n) _Pragma("unroll") for (int k = 0; k < 2; ++k) \
;         acc[ai][bj][m][n] = __builtin_amdgcn_mfma_f32_16x16x32_bf16(Bt[n][k], At[m][k], acc[ai][bj][m][n], 0, 0, 0); __builtin_amdgcn_s_setprio(0); } while (0)
; #define PG8_WAIT_V(n) asm volatile("s_waitcnt vmcnt(" #n ")" ::: "memory")
; #define PG8_WAIT_L(n) asm volatile("s_waitcnt lgkmcnt(" #n ")" ::: "memory")
; #define PG8_BAR __builtin_amdgcn_s_barrier()
; #define PG8_SCHED __builtin_amdgcn_sched_barrier(0)
; template <class Epi, class Sched, bool ALIGN_EPI = false, bool SP2 = false>
; __device__ __forceinline__ void gemm_phase(PG8_LAS unsigned char* lds, const Gemm g, const Sched& S, const Epi& E) {
;     ...
;             PG8_LDB(B0, 1, 0); PG8_LDB(B1, 1, 1); PG8_SCHED; PG8_LDA(At, 1, 0); PG8_STAGE(PG8_SA(0, 1), a2 + hstepA, voffA);
;             PG8_WAIT_V(8); PG8_WAIT_L(0); PG8_BAR; PG8_MMA(0, 0, At, B0); PG8_MMA(0, 1, At, B1); PG8_BAR; PG8_SCHED;
;             PG8_LDA(At, 1, 1); PG8_STAGE(PG8_SB(1, 0), b3, voffB); PG8_STAGE(PG8_SB(1, 1), b3 + hstepB, voffB); PG8_STAGE(PG8_SA(1, 0), a3, voffA);
;             PG8_WAIT_V(8); PG8_WAIT_L(0); PG8_BAR; PG8_MMA(1, 0, At, B0); PG8_MMA(1, 1, At, B1); PG8_BAR; PG8_SCHED;
	s_add_i32 s67, 0, 0x18000
	v_add_u32_e32 v163, s67, v145
	s_add_i32 s68, 0, 0x1c000
	ds_read_b128 v[150:153], v163
	ds_read_b128 v[154:157], v163 offset:1024
	ds_read_b128 v[158:161], v163 offset:2048
	ds_read_b128 v[166:169], v163 offset:3072
	v_add_u32_e32 v163, s68, v145
	ds_read_b128 v[170:173], v163
	ds_read_b128 v[174:177], v163 offset:1024
	ds_read_b128 v[178:181], v163 offset:2048
	ds_read_b128 v[182:185], v163 offset:3072
	s_add_u32 s52, s52, 0x80000
	s_addc_u32 s53, s53, 0
	s_mov_b32 m0, s33
	ds_read_b128 v[186:189], v149 offset:32768
	ds_read_b128 v[190:193], v149 offset:33792
	ds_read_b128 v[194:197], v149 offset:34816
	ds_read_b128 v[198:201], v149 offset:35840
	ds_read_b128 v[202:205], v149 offset:36864
	ds_read_b128 v[206:209], v149 offset:37888
	ds_read_b128 v[210:213], v149 offset:38912
	ds_read_b128 v[214:217], v149 offset:39936
	global_load_lds_dwordx4 v134, s[52:53]
	s_mov_b32 m0, s34
	s_nop 0
	global_load_lds_dwordx4 v130, s[52:53]
	s_waitcnt vmcnt(8)
	s_waitcnt lgkmcnt(0)
	s_barrier
	s_setprio 0
	s_waitcnt lgkmcnt(0)
	v_mfma_f32_16x16x32_bf16 v[124:127], v[150:153], v[186:189], v[124:127]
	v_mfma_f32_16x16x32_bf16 v[120:123], v[158:161], v[186:189], v[120:123]
	v_mfma_f32_16x16x32_bf16 v[112:115], v[150:153], v[194:197], v[112:115]
	v_mfma_f32_16x16x32_bf16 v[104:107], v[158:161], v[194:197], v[104:107]
	v_mfma_f32_16x16x32_bf16 v[96:99], v[150:153], v[202:205], v[96:99]
	v_mfma_f32_16x16x32_bf16 v[88:91], v[158:161], v[202:205], v[88:91]
	v_mfma_f32_16x16x32_bf16 v[80:83], v[150:153], v[210:213], v[80:83]
	v_mfma_f32_16x16x32_bf16 v[72:75], v[158:161], v[210:213], v[72:75]
	v_mfma_f32_16x16x32_bf16 v[124:127], v[154:157], v[190:193], v[124:127]
	v_mfma_f32_16x16x32_bf16 v[120:123], v[166:169], v[190:193], v[120:123]
	v_mfma_f32_16x16x32_bf16 v[112:115], v[154:157], v[198:201], v[112:115]
	v_mfma_f32_16x16x32_bf16 v[104:107], v[166:169], v[198:201], v[104:107]
	v_mfma_f32_16x16x32_bf16 v[96:99], v[154:157], v[206:209], v[96:99]
	v_mfma_f32_16x16x32_bf16 v[88:91], v[166:169], v[206:209], v[88:91]
	v_mfma_f32_16x16x32_bf16 v[80:83], v[154:157], v[214:217], v[80:83]
	v_mfma_f32_16x16x32_bf16 v[72:75], v[166:169], v[214:217], v[72:75]
	v_mfma_f32_16x16x32_bf16 v[116:119], v[170:173], v[186:189], v[116:119]
	v_mfma_f32_16x16x32_bf16 v[108:111], v[178:181], v[186:189], v[108:111]
	v_mfma_f32_16x16x32_bf16 v[100:103], v[170:173], v[194:197], v[100:103]
	v_mfma_f32_16x16x32_bf16 v[92:95], v[178:181], v[194:197], v[92:95]
	v_mfma_f32_16x16x32_bf16 v[84:87], v[170:173], v[202:205], v[84:87]
	v_mfma_f32_16x16x32_bf16 v[76:79], v[178:181], v[202:205], v[76:79]
	v_mfma_f32_16x16x32_bf16 v[68:71], v[170:173], v[210:213], v[68:71]
	v_mfma_f32_16x16x32_bf16 v[64:67], v[178:181], v[210:213], v[64:67]
	v_mfma_f32_16x16x32_bf16 v[116:119], v[174:177], v[190:193], v[116:119]
	v_mfma_f32_16x16x32_bf16 v[108:111], v[182:185], v[190:193], v[108:111]
	v_mfma_f32_16x16x32_bf16 v[100:103], v[174:177], v[198:201], v[100:103]
	v_mfma_f32_16x16x32_bf16 v[92:95], v[182:185], v[198:201], v[92:95]
	v_mfma_f32_16x16x32_bf16 v[84:87], v[174:177], v[206:209], v[84:87]
	v_mfma_f32_16x16x32_bf16 v[76:79], v[182:185], v[206:209], v[76:79]
	v_mfma_f32_16x16x32_bf16 v[68:71], v[174:177], v[214:217], v[68:71]
	v_mfma_f32_16x16x32_bf16 v[64:67], v[182:185], v[214:217], v[64:67]
	s_setprio 1
	s_barrier
	s_add_i32 s52, s67, s28
	v_lshl_add_u64 v[218:219], v[218:219], 0, s[10:11]
	s_mov_b32 m0, s52
	ds_read_b128 v[186:189], v149 offset:49152
	ds_read_b128 v[190:193], v149 offset:50176
	ds_read_b128 v[194:197], v149 offset:51200
	ds_read_b128 v[198:201], v149 offset:52224
	ds_read_b128 v[202:205], v149 offset:53248
	ds_read_b128 v[206:209], v149 offset:54272
	ds_read_b128 v[210:213], v149 offset:55296
	ds_read_b128 v[214:217], v149 offset:56320
	global_load_lds_dwordx4 v[218:219], off
	s_add_i32 m0, s52, 0x2000
	s_add_u32 s50, s50, 0x80080
	v_lshl_add_u64 v[218:219], v[220:221], 0, s[10:11]
	s_addc_u32 s51, s51, 0
	s_add_i32 s52, s68, s28
	global_load_lds_dwordx4 v[218:219], off
	s_mov_b32 m0, s52
	s_nop 0
	global_load_lds_dwordx4 v132, s[50:51]
	s_add_i32 m0, s52, 0x2000
	s_nop 0
	global_load_lds_dwordx4 v128, s[50:51]
	v_lshl_add_u64 v[218:219], v[222:223], 0, s[10:11]
	s_mov_b32 m0, s47
	s_nop 0
	global_load_lds_dwordx4 v[218:219], off
	v_lshl_add_u64 v[218:219], v[224:225], 0, s[10:11]
	s_mov_b32 m0, s54
	s_nop 0
	global_load_lds_dwordx4 v[218:219], off
	s_waitcnt vmcnt(8)
	s_waitcnt lgkmcnt(0)
	s_barrier
	s_setprio 0
	s_waitcnt lgkmcnt(0)
	v_mfma_f32_16x16x32_bf16 v[60:63], v[150:153], v[186:189], v[60:63]
	v_mfma_f32_16x16x32_bf16 v[56:59], v[158:161], v[186:189], v[56:59]
	v_mfma_f32_16x16x32_bf16 v[48:51], v[150:153], v[194:197], v[48:51]
	v_mfma_f32_16x16x32_bf16 v[40:43], v[158:161], v[194:197], v[40:43]
	v_mfma_f32_16x16x32_bf16 v[32:35], v[150:153], v[202:205], v[32:35]
	v_mfma_f32_16x16x32_bf16 v[24:27], v[158:161], v[202:205], v[24:27]
	v_mfma_f32_16x16x32_bf16 v[16:19], v[150:153], v[210:213], v[16:19]
	v_mfma_f32_16x16x32_bf16 v[8:11], v[158:161], v[210:213], v[8:11]
	v_mfma_f32_16x16x32_bf16 v[60:63], v[154:157], v[190:193], v[60:63]
	v_mfma_f32_16x16x32_bf16 v[56:59], v[166:169], v[190:193], v[56:59]
	v_mfma_f32_16x16x32_bf16 v[48:51], v[154:157], v[198:201], v[48:51]
	v_mfma_f32_16x16x32_bf16 v[40:43], v[166:169], v[198:201], v[40:43]
	v_mfma_f32_16x16x32_bf16 v[32:35], v[154:157], v[206:209], v[32:35]
	v_mfma_f32_16x16x32_bf16 v[24:27], v[166:169], v[206:209], v[24:27]
	v_mfma_f32_16x16x32_bf16 v[16:19], v[154:157], v[214:217], v[16:19]
	v_mfma_f32_16x16x32_bf16 v[8:11], v[166:169], v[214:217], v[8:11]
	v_mfma_f32_16x16x32_bf16 v[52:55], v[170:173], v[186:189], v[52:55]
	v_mfma_f32_16x16x32_bf16 v[44:47], v[178:181], v[186:189], v[44:47]
	v_mfma_f32_16x16x32_bf16 v[36:39], v[170:173], v[194:197], v[36:39]
	v_mfma_f32_16x16x32_bf16 v[28:31], v[178:181], v[194:197], v[28:31]
	v_mfma_f32_16x16x32_bf16 v[20:23], v[170:173], v[202:205], v[20:23]
	v_mfma_f32_16x16x32_bf16 v[12:15], v[178:181], v[202:205], v[12:15]
	v_mfma_f32_16x16x32_bf16 v[4:7], v[170:173], v[210:213], v[4:7]
	v_mfma_f32_16x16x32_bf16 v[0:3], v[178:181], v[210:213], v[0:3]
	v_mfma_f32_16x16x32_bf16 v[52:55], v[174:177], v[190:193], v[52:55]
	v_mfma_f32_16x16x32_bf16 v[44:47], v[182:185], v[190:193], v[44:47]
	v_mfma_f32_16x16x32_bf16 v[36:39], v[174:177], v[198:201], v[36:39]
	v_mfma_f32_16x16x32_bf16 v[28:31], v[182:185], v[198:201], v[28:31]
	v_mfma_f32_16x16x32_bf16 v[20:23], v[174:177], v[206:209], v[20:23]
	v_mfma_f32_16x16x32_bf16 v[12:15], v[182:185], v[206:209], v[12:15]
	v_mfma_f32_16x16x32_bf16 v[4:7], v[174:177], v[214:217], v[4:7]
	v_mfma_f32_16x16x32_bf16 v[0:3], v[182:185], v[214:217], v[0:3]
	s_setprio 1
	s_barrier
	s_add_i32 s66, s66, 2
	s_add_u32 s48, s48, 0x100
	s_addc_u32 s49, s49, 0
	s_add_u32 s64, s64, 0x100
	s_addc_u32 s65, s65, 0
	s_cmp_gt_u32 s66, 29
	s_cbranch_scc0 .LBB0_1082
	s_and_b64 vcc, exec, s[16:17]
	s_cbranch_vccz .LBB0_1085
	s_barrier

; #define PG8_STAGE(bufoff, gbase, voff) do { _Pragma("unroll") for (int _i = 0; _i < 2; ++_i) \
;         __builtin_amdgcn_global_load_lds((const unsigned*)((const char*)(gbase) + (voff)[_i]), (PG8_LAS unsigned*)(lds + (bufoff) + ldsw + _i * 8192), 16, 0, 0); } while (0)
; #define PG8_LDA(dst, b, h) do { _Pragma("unroll") for (int m = 0; m < 4; ++m) _Pragma("unroll") for (int k = 0; k < 2; ++k) dst[m][k] = *(const PG8_LAS bf16x8*)(lds + PG8_SA(b, h) + aoff + m * 2048 + k * 1024); } while (0)
; #define PG8_LDB(dst, b, h) do { _Pragma("unroll") for (int n = 0; n < 2; ++n) _Pragma("unroll") for (int k = 0; k < 2; ++k) dst[n][k] = *(const PG8_LAS bf16x8*)(lds + PG8_SB(b, h) + boff + n * 2048 + k * 1024); } while (0)
; #define PG8_MMA(ai, bj, At, Bt) do { __builtin_amdgcn_s_setprio(1); _Pragma("unroll") for (int m = 0; m < 4; ++m) _Pragma("unroll") for (int n = 0; n < 2; ++n) _Pragma("unroll") for (int k = 0; k < 2; ++k) \
;         acc[ai][bj][m][n] = __builtin_amdgcn_mfma_f32_16x16x32_bf16(Bt[n][k], At[m][k], acc[ai][bj][m][n], 0, 0, 0); __builtin_amdgcn_s_setprio(0); } while (0)
; #define PG8_WAIT_V(n) asm volatile("s_waitcnt vmcnt(" #n ")" ::: "memory")
; #define PG8_WAIT_L(n) asm volatile("s_waitcnt lgkmcnt(" #n ")" ::: "memory")
; template <class Epi, class Sched, bool ALIGN_EPI = false, bool SP2 = false>
; __device__ __forceinline__ void gemm_phase(PG8_LAS unsigned char* lds, const Gemm g, const Sched& S, const Epi& E) {
;     ...
;             const bool last = (t == nt - 2);
;             const char* a1 = cA + (size_t)(t + 1) * kstep;
;             const char* a2 = last ? nA : cA + (size_t)(t + 2) * kstep; const char* b2 = last ? nB : cB + (size_t)(t + 2) * kstep;
;             const char* a3 = a2 + kstep; const char* b3 = b2 + kstep;
;             if (last && has_next) S.a_ready(nxt);
;             if constexpr (SP2) {
;             PG8_LDB(B0, 0, 0); PG8_LDB(B1, 0, 1); PG8_SCHED; PG8_LDA(At, 0, 0); PG8_STAGE(PG8_SA(1, 1), a1 + hstepA, voffA);
;             PG8_WAIT_V(8); PG8_WAIT_L(0); PG8_BAR; PG8_MMA(0, 0, At, B0); PG8_MMA(0, 1, At, B1); PG8_BAR; PG8_SCHED;
;             PG8_LDA(At, 0, 1); PG8_STAGE(PG8_SB(0, 0), b2, voffB); PG8_STAGE(PG8_SB(0, 1), b2 + hstepB, voffB); PG8_STAGE(PG8_SA(0, 0), a2, voffA);
;             PG8_WAIT_V(8); PG8_WAIT_L(0); PG8_BAR; PG8_MMA(1, 0, At, B0); PG8_MMA(1, 1, At, B1); PG8_BAR; PG8_SCHED;
.LBB0_1161:
	ds_read_b128 v[166:169], v157
	ds_read_b128 v[170:173], v157 offset:1024
	ds_read_b128 v[174:177], v157 offset:2048
	ds_read_b128 v[178:181], v157 offset:3072
	ds_read_b128 v[182:185], v158
	ds_read_b128 v[186:189], v158 offset:1024
	ds_read_b128 v[190:193], v158 offset:2048
	ds_read_b128 v[194:197], v158 offset:3072
	s_add_u32 s50, s48, 0xffe00080
	s_addc_u32 s51, s49, -1
	s_cmpk_eq_i32 s65, 0x7c
	s_cselect_b32 s53, s41, s51
	s_cselect_b32 s52, s61, s50
	s_cselect_b32 s51, s39, s64
	s_cselect_b32 s50, s62, s63
	s_add_i32 m0, s29, 0xc000
	ds_read_b128 v[198:201], v159
	ds_read_b128 v[202:205], v159 offset:1024
	ds_read_b128 v[206:209], v159 offset:2048
	ds_read_b128 v[210:213], v159 offset:3072
	ds_read_b128 v[214:217], v159 offset:4096
	ds_read_b128 v[218:221], v159 offset:5120
	ds_read_b128 v[222:225], v159 offset:6144
	ds_read_b128 v[226:229], v159 offset:7168
	global_load_lds_dwordx4 v136, s[48:49]
	s_add_i32 m0, s29, 0xe000
	s_nop 0
	global_load_lds_dwordx4 v138, s[48:49]
	s_waitcnt vmcnt(8)
	s_waitcnt lgkmcnt(0)
	s_barrier
	s_setprio 0
	s_waitcnt lgkmcnt(0)
	v_mfma_f32_16x16x32_bf16 v[124:127], v[166:169], v[198:201], v[124:127]
	v_mfma_f32_16x16x32_bf16 v[120:123], v[174:177], v[198:201], v[120:123]
	v_mfma_f32_16x16x32_bf16 v[116:119], v[166:169], v[206:209], v[116:119]
	v_mfma_f32_16x16x32_bf16 v[108:111], v[174:177], v[206:209], v[108:111]
	v_mfma_f32_16x16x32_bf16 v[100:103], v[166:169], v[214:217], v[100:103]
	v_mfma_f32_16x16x32_bf16 v[92:95], v[174:177], v[214:217], v[92:95]
	v_mfma_f32_16x16x32_bf16 v[80:83], v[166:169], v[222:225], v[80:83]
	v_mfma_f32_16x16x32_bf16 v[72:75], v[174:177], v[222:225], v[72:75]
	v_mfma_f32_16x16x32_bf16 v[124:127], v[170:173], v[202:205], v[124:127]
	v_mfma_f32_16x16x32_bf16 v[120:123], v[178:181], v[202:205], v[120:123]
	v_mfma_f32_16x16x32_bf16 v[116:119], v[170:173], v[210:213], v[116:119]
	v_mfma_f32_16x16x32_bf16 v[108:111], v[178:181], v[210:213], v[108:111]
	v_mfma_f32_16x16x32_bf16 v[100:103], v[170:173], v[218:221], v[100:103]
	v_mfma_f32_16x16x32_bf16 v[92:95], v[178:181], v[218:221], v[92:95]
	v_mfma_f32_16x16x32_bf16 v[80:83], v[170:173], v[226:229], v[80:83]
	v_mfma_f32_16x16x32_bf16 v[72:75], v[178:181], v[226:229], v[72:75]
	v_mfma_f32_16x16x32_bf16 v[112:115], v[182:185], v[198:201], v[112:115]
	v_mfma_f32_16x16x32_bf16 v[104:107], v[190:193], v[198:201], v[104:107]
	v_mfma_f32_16x16x32_bf16 v[96:99], v[182:185], v[206:209], v[96:99]
	v_mfma_f32_16x16x32_bf16 v[88:91], v[190:193], v[206:209], v[88:91]
	v_mfma_f32_16x16x32_bf16 v[84:87], v[182:185], v[214:217], v[84:87]
	v_mfma_f32_16x16x32_bf16 v[76:79], v[190:193], v[214:217], v[76:79]
	v_mfma_f32_16x16x32_bf16 v[68:71], v[182:185], v[222:225], v[68:71]
	v_mfma_f32_16x16x32_bf16 v[64:67], v[190:193], v[222:225], v[64:67]
	v_mfma_f32_16x16x32_bf16 v[112:115], v[186:189], v[202:205], v[112:115]
	v_mfma_f32_16x16x32_bf16 v[104:107], v[194:197], v[202:205], v[104:107]
	v_mfma_f32_16x16x32_bf16 v[96:99], v[186:189], v[210:213], v[96:99]
	v_mfma_f32_16x16x32_bf16 v[88:91], v[194:197], v[210:213], v[88:91]
	v_mfma_f32_16x16x32_bf16 v[84:87], v[186:189], v[218:221], v[84:87]
	v_mfma_f32_16x16x32_bf16 v[76:79], v[194:197], v[218:221], v[76:79]
	v_mfma_f32_16x16x32_bf16 v[68:71], v[186:189], v[226:229], v[68:71]
	v_mfma_f32_16x16x32_bf16 v[64:67], v[194:197], v[226:229], v[64:67]
	s_setprio 1
	s_barrier
	s_add_i32 s66, s54, s28
	v_lshl_add_u64 v[144:145], s[50:51], 0, v[130:131]
	s_mov_b32 m0, s66
	ds_read_b128 v[198:201], v159 offset:16384
	ds_read_b128 v[202:205], v159 offset:17408
	ds_read_b128 v[206:209], v159 offset:18432
	ds_read_b128 v[210:213], v159 offset:19456
	ds_read_b128 v[214:217], v159 offset:20480
	ds_read_b128 v[218:221], v159 offset:21504
	ds_read_b128 v[222:225], v159 offset:22528
	ds_read_b128 v[226:229], v159 offset:23552
	global_load_lds_dwordx4 v130, s[50:51]
	s_add_i32 m0, s66, 0x2000
	s_add_u32 s66, s50, 0x200000
	v_lshl_add_u64 v[160:161], s[50:51], 0, v[134:135]
	s_addc_u32 s67, s51, 0
	s_add_i32 s68, s55, s28
	global_load_lds_dwordx4 v134, s[50:51]
	s_mov_b32 m0, s68
	v_lshl_add_u64 v[232:233], s[52:53], 0, v[132:133]
	global_load_lds_dwordx4 v130, s[66:67]
	s_add_i32 m0, s68, 0x2000
	s_nop 0
	global_load_lds_dwordx4 v134, s[66:67]
	v_lshl_add_u64 v[230:231], s[52:53], 0, v[128:129]
	s_mov_b32 m0, s29
	s_nop 0
	global_load_lds_dwordx4 v128, s[52:53]
	s_mov_b32 m0, s30
	s_nop 0
	global_load_lds_dwordx4 v132, s[52:53]
	s_waitcnt vmcnt(8)
	s_waitcnt lgkmcnt(0)
	s_barrier
	s_setprio 0
	s_waitcnt lgkmcnt(0)
	v_mfma_f32_16x16x32_bf16 v[60:63], v[166:169], v[198:201], v[60:63]
	v_mfma_f32_16x16x32_bf16 v[56:59], v[174:177], v[198:201], v[56:59]
	v_mfma_f32_16x16x32_bf16 v[52:55], v[166:169], v[206:209], v[52:55]
	v_mfma_f32_16x16x32_bf16 v[44:47], v[174:177], v[206:209], v[44:47]
	v_mfma_f32_16x16x32_bf16 v[36:39], v[166:169], v[214:217], v[36:39]
	v_mfma_f32_16x16x32_bf16 v[28:31], v[174:177], v[214:217], v[28:31]
	v_mfma_f32_16x16x32_bf16 v[20:23], v[166:169], v[222:225], v[20:23]
	v_mfma_f32_16x16x32_bf16 v[12:15], v[174:177], v[222:225], v[12:15]
	v_mfma_f32_16x16x32_bf16 v[60:63], v[170:173], v[202:205], v[60:63]
	v_mfma_f32_16x16x32_bf16 v[56:59], v[178:181], v[202:205], v[56:59]
	v_mfma_f32_16x16x32_bf16 v[52:55], v[170:173], v[210:213], v[52:55]
	v_mfma_f32_16x16x32_bf16 v[44:47], v[178:181], v[210:213], v[44:47]
	v_mfma_f32_16x16x32_bf16 v[36:39], v[170:173], v[218:221], v[36:39]
	v_mfma_f32_16x16x32_bf16 v[28:31], v[178:181], v[218:221], v[28:31]
	v_mfma_f32_16x16x32_bf16 v[20:23], v[170:173], v[226:229], v[20:23]
	v_mfma_f32_16x16x32_bf16 v[12:15], v[178:181], v[226:229], v[12:15]
	v_mfma_f32_16x16x32_bf16 v[48:51], v[182:185], v[198:201], v[48:51]
	v_mfma_f32_16x16x32_bf16 v[40:43], v[190:193], v[198:201], v[40:43]
	v_mfma_f32_16x16x32_bf16 v[32:35], v[182:185], v[206:209], v[32:35]
	v_mfma_f32_16x16x32_bf16 v[24:27], v[190:193], v[206:209], v[24:27]
	v_mfma_f32_16x16x32_bf16 v[16:19], v[182:185], v[214:217], v[16:19]
	v_mfma_f32_16x16x32_bf16 v[8:11], v[190:193], v[214:217], v[8:11]
	v_mfma_f32_16x16x32_bf16 v[4:7], v[182:185], v[222:225], v[4:7]
	v_mfma_f32_16x16x32_bf16 v[0:3], v[190:193], v[222:225], v[0:3]
	v_mfma_f32_16x16x32_bf16 v[48:51], v[186:189], v[202:205], v[48:51]
	v_mfma_f32_16x16x32_bf16 v[40:43], v[194:197], v[202:205], v[40:43]
	v_mfma_f32_16x16x32_bf16 v[32:35], v[186:189], v[210:213], v[32:35]
	v_mfma_f32_16x16x32_bf16 v[24:27], v[194:197], v[210:213], v[24:27]
	v_mfma_f32_16x16x32_bf16 v[16:19], v[186:189], v[218:221], v[16:19]
	v_mfma_f32_16x16x32_bf16 v[8:11], v[194:197], v[218:221], v[8:11]
	v_mfma_f32_16x16x32_bf16 v[4:7], v[186:189], v[226:229], v[4:7]
	v_mfma_f32_16x16x32_bf16 v[0:3], v[194:197], v[226:229], v[0:3]
	s_setprio 1
	s_barrier
; #define PG8_STAGE(bufoff, gbase, voff) do { _Pragma("unroll") for (int _i = 0; _i < 2; ++_i) \
;         __builtin_amdgcn_global_load_lds((const unsigned*)((const char*)(gbase) + (voff)[_i]), (PG8_LAS unsigned*)(lds + (bufoff) + ldsw + _i * 8192), 16, 0, 0); } while (0)
; #define PG8_LDA(dst, b, h) do { _Pragma("unroll") for (int m = 0; m < 4; ++m) _Pragma("unroll") for (int k = 0; k < 2; ++k) dst[m][k] = *(const PG8_LAS bf16x8*)(lds + PG8_SA(b, h) + aoff + m * 2048 + k * 1024); } while (0)
; #define PG8_LDB(dst, b, h) do { _Pragma("unroll") for (int n = 0; n < 2; ++n) _Pragma("unroll") for (int k = 0; k < 2; ++k) dst[n][k] = *(const PG8_LAS bf16x8*)(lds + PG8_SB(b, h) + boff + n * 2048 + k * 1024); } while (0)
; #define PG8_MMA(ai, bj, At, Bt) do { __builtin_amdgcn_s_setprio(1); _Pragma("unroll") for (int m = 0; m < 4; ++m) _Pragma("unroll") for (int n = 0; n < 2; ++n) _Pragma("unroll") for (int k = 0; k < 2; ++k) \
;         acc[ai][bj][m][n] = __builtin_amdgcn_mfma_f32_16x16x32_bf16(Bt[n][k], At[m][k], acc[ai][bj][m][n], 0, 0, 0); __builtin_amdgcn_s_setprio(0); } while (0)
; #define PG8_WAIT_V(n) asm volatile("s_waitcnt vmcnt(" #n ")" ::: "memory")
; #define PG8_WAIT_L(n) asm volatile("s_waitcnt lgkmcnt(" #n ")" ::: "memory")
; #define PG8_BAR __builtin_amdgcn_s_barrier()
; #define PG8_SCHED __builtin_amdgcn_sched_barrier(0)
; template <class Epi, class Sched, bool ALIGN_EPI = false, bool SP2 = false>
; __device__ __forceinline__ void gemm_phase(PG8_LAS unsigned char* lds, const Gemm g, const Sched& S, const Epi& E) {
;     ...
;             PG8_LDB(B0, 1, 0); PG8_LDB(B1, 1, 1); PG8_SCHED; PG8_LDA(At, 1, 0); PG8_STAGE(PG8_SA(0, 1), a2 + hstepA, voffA);
;             PG8_WAIT_V(8); PG8_WAIT_L(0); PG8_BAR; PG8_MMA(0, 0, At, B0); PG8_MMA(0, 1, At, B1); PG8_BAR; PG8_SCHED;
;             PG8_LDA(At, 1, 1); PG8_STAGE(PG8_SB(1, 0), b3, voffB); PG8_STAGE(PG8_SB(1, 1), b3 + hstepB, voffB); PG8_STAGE(PG8_SA(1, 0), a3, voffA);
;             PG8_WAIT_V(8); PG8_WAIT_L(0); PG8_BAR; PG8_MMA(1, 0, At, B0); PG8_MMA(1, 1, At, B1); PG8_BAR; PG8_SCHED;
	s_add_i32 s66, 0, 0x18000
	v_add_u32_e32 v163, s66, v155
	s_add_i32 s67, 0, 0x1c000
	ds_read_b128 v[166:169], v163
	ds_read_b128 v[170:173], v163 offset:1024
	ds_read_b128 v[174:177], v163 offset:2048
	ds_read_b128 v[178:181], v163 offset:3072
	v_add_u32_e32 v163, s67, v155
	ds_read_b128 v[182:185], v163
	ds_read_b128 v[186:189], v163 offset:1024
	ds_read_b128 v[190:193], v163 offset:2048
	ds_read_b128 v[194:197], v163 offset:3072
	s_add_u32 s52, s52, 0x200000
	s_addc_u32 s53, s53, 0
	s_mov_b32 m0, s31
	ds_read_b128 v[198:201], v159 offset:32768
	ds_read_b128 v[202:205], v159 offset:33792
	ds_read_b128 v[206:209], v159 offset:34816
	ds_read_b128 v[210:213], v159 offset:35840
	ds_read_b128 v[214:217], v159 offset:36864
	ds_read_b128 v[218:221], v159 offset:37888
	ds_read_b128 v[222:225], v159 offset:38912
	ds_read_b128 v[226:229], v159 offset:39936
	global_load_lds_dwordx4 v128, s[52:53]
	s_mov_b32 m0, s33
	s_nop 0
	global_load_lds_dwordx4 v132, s[52:53]
	s_waitcnt vmcnt(8)
	s_waitcnt lgkmcnt(0)
	s_barrier
	s_setprio 0
	s_waitcnt lgkmcnt(0)
	v_mfma_f32_16x16x32_bf16 v[124:127], v[166:169], v[198:201], v[124:127]
	v_mfma_f32_16x16x32_bf16 v[120:123], v[174:177], v[198:201], v[120:123]
	v_mfma_f32_16x16x32_bf16 v[116:119], v[166:169], v[206:209], v[116:119]
	v_mfma_f32_16x16x32_bf16 v[108:111], v[174:177], v[206:209], v[108:111]
	v_mfma_f32_16x16x32_bf16 v[100:103], v[166:169], v[214:217], v[100:103]
	v_mfma_f32_16x16x32_bf16 v[92:95], v[174:177], v[214:217], v[92:95]
	v_mfma_f32_16x16x32_bf16 v[80:83], v[166:169], v[222:225], v[80:83]
	v_mfma_f32_16x16x32_bf16 v[72:75], v[174:177], v[222:225], v[72:75]
	v_mfma_f32_16x16x32_bf16 v[124:127], v[170:173], v[202:205], v[124:127]
	v_mfma_f32_16x16x32_bf16 v[120:123], v[178:181], v[202:205], v[120:123]
	v_mfma_f32_16x16x32_bf16 v[116:119], v[170:173], v[210:213], v[116:119]
	v_mfma_f32_16x16x32_bf16 v[108:111], v[178:181], v[210:213], v[108:111]
	v_mfma_f32_16x16x32_bf16 v[100:103], v[170:173], v[218:221], v[100:103]
	v_mfma_f32_16x16x32_bf16 v[92:95], v[178:181], v[218:221], v[92:95]
	v_mfma_f32_16x16x32_bf16 v[80:83], v[170:173], v[226:229], v[80:83]
	v_mfma_f32_16x16x32_bf16 v[72:75], v[178:181], v[226:229], v[72:75]
	v_mfma_f32_16x16x32_bf16 v[112:115], v[182:185], v[198:201], v[112:115]
	v_mfma_f32_16x16x32_bf16 v[104:107], v[190:193], v[198:201], v[104:107]
	v_mfma_f32_16x16x32_bf16 v[96:99], v[182:185], v[206:209], v[96:99]
	v_mfma_f32_16x16x32_bf16 v[88:91], v[190:193], v[206:209], v[88:91]
	v_mfma_f32_16x16x32_bf16 v[84:87], v[182:185], v[214:217], v[84:87]
	v_mfma_f32_16x16x32_bf16 v[76:79], v[190:193], v[214:217], v[76:79]
	v_mfma_f32_16x16x32_bf16 v[68:71], v[182:185], v[222:225], v[68:71]
	v_mfma_f32_16x16x32_bf16 v[64:67], v[190:193], v[222:225], v[64:67]
	v_mfma_f32_16x16x32_bf16 v[112:115], v[186:189], v[202:205], v[112:115]
	v_mfma_f32_16x16x32_bf16 v[104:107], v[194:197], v[202:205], v[104:107]
	v_mfma_f32_16x16x32_bf16 v[96:99], v[186:189], v[210:213], v[96:99]
	v_mfma_f32_16x16x32_bf16 v[88:91], v[194:197], v[210:213], v[88:91]
	v_mfma_f32_16x16x32_bf16 v[84:87], v[186:189], v[218:221], v[84:87]
	v_mfma_f32_16x16x32_bf16 v[76:79], v[194:197], v[218:221], v[76:79]
	v_mfma_f32_16x16x32_bf16 v[68:71], v[186:189], v[226:229], v[68:71]
	v_mfma_f32_16x16x32_bf16 v[64:67], v[194:197], v[226:229], v[64:67]
	s_setprio 1
	s_barrier
	s_add_i32 s52, s66, s28
	v_lshl_add_u64 v[144:145], v[144:145], 0, s[10:11]
	s_mov_b32 m0, s52
	ds_read_b128 v[198:201], v159 offset:49152
	ds_read_b128 v[202:205], v159 offset:50176
	ds_read_b128 v[206:209], v159 offset:51200
	ds_read_b128 v[210:213], v159 offset:52224
	ds_read_b128 v[214:217], v159 offset:53248
	ds_read_b128 v[218:221], v159 offset:54272
	ds_read_b128 v[222:225], v159 offset:55296
	ds_read_b128 v[226:229], v159 offset:56320
	global_load_lds_dwordx4 v[144:145], off
	s_add_i32 m0, s52, 0x2000
	s_add_u32 s50, s50, 0x200080
	v_lshl_add_u64 v[144:145], v[160:161], 0, s[10:11]
	s_addc_u32 s51, s51, 0
	s_add_i32 s52, s67, s28
	global_load_lds_dwordx4 v[144:145], off
	s_mov_b32 m0, s52
	s_nop 0
	global_load_lds_dwordx4 v130, s[50:51]
	s_add_i32 m0, s52, 0x2000
	s_nop 0
	global_load_lds_dwordx4 v134, s[50:51]
	v_lshl_add_u64 v[144:145], v[230:231], 0, s[10:11]
	s_mov_b32 m0, s35
	s_nop 0
	global_load_lds_dwordx4 v[144:145], off
	v_lshl_add_u64 v[144:145], v[232:233], 0, s[10:11]
	s_mov_b32 m0, s47
	s_nop 0
	global_load_lds_dwordx4 v[144:145], off
	s_waitcnt vmcnt(8)
	s_waitcnt lgkmcnt(0)
	s_barrier
	s_setprio 0
	s_waitcnt lgkmcnt(0)
	v_mfma_f32_16x16x32_bf16 v[60:63], v[166:169], v[198:201], v[60:63]
	v_mfma_f32_16x16x32_bf16 v[56:59], v[174:177], v[198:201], v[56:59]
	v_mfma_f32_16x16x32_bf16 v[52:55], v[166:169], v[206:209], v[52:55]
	v_mfma_f32_16x16x32_bf16 v[44:47], v[174:177], v[206:209], v[44:47]
	v_mfma_f32_16x16x32_bf16 v[36:39], v[166:169], v[214:217], v[36:39]
	v_mfma_f32_16x16x32_bf16 v[28:31], v[174:177], v[214:217], v[28:31]
	v_mfma_f32_16x16x32_bf16 v[20:23], v[166:169], v[222:225], v[20:23]
	v_mfma_f32_16x16x32_bf16 v[12:15], v[174:177], v[222:225], v[12:15]
	v_mfma_f32_16x16x32_bf16 v[60:63], v[170:173], v[202:205], v[60:63]
	v_mfma_f32_16x16x32_bf16 v[56:59], v[178:181], v[202:205], v[56:59]
	v_mfma_f32_16x16x32_bf16 v[52:55], v[170:173], v[210:213], v[52:55]
	v_mfma_f32_16x16x32_bf16 v[44:47], v[178:181], v[210:213], v[44:47]
	v_mfma_f32_16x16x32_bf16 v[36:39], v[170:173], v[218:221], v[36:39]
	v_mfma_f32_16x16x32_bf16 v[28:31], v[178:181], v[218:221], v[28:31]
	v_mfma_f32_16x16x32_bf16 v[20:23], v[170:173], v[226:229], v[20:23]
	v_mfma_f32_16x16x32_bf16 v[12:15], v[178:181], v[226:229], v[12:15]
	v_mfma_f32_16x16x32_bf16 v[48:51], v[182:185], v[198:201], v[48:51]
	v_mfma_f32_16x16x32_bf16 v[40:43], v[190:193], v[198:201], v[40:43]
	v_mfma_f32_16x16x32_bf16 v[32:35], v[182:185], v[206:209], v[32:35]
	v_mfma_f32_16x16x32_bf16 v[24:27], v[190:193], v[206:209], v[24:27]
	v_mfma_f32_16x16x32_bf16 v[16:19], v[182:185], v[214:217], v[16:19]
	v_mfma_f32_16x16x32_bf16 v[8:11], v[190:193], v[214:217], v[8:11]
	v_mfma_f32_16x16x32_bf16 v[4:7], v[182:185], v[222:225], v[4:7]
	v_mfma_f32_16x16x32_bf16 v[0:3], v[190:193], v[222:225], v[0:3]
	v_mfma_f32_16x16x32_bf16 v[48:51], v[186:189], v[202:205], v[48:51]
	v_mfma_f32_16x16x32_bf16 v[40:43], v[194:197], v[202:205], v[40:43]
	v_mfma_f32_16x16x32_bf16 v[32:35], v[186:189], v[210:213], v[32:35]
	v_mfma_f32_16x16x32_bf16 v[24:27], v[194:197], v[210:213], v[24:27]
	v_mfma_f32_16x16x32_bf16 v[16:19], v[186:189], v[218:221], v[16:19]
	v_mfma_f32_16x16x32_bf16 v[8:11], v[194:197], v[218:221], v[8:11]
	v_mfma_f32_16x16x32_bf16 v[4:7], v[186:189], v[226:229], v[4:7]
	v_mfma_f32_16x16x32_bf16 v[0:3], v[194:197], v[226:229], v[0:3]
	s_setprio 1
	s_barrier
	s_add_i32 s65, s65, 2
	s_add_u32 s48, s48, 0x100
	s_addc_u32 s49, s49, 0
	s_add_u32 s63, s63, 0x100
	s_addc_u32 s64, s64, 0
	s_cmpk_gt_u32 s65, 0x7d
	s_cbranch_scc0 .LBB0_1161
	s_and_b64 vcc, exec, s[16:17]
	s_cbranch_vccz .LBB0_1164
	s_barrier

; #define PG8_STAGE(bufoff, gbase, voff) do { _Pragma("unroll") for (int _i = 0; _i < 2; ++_i) \
;         __builtin_amdgcn_global_load_lds((const unsigned*)((const char*)(gbase) + (voff)[_i]), (PG8_LAS unsigned*)(lds + (bufoff) + ldsw + _i * 8192), 16, 0, 0); } while (0)
; #define PG8_LDA(dst, b, h) do { _Pragma("unroll") for (int m = 0; m < 4; ++m) _Pragma("unroll") for (int k = 0; k < 2; ++k) dst[m][k] = *(const PG8_LAS bf16x8*)(lds + PG8_SA(b, h) + aoff + m * 2048 + k * 1024); } while (0)
; #define PG8_LDB(dst, b, h) do { _Pragma("unroll") for (int n = 0; n < 2; ++n) _Pragma("unroll") for (int k = 0; k < 2; ++k) dst[n][k] = *(const PG8_LAS bf16x8*)(lds + PG8_SB(b, h) + boff + n * 2048 + k * 1024); } while (0)
; #define PG8_MMA(ai, bj, At, Bt) do { __builtin_amdgcn_s_setprio(1); _Pragma("unroll") for (int m = 0; m < 4; ++m) _Pragma("unroll") for (int n = 0; n < 2; ++n) _Pragma("unroll") for (int k = 0; k < 2; ++k) \
;         acc[ai][bj][m][n] = __builtin_amdgcn_mfma_f32_16x16x32_bf16(Bt[n][k], At[m][k], acc[ai][bj][m][n], 0, 0, 0); __builtin_amdgcn_s_setprio(0); } while (0)
; #define PG8_WAIT_V(n) asm volatile("s_waitcnt vmcnt(" #n ")" ::: "memory")
; #define PG8_WAIT_L(n) asm volatile("s_waitcnt lgkmcnt(" #n ")" ::: "memory")
; template <class Epi, class Sched, bool ALIGN_EPI = false, bool SP2 = false>
; __device__ __forceinline__ void gemm_phase(PG8_LAS unsigned char* lds, const Gemm g, const Sched& S, const Epi& E) {
;     ...
;             const bool last = (t == nt - 2);
;             const char* a1 = cA + (size_t)(t + 1) * kstep;
;             const char* a2 = last ? nA : cA + (size_t)(t + 2) * kstep; const char* b2 = last ? nB : cB + (size_t)(t + 2) * kstep;
;             const char* a3 = a2 + kstep; const char* b3 = b2 + kstep;
;             if (last && has_next) S.a_ready(nxt);
;             if constexpr (SP2) {
;             PG8_LDB(B0, 0, 0); PG8_LDB(B1, 0, 1); PG8_SCHED; PG8_LDA(At, 0, 0); PG8_STAGE(PG8_SA(1, 1), a1 + hstepA, voffA);
;             PG8_WAIT_V(8); PG8_WAIT_L(0); PG8_BAR; PG8_MMA(0, 0, At, B0); PG8_MMA(0, 1, At, B1); PG8_BAR; PG8_SCHED;
;             PG8_LDA(At, 0, 1); PG8_STAGE(PG8_SB(0, 0), b2, voffB); PG8_STAGE(PG8_SB(0, 1), b2 + hstepB, voffB); PG8_STAGE(PG8_SA(0, 0), a2, voffA);
;             PG8_WAIT_V(8); PG8_WAIT_L(0); PG8_BAR; PG8_MMA(1, 0, At, B0); PG8_MMA(1, 1, At, B1); PG8_BAR; PG8_SCHED;
.LBB0_1181:
	ds_read_b128 v[150:153], v146
	ds_read_b128 v[154:157], v146 offset:1024
	ds_read_b128 v[158:161], v146 offset:2048
	ds_read_b128 v[166:169], v146 offset:3072
	ds_read_b128 v[170:173], v147
	ds_read_b128 v[174:177], v147 offset:1024
	ds_read_b128 v[178:181], v147 offset:2048
	ds_read_b128 v[182:185], v147 offset:3072
	s_add_u32 s43, s46, 0xffe00080
	s_addc_u32 s48, s47, -1
	s_cmp_eq_u32 s41, 12
	s_cselect_b32 s51, s1, s48
	s_cselect_b32 s50, s0, s43
	s_cselect_b32 s49, s45, s39
	s_cselect_b32 s48, s44, s19
	s_mov_b32 m0, s55
	ds_read_b128 v[186:189], v148
	ds_read_b128 v[190:193], v148 offset:1024
	ds_read_b128 v[194:197], v148 offset:2048
	ds_read_b128 v[198:201], v148 offset:3072
	ds_read_b128 v[202:205], v148 offset:4096
	ds_read_b128 v[206:209], v148 offset:5120
	ds_read_b128 v[210:213], v148 offset:6144
	ds_read_b128 v[214:217], v148 offset:7168
	global_load_lds_dwordx4 v136, s[46:47]
	s_mov_b32 m0, s56
	s_nop 0
	global_load_lds_dwordx4 v138, s[46:47]
	s_waitcnt vmcnt(8)
	s_waitcnt lgkmcnt(0)
	s_barrier
	s_setprio 0
	s_waitcnt lgkmcnt(0)
	v_mfma_f32_16x16x32_bf16 v[124:127], v[150:153], v[186:189], v[124:127]
	v_mfma_f32_16x16x32_bf16 v[120:123], v[158:161], v[186:189], v[120:123]
	v_mfma_f32_16x16x32_bf16 v[116:119], v[150:153], v[194:197], v[116:119]
	v_mfma_f32_16x16x32_bf16 v[112:115], v[158:161], v[194:197], v[112:115]
	v_mfma_f32_16x16x32_bf16 v[100:103], v[150:153], v[202:205], v[100:103]
	v_mfma_f32_16x16x32_bf16 v[96:99], v[158:161], v[202:205], v[96:99]
	v_mfma_f32_16x16x32_bf16 v[84:87], v[150:153], v[210:213], v[84:87]
	v_mfma_f32_16x16x32_bf16 v[80:83], v[158:161], v[210:213], v[80:83]
	v_mfma_f32_16x16x32_bf16 v[124:127], v[154:157], v[190:193], v[124:127]
	v_mfma_f32_16x16x32_bf16 v[120:123], v[166:169], v[190:193], v[120:123]
	v_mfma_f32_16x16x32_bf16 v[116:119], v[154:157], v[198:201], v[116:119]
	v_mfma_f32_16x16x32_bf16 v[112:115], v[166:169], v[198:201], v[112:115]
	v_mfma_f32_16x16x32_bf16 v[100:103], v[154:157], v[206:209], v[100:103]
	v_mfma_f32_16x16x32_bf16 v[96:99], v[166:169], v[206:209], v[96:99]
	v_mfma_f32_16x16x32_bf16 v[84:87], v[154:157], v[214:217], v[84:87]
	v_mfma_f32_16x16x32_bf16 v[80:83], v[166:169], v[214:217], v[80:83]
	v_mfma_f32_16x16x32_bf16 v[108:111], v[170:173], v[186:189], v[108:111]
	v_mfma_f32_16x16x32_bf16 v[104:107], v[178:181], v[186:189], v[104:107]
	v_mfma_f32_16x16x32_bf16 v[92:95], v[170:173], v[194:197], v[92:95]
	v_mfma_f32_16x16x32_bf16 v[88:91], v[178:181], v[194:197], v[88:91]
	v_mfma_f32_16x16x32_bf16 v[76:79], v[170:173], v[202:205], v[76:79]
	v_mfma_f32_16x16x32_bf16 v[72:75], v[178:181], v[202:205], v[72:75]
	v_mfma_f32_16x16x32_bf16 v[68:71], v[170:173], v[210:213], v[68:71]
	v_mfma_f32_16x16x32_bf16 v[64:67], v[178:181], v[210:213], v[64:67]
	v_mfma_f32_16x16x32_bf16 v[108:111], v[174:177], v[190:193], v[108:111]
	v_mfma_f32_16x16x32_bf16 v[104:107], v[182:185], v[190:193], v[104:107]
	v_mfma_f32_16x16x32_bf16 v[92:95], v[174:177], v[198:201], v[92:95]
	v_mfma_f32_16x16x32_bf16 v[88:91], v[182:185], v[198:201], v[88:91]
	v_mfma_f32_16x16x32_bf16 v[76:79], v[174:177], v[206:209], v[76:79]
	v_mfma_f32_16x16x32_bf16 v[72:75], v[182:185], v[206:209], v[72:75]
	v_mfma_f32_16x16x32_bf16 v[68:71], v[174:177], v[214:217], v[68:71]
	v_mfma_f32_16x16x32_bf16 v[64:67], v[182:185], v[214:217], v[64:67]
	s_setprio 1
	s_barrier
	s_add_i32 s43, s53, s30
	v_lshl_add_u64 v[218:219], s[48:49], 0, v[130:131]
	s_mov_b32 m0, s43
	ds_read_b128 v[186:189], v148 offset:16384
	ds_read_b128 v[190:193], v148 offset:17408
	ds_read_b128 v[194:197], v148 offset:18432
	ds_read_b128 v[198:201], v148 offset:19456
	ds_read_b128 v[202:205], v148 offset:20480
	ds_read_b128 v[206:209], v148 offset:21504
	ds_read_b128 v[210:213], v148 offset:22528
	ds_read_b128 v[214:217], v148 offset:23552
	global_load_lds_dwordx4 v130, s[48:49]
	s_add_i32 m0, s43, 0x2000
	s_add_u32 s58, s48, 0x200000
	v_lshl_add_u64 v[220:221], s[48:49], 0, v[134:135]
	s_addc_u32 s59, s49, 0
	s_add_i32 s43, s54, s30
	global_load_lds_dwordx4 v134, s[48:49]
	s_mov_b32 m0, s43
	v_lshl_add_u64 v[224:225], s[50:51], 0, v[132:133]
	global_load_lds_dwordx4 v130, s[58:59]
	s_add_i32 m0, s43, 0x2000
	s_nop 0
	global_load_lds_dwordx4 v134, s[58:59]
	v_lshl_add_u64 v[222:223], s[50:51], 0, v[128:129]
	s_mov_b32 m0, s21
	s_nop 0
	global_load_lds_dwordx4 v128, s[50:51]
	s_mov_b32 m0, s23
	s_nop 0
	global_load_lds_dwordx4 v132, s[50:51]
	s_waitcnt vmcnt(8)
	s_waitcnt lgkmcnt(0)
	s_barrier
	s_setprio 0
	s_waitcnt lgkmcnt(0)
	v_mfma_f32_16x16x32_bf16 v[60:63], v[150:153], v[186:189], v[60:63]
	v_mfma_f32_16x16x32_bf16 v[56:59], v[158:161], v[186:189], v[56:59]
	v_mfma_f32_16x16x32_bf16 v[52:55], v[150:153], v[194:197], v[52:55]
	v_mfma_f32_16x16x32_bf16 v[48:51], v[158:161], v[194:197], v[48:51]
	v_mfma_f32_16x16x32_bf16 v[36:39], v[150:153], v[202:205], v[36:39]
	v_mfma_f32_16x16x32_bf16 v[32:35], v[158:161], v[202:205], v[32:35]
	v_mfma_f32_16x16x32_bf16 v[20:23], v[150:153], v[210:213], v[20:23]
	v_mfma_f32_16x16x32_bf16 v[16:19], v[158:161], v[210:213], v[16:19]
	v_mfma_f32_16x16x32_bf16 v[60:63], v[154:157], v[190:193], v[60:63]
	v_mfma_f32_16x16x32_bf16 v[56:59], v[166:169], v[190:193], v[56:59]
	v_mfma_f32_16x16x32_bf16 v[52:55], v[154:157], v[198:201], v[52:55]
	v_mfma_f32_16x16x32_bf16 v[48:51], v[166:169], v[198:201], v[48:51]
	v_mfma_f32_16x16x32_bf16 v[36:39], v[154:157], v[206:209], v[36:39]
	v_mfma_f32_16x16x32_bf16 v[32:35], v[166:169], v[206:209], v[32:35]
	v_mfma_f32_16x16x32_bf16 v[20:23], v[154:157], v[214:217], v[20:23]
	v_mfma_f32_16x16x32_bf16 v[16:19], v[166:169], v[214:217], v[16:19]
	v_mfma_f32_16x16x32_bf16 v[44:47], v[170:173], v[186:189], v[44:47]
	v_mfma_f32_16x16x32_bf16 v[40:43], v[178:181], v[186:189], v[40:43]
	v_mfma_f32_16x16x32_bf16 v[28:31], v[170:173], v[194:197], v[28:31]
	v_mfma_f32_16x16x32_bf16 v[24:27], v[178:181], v[194:197], v[24:27]
	v_mfma_f32_16x16x32_bf16 v[12:15], v[170:173], v[202:205], v[12:15]
	v_mfma_f32_16x16x32_bf16 v[8:11], v[178:181], v[202:205], v[8:11]
	v_mfma_f32_16x16x32_bf16 v[4:7], v[170:173], v[210:213], v[4:7]
	v_mfma_f32_16x16x32_bf16 v[0:3], v[178:181], v[210:213], v[0:3]
	v_mfma_f32_16x16x32_bf16 v[44:47], v[174:177], v[190:193], v[44:47]
	v_mfma_f32_16x16x32_bf16 v[40:43], v[182:185], v[190:193], v[40:43]
	v_mfma_f32_16x16x32_bf16 v[28:31], v[174:177], v[198:201], v[28:31]
	v_mfma_f32_16x16x32_bf16 v[24:27], v[182:185], v[198:201], v[24:27]
	v_mfma_f32_16x16x32_bf16 v[12:15], v[174:177], v[206:209], v[12:15]
	v_mfma_f32_16x16x32_bf16 v[8:11], v[182:185], v[206:209], v[8:11]
	v_mfma_f32_16x16x32_bf16 v[4:7], v[174:177], v[214:217], v[4:7]
	v_mfma_f32_16x16x32_bf16 v[0:3], v[182:185], v[214:217], v[0:3]
	s_setprio 1
	s_barrier
; #define PG8_STAGE(bufoff, gbase, voff) do { _Pragma("unroll") for (int _i = 0; _i < 2; ++_i) \
;         __builtin_amdgcn_global_load_lds((const unsigned*)((const char*)(gbase) + (voff)[_i]), (PG8_LAS unsigned*)(lds + (bufoff) + ldsw + _i * 8192), 16, 0, 0); } while (0)
; #define PG8_LDA(dst, b, h) do { _Pragma("unroll") for (int m = 0; m < 4; ++m) _Pragma("unroll") for (int k = 0; k < 2; ++k) dst[m][k] = *(const PG8_LAS bf16x8*)(lds + PG8_SA(b, h) + aoff + m * 2048 + k * 1024); } while (0)
; #define PG8_LDB(dst, b, h) do { _Pragma("unroll") for (int n = 0; n < 2; ++n) _Pragma("unroll") for (int k = 0; k < 2; ++k) dst[n][k] = *(const PG8_LAS bf16x8*)(lds + PG8_SB(b, h) + boff + n * 2048 + k * 1024); } while (0)
; #define PG8_MMA(ai, bj, At, Bt) do { __builtin_amdgcn_s_setprio(1); _Pragma("unroll") for (int m = 0; m < 4; ++m) _Pragma("unroll") for (int n = 0; n < 2; ++n) _Pragma("unroll") for (int k = 0; k < 2; ++k) \
;         acc[ai][bj][m][n] = __builtin_amdgcn_mfma_f32_16x16x32_bf16(Bt[n][k], At[m][k], acc[ai][bj][m][n], 0, 0, 0); __builtin_amdgcn_s_setprio(0); } while (0)
; #define PG8_WAIT_V(n) asm volatile("s_waitcnt vmcnt(" #n ")" ::: "memory")
; #define PG8_WAIT_L(n) asm volatile("s_waitcnt lgkmcnt(" #n ")" ::: "memory")
; #define PG8_BAR __builtin_amdgcn_s_barrier()
; #define PG8_SCHED __builtin_amdgcn_sched_barrier(0)
; template <class Epi, class Sched, bool ALIGN_EPI = false, bool SP2 = false>
; __device__ __forceinline__ void gemm_phase(PG8_LAS unsigned char* lds, const Gemm g, const Sched& S, const Epi& E) {
;     ...
;             PG8_LDB(B0, 1, 0); PG8_LDB(B1, 1, 1); PG8_SCHED; PG8_LDA(At, 1, 0); PG8_STAGE(PG8_SA(0, 1), a2 + hstepA, voffA);
;             PG8_WAIT_V(8); PG8_WAIT_L(0); PG8_BAR; PG8_MMA(0, 0, At, B0); PG8_MMA(0, 1, At, B1); PG8_BAR; PG8_SCHED;
;             PG8_LDA(At, 1, 1); PG8_STAGE(PG8_SB(1, 0), b3, voffB); PG8_STAGE(PG8_SB(1, 1), b3 + hstepB, voffB); PG8_STAGE(PG8_SA(1, 0), a3, voffA);
;             PG8_WAIT_V(8); PG8_WAIT_L(0); PG8_BAR; PG8_MMA(1, 0, At, B0); PG8_MMA(1, 1, At, B1); PG8_BAR; PG8_SCHED;
	s_add_i32 s43, 0, 0x18000
	v_add_u32_e32 v163, s43, v145
	s_add_i32 s57, 0, 0x1c000
	ds_read_b128 v[150:153], v163
	ds_read_b128 v[154:157], v163 offset:1024
	ds_read_b128 v[158:161], v163 offset:2048
	ds_read_b128 v[166:169], v163 offset:3072
	v_add_u32_e32 v163, s57, v145
	ds_read_b128 v[170:173], v163
	ds_read_b128 v[174:177], v163 offset:1024
	ds_read_b128 v[178:181], v163 offset:2048
	ds_read_b128 v[182:185], v163 offset:3072
	s_add_u32 s50, s50, 0x200000
	s_addc_u32 s51, s51, 0
	s_mov_b32 m0, s31
	ds_read_b128 v[186:189], v148 offset:32768
	ds_read_b128 v[190:193], v148 offset:33792
	ds_read_b128 v[194:197], v148 offset:34816
	ds_read_b128 v[198:201], v148 offset:35840
	ds_read_b128 v[202:205], v148 offset:36864
	ds_read_b128 v[206:209], v148 offset:37888
	ds_read_b128 v[210:213], v148 offset:38912
	ds_read_b128 v[214:217], v148 offset:39936
	global_load_lds_dwordx4 v128, s[50:51]
	s_mov_b32 m0, s33
	s_nop 0
	global_load_lds_dwordx4 v132, s[50:51]
	s_waitcnt vmcnt(8)
	s_waitcnt lgkmcnt(0)
	s_barrier
	s_setprio 0
	s_waitcnt lgkmcnt(0)
	v_mfma_f32_16x16x32_bf16 v[124:127], v[150:153], v[186:189], v[124:127]
	v_mfma_f32_16x16x32_bf16 v[120:123], v[158:161], v[186:189], v[120:123]
	v_mfma_f32_16x16x32_bf16 v[116:119], v[150:153], v[194:197], v[116:119]
	v_mfma_f32_16x16x32_bf16 v[112:115], v[158:161], v[194:197], v[112:115]
	v_mfma_f32_16x16x32_bf16 v[100:103], v[150:153], v[202:205], v[100:103]
	v_mfma_f32_16x16x32_bf16 v[96:99], v[158:161], v[202:205], v[96:99]
	v_mfma_f32_16x16x32_bf16 v[84:87], v[150:153], v[210:213], v[84:87]
	v_mfma_f32_16x16x32_bf16 v[80:83], v[158:161], v[210:213], v[80:83]
	v_mfma_f32_16x16x32_bf16 v[124:127], v[154:157], v[190:193], v[124:127]
	v_mfma_f32_16x16x32_bf16 v[120:123], v[166:169], v[190:193], v[120:123]
	v_mfma_f32_16x16x32_bf16 v[116:119], v[154:157], v[198:201], v[116:119]
	v_mfma_f32_16x16x32_bf16 v[112:115], v[166:169], v[198:201], v[112:115]
	v_mfma_f32_16x16x32_bf16 v[100:103], v[154:157], v[206:209], v[100:103]
	v_mfma_f32_16x16x32_bf16 v[96:99], v[166:169], v[206:209], v[96:99]
	v_mfma_f32_16x16x32_bf16 v[84:87], v[154:157], v[214:217], v[84:87]
	v_mfma_f32_16x16x32_bf16 v[80:83], v[166:169], v[214:217], v[80:83]
	v_mfma_f32_16x16x32_bf16 v[108:111], v[170:173], v[186:189], v[108:111]
	v_mfma_f32_16x16x32_bf16 v[104:107], v[178:181], v[186:189], v[104:107]
	v_mfma_f32_16x16x32_bf16 v[92:95], v[170:173], v[194:197], v[92:95]
	v_mfma_f32_16x16x32_bf16 v[88:91], v[178:181], v[194:197], v[88:91]
	v_mfma_f32_16x16x32_bf16 v[76:79], v[170:173], v[202:205], v[76:79]
	v_mfma_f32_16x16x32_bf16 v[72:75], v[178:181], v[202:205], v[72:75]
	v_mfma_f32_16x16x32_bf16 v[68:71], v[170:173], v[210:213], v[68:71]
	v_mfma_f32_16x16x32_bf16 v[64:67], v[178:181], v[210:213], v[64:67]
	v_mfma_f32_16x16x32_bf16 v[108:111], v[174:177], v[190:193], v[108:111]
	v_mfma_f32_16x16x32_bf16 v[104:107], v[182:185], v[190:193], v[104:107]
	v_mfma_f32_16x16x32_bf16 v[92:95], v[174:177], v[198:201], v[92:95]
	v_mfma_f32_16x16x32_bf16 v[88:91], v[182:185], v[198:201], v[88:91]
	v_mfma_f32_16x16x32_bf16 v[76:79], v[174:177], v[206:209], v[76:79]
	v_mfma_f32_16x16x32_bf16 v[72:75], v[182:185], v[206:209], v[72:75]
	v_mfma_f32_16x16x32_bf16 v[68:71], v[174:177], v[214:217], v[68:71]
	v_mfma_f32_16x16x32_bf16 v[64:67], v[182:185], v[214:217], v[64:67]
	s_setprio 1
	s_barrier
	s_add_i32 s43, s43, s30
	v_lshl_add_u64 v[218:219], v[218:219], 0, s[16:17]
	s_mov_b32 m0, s43
	ds_read_b128 v[186:189], v148 offset:49152
	ds_read_b128 v[190:193], v148 offset:50176
	ds_read_b128 v[194:197], v148 offset:51200
	ds_read_b128 v[198:201], v148 offset:52224
	ds_read_b128 v[202:205], v148 offset:53248
	ds_read_b128 v[206:209], v148 offset:54272
	ds_read_b128 v[210:213], v148 offset:55296
	ds_read_b128 v[214:217], v148 offset:56320
	global_load_lds_dwordx4 v[218:219], off
	s_add_i32 m0, s43, 0x2000
	s_add_u32 s48, s48, 0x200080
	v_lshl_add_u64 v[218:219], v[220:221], 0, s[16:17]
	s_addc_u32 s49, s49, 0
	s_add_i32 s43, s57, s30
	global_load_lds_dwordx4 v[218:219], off
	s_mov_b32 m0, s43
	s_nop 0
	global_load_lds_dwordx4 v130, s[48:49]
	s_add_i32 m0, s43, 0x2000
	s_nop 0
	global_load_lds_dwordx4 v134, s[48:49]
	v_lshl_add_u64 v[218:219], v[222:223], 0, s[16:17]
	s_mov_b32 m0, s35
	s_nop 0
	global_load_lds_dwordx4 v[218:219], off
	v_lshl_add_u64 v[218:219], v[224:225], 0, s[16:17]
	s_mov_b32 m0, s52
	s_nop 0
	global_load_lds_dwordx4 v[218:219], off
	s_waitcnt vmcnt(8)
	s_waitcnt lgkmcnt(0)
	s_barrier
	s_setprio 0
	s_waitcnt lgkmcnt(0)
	v_mfma_f32_16x16x32_bf16 v[60:63], v[150:153], v[186:189], v[60:63]
	v_mfma_f32_16x16x32_bf16 v[56:59], v[158:161], v[186:189], v[56:59]
	v_mfma_f32_16x16x32_bf16 v[52:55], v[150:153], v[194:197], v[52:55]
	v_mfma_f32_16x16x32_bf16 v[48:51], v[158:161], v[194:197], v[48:51]
	v_mfma_f32_16x16x32_bf16 v[36:39], v[150:153], v[202:205], v[36:39]
	v_mfma_f32_16x16x32_bf16 v[32:35], v[158:161], v[202:205], v[32:35]
	v_mfma_f32_16x16x32_bf16 v[20:23], v[150:153], v[210:213], v[20:23]
	v_mfma_f32_16x16x32_bf16 v[16:19], v[158:161], v[210:213], v[16:19]
	v_mfma_f32_16x16x32_bf16 v[60:63], v[154:157], v[190:193], v[60:63]
	v_mfma_f32_16x16x32_bf16 v[56:59], v[166:169], v[190:193], v[56:59]
	v_mfma_f32_16x16x32_bf16 v[52:55], v[154:157], v[198:201], v[52:55]
	v_mfma_f32_16x16x32_bf16 v[48:51], v[166:169], v[198:201], v[48:51]
	v_mfma_f32_16x16x32_bf16 v[36:39], v[154:157], v[206:209], v[36:39]
	v_mfma_f32_16x16x32_bf16 v[32:35], v[166:169], v[206:209], v[32:35]
	v_mfma_f32_16x16x32_bf16 v[20:23], v[154:157], v[214:217], v[20:23]
	v_mfma_f32_16x16x32_bf16 v[16:19], v[166:169], v[214:217], v[16:19]
	v_mfma_f32_16x16x32_bf16 v[44:47], v[170:173], v[186:189], v[44:47]
	v_mfma_f32_16x16x32_bf16 v[40:43], v[178:181], v[186:189], v[40:43]
	v_mfma_f32_16x16x32_bf16 v[28:31], v[170:173], v[194:197], v[28:31]
	v_mfma_f32_16x16x32_bf16 v[24:27], v[178:181], v[194:197], v[24:27]
	v_mfma_f32_16x16x32_bf16 v[12:15], v[170:173], v[202:205], v[12:15]
	v_mfma_f32_16x16x32_bf16 v[8:11], v[178:181], v[202:205], v[8:11]
	v_mfma_f32_16x16x32_bf16 v[4:7], v[170:173], v[210:213], v[4:7]
	v_mfma_f32_16x16x32_bf16 v[0:3], v[178:181], v[210:213], v[0:3]
	v_mfma_f32_16x16x32_bf16 v[44:47], v[174:177], v[190:193], v[44:47]
	v_mfma_f32_16x16x32_bf16 v[40:43], v[182:185], v[190:193], v[40:43]
	v_mfma_f32_16x16x32_bf16 v[28:31], v[174:177], v[198:201], v[28:31]
	v_mfma_f32_16x16x32_bf16 v[24:27], v[182:185], v[198:201], v[24:27]
	v_mfma_f32_16x16x32_bf16 v[12:15], v[174:177], v[206:209], v[12:15]
	v_mfma_f32_16x16x32_bf16 v[8:11], v[182:185], v[206:209], v[8:11]
	v_mfma_f32_16x16x32_bf16 v[4:7], v[174:177], v[214:217], v[4:7]
	v_mfma_f32_16x16x32_bf16 v[0:3], v[182:185], v[214:217], v[0:3]
	s_setprio 1
	s_barrier
	s_add_i32 s41, s41, 2
	s_add_u32 s46, s46, 0x100
	s_addc_u32 s47, s47, 0
	s_add_u32 s19, s19, 0x100
	s_addc_u32 s39, s39, 0
	s_cmp_gt_u32 s41, 13
	s_cbranch_scc0 .LBB0_1181
	s_and_b64 vcc, exec, s[36:37]
	s_cbranch_vccz .LBB0_1184
	s_barrier

; #define PG8_STAGE(bufoff, gbase, voff) do { _Pragma("unroll") for (int _i = 0; _i < 2; ++_i) \
;         __builtin_amdgcn_global_load_lds((const unsigned*)((const char*)(gbase) + (voff)[_i]), (PG8_LAS unsigned*)(lds + (bufoff) + ldsw + _i * 8192), 16, 0, 0); } while (0)
; #define PG8_LDA(dst, b, h) do { _Pragma("unroll") for (int m = 0; m < 4; ++m) _Pragma("unroll") for (int k = 0; k < 2; ++k) dst[m][k] = *(const PG8_LAS bf16x8*)(lds + PG8_SA(b, h) + aoff + m * 2048 + k * 1024); } while (0)
; #define PG8_LDB(dst, b, h) do { _Pragma("unroll") for (int n = 0; n < 2; ++n) _Pragma("unroll") for (int k = 0; k < 2; ++k) dst[n][k] = *(const PG8_LAS bf16x8*)(lds + PG8_SB(b, h) + boff + n * 2048 + k * 1024); } while (0)
; #define PG8_MMA(ai, bj, At, Bt) do { __builtin_amdgcn_s_setprio(1); _Pragma("unroll") for (int m = 0; m < 4; ++m) _Pragma("unroll") for (int n = 0; n < 2; ++n) _Pragma("unroll") for (int k = 0; k < 2; ++k) \
;         acc[ai][bj][m][n] = __builtin_amdgcn_mfma_f32_16x16x32_bf16(Bt[n][k], At[m][k], acc[ai][bj][m][n], 0, 0, 0); __builtin_amdgcn_s_setprio(0); } while (0)
; #define PG8_WAIT_V(n) asm volatile("s_waitcnt vmcnt(" #n ")" ::: "memory")
; #define PG8_WAIT_L(n) asm volatile("s_waitcnt lgkmcnt(" #n ")" ::: "memory")
; template <class Epi, class Sched, bool ALIGN_EPI = false, bool SP2 = false>
; __device__ __forceinline__ void gemm_phase(PG8_LAS unsigned char* lds, const Gemm g, const Sched& S, const Epi& E) {
;     ...
;             const bool last = (t == nt - 2);
;             const char* a1 = cA + (size_t)(t + 1) * kstep;
;             const char* a2 = last ? nA : cA + (size_t)(t + 2) * kstep; const char* b2 = last ? nB : cB + (size_t)(t + 2) * kstep;
;             const char* a3 = a2 + kstep; const char* b3 = b2 + kstep;
;             if (last && has_next) S.a_ready(nxt);
;             if constexpr (SP2) {
;             PG8_LDB(B0, 0, 0); PG8_LDB(B1, 0, 1); PG8_SCHED; PG8_LDA(At, 0, 0); PG8_STAGE(PG8_SA(1, 1), a1 + hstepA, voffA);
;             PG8_WAIT_V(8); PG8_WAIT_L(0); PG8_BAR; PG8_MMA(0, 0, At, B0); PG8_MMA(0, 1, At, B1); PG8_BAR; PG8_SCHED;
;             PG8_LDA(At, 0, 1); PG8_STAGE(PG8_SB(0, 0), b2, voffB); PG8_STAGE(PG8_SB(0, 1), b2 + hstepB, voffB); PG8_STAGE(PG8_SA(0, 0), a2, voffA);
;             PG8_WAIT_V(8); PG8_WAIT_L(0); PG8_BAR; PG8_MMA(1, 0, At, B0); PG8_MMA(1, 1, At, B1); PG8_BAR; PG8_SCHED;
.LBB0_1262:
	s_add_u32 s51, s44, s50
	s_addc_u32 s56, s45, 0
	s_add_u32 s54, s51, 0x100
	s_addc_u32 s55, s56, 0
	s_and_b64 s[52:53], s[48:49], exec
	s_cselect_b32 s53, s23, s55
	s_cselect_b32 s52, s69, s54
	s_add_u32 s50, s42, s50
	s_addc_u32 s54, s43, 0
	s_add_u32 s50, s50, 0x100
	s_addc_u32 s54, s54, 0
	s_and_b64 s[48:49], s[48:49], exec
	s_cselect_b32 s55, s21, s54
	s_cselect_b32 s54, s70, s50
	s_add_u32 s58, s51, 0x10080
	ds_read_b128 v[148:151], v145
	ds_read_b128 v[152:155], v145 offset:1024
	ds_read_b128 v[156:159], v145 offset:2048
	ds_read_b128 v[166:169], v145 offset:3072
	ds_read_b128 v[170:173], v146
	ds_read_b128 v[174:177], v146 offset:1024
	ds_read_b128 v[178:181], v146 offset:2048
	ds_read_b128 v[182:185], v146 offset:3072
	s_addc_u32 s59, s56, 0
	s_add_i32 s80, s63, s28
	s_add_i32 m0, s33, 0xc000
	s_add_i32 s81, s33, 0xe000
	s_add_i32 s77, s80, 0x2000
	s_add_u32 s56, s54, 0x10000
	s_addc_u32 s57, s55, 0
	s_add_i32 s79, s64, s28
	s_add_i32 s78, s79, 0x2000
	s_add_i32 s76, 0, 0x18000
	s_add_i32 s75, 0, 0x1c000
	s_add_u32 s50, s52, 0x10000
	s_addc_u32 s51, s53, 0
	s_add_i32 s74, s76, s28
	s_add_i32 s72, s74, 0x2000
	s_add_u32 s48, s54, 0x10080
	s_addc_u32 s49, s55, 0
	s_add_i32 s73, s75, s28
	s_add_i32 s71, s73, 0x2000
	ds_read_b128 v[186:189], v147
	ds_read_b128 v[190:193], v147 offset:1024
	ds_read_b128 v[194:197], v147 offset:2048
	ds_read_b128 v[198:201], v147 offset:3072
	ds_read_b128 v[202:205], v147 offset:4096
	ds_read_b128 v[206:209], v147 offset:5120
	ds_read_b128 v[210:213], v147 offset:6144
	ds_read_b128 v[214:217], v147 offset:7168
	global_load_lds_dwordx4 v134, s[58:59]
	s_mov_b32 m0, s81
	s_nop 0
	global_load_lds_dwordx4 v130, s[58:59]
	s_waitcnt vmcnt(8)
	s_waitcnt lgkmcnt(0)
	s_barrier
	s_setprio 0
	s_waitcnt lgkmcnt(0)
	v_mfma_f32_16x16x32_bf16 v[124:127], v[148:151], v[186:189], v[124:127]
	v_mfma_f32_16x16x32_bf16 v[120:123], v[156:159], v[186:189], v[120:123]
	v_mfma_f32_16x16x32_bf16 v[116:119], v[148:151], v[194:197], v[116:119]
	v_mfma_f32_16x16x32_bf16 v[108:111], v[156:159], v[194:197], v[108:111]
	v_mfma_f32_16x16x32_bf16 v[100:103], v[148:151], v[202:205], v[100:103]
	v_mfma_f32_16x16x32_bf16 v[92:95], v[156:159], v[202:205], v[92:95]
	v_mfma_f32_16x16x32_bf16 v[84:87], v[148:151], v[210:213], v[84:87]
	v_mfma_f32_16x16x32_bf16 v[76:79], v[156:159], v[210:213], v[76:79]
	v_mfma_f32_16x16x32_bf16 v[124:127], v[152:155], v[190:193], v[124:127]
	v_mfma_f32_16x16x32_bf16 v[120:123], v[166:169], v[190:193], v[120:123]
	v_mfma_f32_16x16x32_bf16 v[116:119], v[152:155], v[198:201], v[116:119]
	v_mfma_f32_16x16x32_bf16 v[108:111], v[166:169], v[198:201], v[108:111]
	v_mfma_f32_16x16x32_bf16 v[100:103], v[152:155], v[206:209], v[100:103]
	v_mfma_f32_16x16x32_bf16 v[92:95], v[166:169], v[206:209], v[92:95]
	v_mfma_f32_16x16x32_bf16 v[84:87], v[152:155], v[214:217], v[84:87]
	v_mfma_f32_16x16x32_bf16 v[76:79], v[166:169], v[214:217], v[76:79]
	v_mfma_f32_16x16x32_bf16 v[112:115], v[170:173], v[186:189], v[112:115]
	v_mfma_f32_16x16x32_bf16 v[104:107], v[178:181], v[186:189], v[104:107]
	v_mfma_f32_16x16x32_bf16 v[96:99], v[170:173], v[194:197], v[96:99]
	v_mfma_f32_16x16x32_bf16 v[88:91], v[178:181], v[194:197], v[88:91]
	v_mfma_f32_16x16x32_bf16 v[80:83], v[170:173], v[202:205], v[80:83]
	v_mfma_f32_16x16x32_bf16 v[72:75], v[178:181], v[202:205], v[72:75]
	v_mfma_f32_16x16x32_bf16 v[68:71], v[170:173], v[210:213], v[68:71]
	v_mfma_f32_16x16x32_bf16 v[64:67], v[178:181], v[210:213], v[64:67]
	v_mfma_f32_16x16x32_bf16 v[112:115], v[174:177], v[190:193], v[112:115]
	v_mfma_f32_16x16x32_bf16 v[104:107], v[182:185], v[190:193], v[104:107]
	v_mfma_f32_16x16x32_bf16 v[96:99], v[174:177], v[198:201], v[96:99]
	v_mfma_f32_16x16x32_bf16 v[88:91], v[182:185], v[198:201], v[88:91]
	v_mfma_f32_16x16x32_bf16 v[80:83], v[174:177], v[206:209], v[80:83]
	v_mfma_f32_16x16x32_bf16 v[72:75], v[182:185], v[206:209], v[72:75]
	v_mfma_f32_16x16x32_bf16 v[68:71], v[174:177], v[214:217], v[68:71]
	v_mfma_f32_16x16x32_bf16 v[64:67], v[182:185], v[214:217], v[64:67]
	s_setprio 1
	s_barrier
	s_mov_b32 m0, s80
	v_lshl_add_u64 v[140:141], s[54:55], 0, v[132:133]
	ds_read_b128 v[186:189], v147 offset:16384
	ds_read_b128 v[190:193], v147 offset:17408
	ds_read_b128 v[194:197], v147 offset:18432
	ds_read_b128 v[198:201], v147 offset:19456
	ds_read_b128 v[202:205], v147 offset:20480
	ds_read_b128 v[206:209], v147 offset:21504
	ds_read_b128 v[210:213], v147 offset:22528
	ds_read_b128 v[214:217], v147 offset:23552
	global_load_lds_dwordx4 v132, s[54:55]
	v_lshl_add_u64 v[160:161], s[54:55], 0, v[128:129]
	s_mov_b32 m0, s77
	s_nop 0
	global_load_lds_dwordx4 v128, s[54:55]
	s_mov_b32 m0, s79
	v_lshl_add_u64 v[220:221], s[52:53], 0, v[130:131]
	global_load_lds_dwordx4 v132, s[56:57]
	s_mov_b32 m0, s78
	s_nop 0
	global_load_lds_dwordx4 v128, s[56:57]
	v_lshl_add_u64 v[218:219], s[52:53], 0, v[134:135]
	s_mov_b32 m0, s33
	s_nop 0
	global_load_lds_dwordx4 v134, s[52:53]
	s_mov_b32 m0, s34
	s_nop 0
	global_load_lds_dwordx4 v130, s[52:53]
	s_waitcnt vmcnt(8)
	s_waitcnt lgkmcnt(0)
	s_barrier
; #define PG8_STAGE(bufoff, gbase, voff) do { _Pragma("unroll") for (int _i = 0; _i < 2; ++_i) \
;         __builtin_amdgcn_global_load_lds((const unsigned*)((const char*)(gbase) + (voff)[_i]), (PG8_LAS unsigned*)(lds + (bufoff) + ldsw + _i * 8192), 16, 0, 0); } while (0)
; #define PG8_LDA(dst, b, h) do { _Pragma("unroll") for (int m = 0; m < 4; ++m) _Pragma("unroll") for (int k = 0; k < 2; ++k) dst[m][k] = *(const PG8_LAS bf16x8*)(lds + PG8_SA(b, h) + aoff + m * 2048 + k * 1024); } while (0)
; #define PG8_LDB(dst, b, h) do { _Pragma("unroll") for (int n = 0; n < 2; ++n) _Pragma("unroll") for (int k = 0; k < 2; ++k) dst[n][k] = *(const PG8_LAS bf16x8*)(lds + PG8_SB(b, h) + boff + n * 2048 + k * 1024); } while (0)
; #define PG8_MMA(ai, bj, At, Bt) do { __builtin_amdgcn_s_setprio(1); _Pragma("unroll") for (int m = 0; m < 4; ++m) _Pragma("unroll") for (int n = 0; n < 2; ++n) _Pragma("unroll") for (int k = 0; k < 2; ++k) \
;         acc[ai][bj][m][n] = __builtin_amdgcn_mfma_f32_16x16x32_bf16(Bt[n][k], At[m][k], acc[ai][bj][m][n], 0, 0, 0); __builtin_amdgcn_s_setprio(0); } while (0)
; #define PG8_WAIT_V(n) asm volatile("s_waitcnt vmcnt(" #n ")" ::: "memory")
; #define PG8_WAIT_L(n) asm volatile("s_waitcnt lgkmcnt(" #n ")" ::: "memory")
; #define PG8_BAR __builtin_amdgcn_s_barrier()
; #define PG8_SCHED __builtin_amdgcn_sched_barrier(0)
; template <class Epi, class Sched, bool ALIGN_EPI = false, bool SP2 = false>
; __device__ __forceinline__ void gemm_phase(PG8_LAS unsigned char* lds, const Gemm g, const Sched& S, const Epi& E) {
;     ...
;             PG8_WAIT_V(8); PG8_WAIT_L(0); PG8_BAR; PG8_MMA(1, 0, At, B0); PG8_MMA(1, 1, At, B1); PG8_BAR; PG8_SCHED;
;             PG8_LDB(B0, 1, 0); PG8_LDB(B1, 1, 1); PG8_SCHED; PG8_LDA(At, 1, 0); PG8_STAGE(PG8_SA(0, 1), a2 + hstepA, voffA);
;             PG8_WAIT_V(8); PG8_WAIT_L(0); PG8_BAR; PG8_MMA(0, 0, At, B0); PG8_MMA(0, 1, At, B1); PG8_BAR; PG8_SCHED;
	s_setprio 0
	s_waitcnt lgkmcnt(0)
	v_mfma_f32_16x16x32_bf16 v[60:63], v[148:151], v[186:189], v[60:63]
	v_mfma_f32_16x16x32_bf16 v[56:59], v[156:159], v[186:189], v[56:59]
	v_mfma_f32_16x16x32_bf16 v[52:55], v[148:151], v[194:197], v[52:55]
	v_mfma_f32_16x16x32_bf16 v[44:47], v[156:159], v[194:197], v[44:47]
	v_mfma_f32_16x16x32_bf16 v[36:39], v[148:151], v[202:205], v[36:39]
	v_mfma_f32_16x16x32_bf16 v[28:31], v[156:159], v[202:205], v[28:31]
	v_mfma_f32_16x16x32_bf16 v[20:23], v[148:151], v[210:213], v[20:23]
	v_mfma_f32_16x16x32_bf16 v[12:15], v[156:159], v[210:213], v[12:15]
	v_mfma_f32_16x16x32_bf16 v[60:63], v[152:155], v[190:193], v[60:63]
	v_mfma_f32_16x16x32_bf16 v[56:59], v[166:169], v[190:193], v[56:59]
	v_mfma_f32_16x16x32_bf16 v[52:55], v[152:155], v[198:201], v[52:55]
	v_mfma_f32_16x16x32_bf16 v[44:47], v[166:169], v[198:201], v[44:47]
	v_mfma_f32_16x16x32_bf16 v[36:39], v[152:155], v[206:209], v[36:39]
	v_mfma_f32_16x16x32_bf16 v[28:31], v[166:169], v[206:209], v[28:31]
	v_mfma_f32_16x16x32_bf16 v[20:23], v[152:155], v[214:217], v[20:23]
	v_mfma_f32_16x16x32_bf16 v[12:15], v[166:169], v[214:217], v[12:15]
	v_mfma_f32_16x16x32_bf16 v[48:51], v[170:173], v[186:189], v[48:51]
	v_mfma_f32_16x16x32_bf16 v[40:43], v[178:181], v[186:189], v[40:43]
	v_mfma_f32_16x16x32_bf16 v[32:35], v[170:173], v[194:197], v[32:35]
	v_mfma_f32_16x16x32_bf16 v[24:27], v[178:181], v[194:197], v[24:27]
	v_mfma_f32_16x16x32_bf16 v[16:19], v[170:173], v[202:205], v[16:19]
	v_mfma_f32_16x16x32_bf16 v[8:11], v[178:181], v[202:205], v[8:11]
	v_mfma_f32_16x16x32_bf16 v[4:7], v[170:173], v[210:213], v[4:7]
	v_mfma_f32_16x16x32_bf16 v[0:3], v[178:181], v[210:213], v[0:3]
	v_mfma_f32_16x16x32_bf16 v[48:51], v[174:177], v[190:193], v[48:51]
	v_mfma_f32_16x16x32_bf16 v[40:43], v[182:185], v[190:193], v[40:43]
	v_mfma_f32_16x16x32_bf16 v[32:35], v[174:177], v[198:201], v[32:35]
	v_mfma_f32_16x16x32_bf16 v[24:27], v[182:185], v[198:201], v[24:27]
	v_mfma_f32_16x16x32_bf16 v[16:19], v[174:177], v[206:209], v[16:19]
	v_mfma_f32_16x16x32_bf16 v[8:11], v[182:185], v[206:209], v[8:11]
	v_mfma_f32_16x16x32_bf16 v[4:7], v[174:177], v[214:217], v[4:7]
	v_mfma_f32_16x16x32_bf16 v[0:3], v[182:185], v[214:217], v[0:3]
	s_setprio 1
	s_barrier
	v_add_u32_e32 v163, s76, v143
	ds_read_b128 v[148:151], v163
	ds_read_b128 v[152:155], v163 offset:1024
	ds_read_b128 v[156:159], v163 offset:2048
	ds_read_b128 v[166:169], v163 offset:3072
	v_add_u32_e32 v163, s75, v143
	ds_read_b128 v[170:173], v163
	ds_read_b128 v[174:177], v163 offset:1024
	ds_read_b128 v[178:181], v163 offset:2048
	ds_read_b128 v[182:185], v163 offset:3072
	s_mov_b32 m0, s35
	ds_read_b128 v[186:189], v147 offset:32768
	ds_read_b128 v[190:193], v147 offset:33792
	ds_read_b128 v[194:197], v147 offset:34816
	ds_read_b128 v[198:201], v147 offset:35840
	ds_read_b128 v[202:205], v147 offset:36864
	ds_read_b128 v[206:209], v147 offset:37888
	ds_read_b128 v[210:213], v147 offset:38912
	ds_read_b128 v[214:217], v147 offset:39936
	global_load_lds_dwordx4 v134, s[50:51]
	s_mov_b32 m0, s41
	s_nop 0
	global_load_lds_dwordx4 v130, s[50:51]
	s_waitcnt vmcnt(8)
	s_waitcnt lgkmcnt(0)
	s_barrier
	s_setprio 0
	s_waitcnt lgkmcnt(0)
	v_mfma_f32_16x16x32_bf16 v[124:127], v[148:151], v[186:189], v[124:127]
	v_mfma_f32_16x16x32_bf16 v[120:123], v[156:159], v[186:189], v[120:123]
	v_mfma_f32_16x16x32_bf16 v[116:119], v[148:151], v[194:197], v[116:119]
	v_mfma_f32_16x16x32_bf16 v[108:111], v[156:159], v[194:197], v[108:111]
	v_mfma_f32_16x16x32_bf16 v[100:103], v[148:151], v[202:205], v[100:103]
	v_mfma_f32_16x16x32_bf16 v[92:95], v[156:159], v[202:205], v[92:95]
	v_mfma_f32_16x16x32_bf16 v[84:87], v[148:151], v[210:213], v[84:87]
	v_mfma_f32_16x16x32_bf16 v[76:79], v[156:159], v[210:213], v[76:79]
	v_mfma_f32_16x16x32_bf16 v[124:127], v[152:155], v[190:193], v[124:127]
	v_mfma_f32_16x16x32_bf16 v[120:123], v[166:169], v[190:193], v[120:123]
	v_mfma_f32_16x16x32_bf16 v[116:119], v[152:155], v[198:201], v[116:119]
	v_mfma_f32_16x16x32_bf16 v[108:111], v[166:169], v[198:201], v[108:111]
	v_mfma_f32_16x16x32_bf16 v[100:103], v[152:155], v[206:209], v[100:103]
	v_mfma_f32_16x16x32_bf16 v[92:95], v[166:169], v[206:209], v[92:95]
	v_mfma_f32_16x16x32_bf16 v[84:87], v[152:155], v[214:217], v[84:87]
	v_mfma_f32_16x16x32_bf16 v[76:79], v[166:169], v[214:217], v[76:79]
	v_mfma_f32_16x16x32_bf16 v[112:115], v[170:173], v[186:189], v[112:115]
	v_mfma_f32_16x16x32_bf16 v[104:107], v[178:181], v[186:189], v[104:107]
	v_mfma_f32_16x16x32_bf16 v[96:99], v[170:173], v[194:197], v[96:99]
	v_mfma_f32_16x16x32_bf16 v[88:91], v[178:181], v[194:197], v[88:91]
	v_mfma_f32_16x16x32_bf16 v[80:83], v[170:173], v[202:205], v[80:83]
	v_mfma_f32_16x16x32_bf16 v[72:75], v[178:181], v[202:205], v[72:75]
	v_mfma_f32_16x16x32_bf16 v[68:71], v[170:173], v[210:213], v[68:71]
	v_mfma_f32_16x16x32_bf16 v[64:67], v[178:181], v[210:213], v[64:67]
	v_mfma_f32_16x16x32_bf16 v[112:115], v[174:177], v[190:193], v[112:115]
	v_mfma_f32_16x16x32_bf16 v[104:107], v[182:185], v[190:193], v[104:107]
	v_mfma_f32_16x16x32_bf16 v[96:99], v[174:177], v[198:201], v[96:99]
	v_mfma_f32_16x16x32_bf16 v[88:91], v[182:185], v[198:201], v[88:91]
	v_mfma_f32_16x16x32_bf16 v[80:83], v[174:177], v[206:209], v[80:83]
	v_mfma_f32_16x16x32_bf16 v[72:75], v[182:185], v[206:209], v[72:75]
	v_mfma_f32_16x16x32_bf16 v[68:71], v[174:177], v[214:217], v[68:71]
	v_mfma_f32_16x16x32_bf16 v[64:67], v[182:185], v[214:217], v[64:67]
	s_setprio 1
	s_barrier
; #define PG8_STAGE(bufoff, gbase, voff) do { _Pragma("unroll") for (int _i = 0; _i < 2; ++_i) \
;         __builtin_amdgcn_global_load_lds((const unsigned*)((const char*)(gbase) + (voff)[_i]), (PG8_LAS unsigned*)(lds + (bufoff) + ldsw + _i * 8192), 16, 0, 0); } while (0)
; #define PG8_LDA(dst, b, h) do { _Pragma("unroll") for (int m = 0; m < 4; ++m) _Pragma("unroll") for (int k = 0; k < 2; ++k) dst[m][k] = *(const PG8_LAS bf16x8*)(lds + PG8_SA(b, h) + aoff + m * 2048 + k * 1024); } while (0)
; #define PG8_MMA(ai, bj, At, Bt) do { __builtin_amdgcn_s_setprio(1); _Pragma("unroll") for (int m = 0; m < 4; ++m) _Pragma("unroll") for (int n = 0; n < 2; ++n) _Pragma("unroll") for (int k = 0; k < 2; ++k) \
;         acc[ai][bj][m][n] = __builtin_amdgcn_mfma_f32_16x16x32_bf16(Bt[n][k], At[m][k], acc[ai][bj][m][n], 0, 0, 0); __builtin_amdgcn_s_setprio(0); } while (0)
; #define PG8_WAIT_V(n) asm volatile("s_waitcnt vmcnt(" #n ")" ::: "memory")
; #define PG8_WAIT_L(n) asm volatile("s_waitcnt lgkmcnt(" #n ")" ::: "memory")
; #define PG8_BAR __builtin_amdgcn_s_barrier()
; #define PG8_SCHED __builtin_amdgcn_sched_barrier(0)
; template <class Epi, class Sched, bool ALIGN_EPI = false, bool SP2 = false>
; __device__ __forceinline__ void gemm_phase(PG8_LAS unsigned char* lds, const Gemm g, const Sched& S, const Epi& E) {
;     ...
;             PG8_LDA(At, 1, 1); PG8_STAGE(PG8_SB(1, 0), b3, voffB); PG8_STAGE(PG8_SB(1, 1), b3 + hstepB, voffB); PG8_STAGE(PG8_SA(1, 0), a3, voffA);
;             PG8_WAIT_V(8); PG8_WAIT_L(0); PG8_BAR; PG8_MMA(1, 0, At, B0); PG8_MMA(1, 1, At, B1); PG8_BAR; PG8_SCHED;
	s_mov_b32 m0, s74
	v_lshl_add_u64 v[140:141], v[140:141], 0, s[8:9]
	ds_read_b128 v[186:189], v147 offset:49152
	ds_read_b128 v[190:193], v147 offset:50176
	ds_read_b128 v[194:197], v147 offset:51200
	ds_read_b128 v[198:201], v147 offset:52224
	ds_read_b128 v[202:205], v147 offset:53248
	ds_read_b128 v[206:209], v147 offset:54272
	ds_read_b128 v[210:213], v147 offset:55296
	ds_read_b128 v[214:217], v147 offset:56320
	global_load_lds_dwordx4 v[140:141], off
	v_lshl_add_u64 v[140:141], v[160:161], 0, s[8:9]
	s_mov_b32 m0, s72
	s_nop 0
	global_load_lds_dwordx4 v[140:141], off
	s_mov_b32 m0, s73
	s_nop 0
	global_load_lds_dwordx4 v132, s[48:49]
	s_mov_b32 m0, s71
	s_nop 0
	global_load_lds_dwordx4 v128, s[48:49]
	v_lshl_add_u64 v[140:141], v[218:219], 0, s[8:9]
	s_mov_b32 m0, s61
	s_nop 0
	global_load_lds_dwordx4 v[140:141], off
	v_lshl_add_u64 v[140:141], v[220:221], 0, s[8:9]
	s_mov_b32 m0, s62
	s_nop 0
	global_load_lds_dwordx4 v[140:141], off
	s_waitcnt vmcnt(8)
	s_waitcnt lgkmcnt(0)
	s_barrier
	s_setprio 0
	s_waitcnt lgkmcnt(0)
	v_mfma_f32_16x16x32_bf16 v[60:63], v[148:151], v[186:189], v[60:63]
	v_mfma_f32_16x16x32_bf16 v[56:59], v[156:159], v[186:189], v[56:59]
	v_mfma_f32_16x16x32_bf16 v[52:55], v[148:151], v[194:197], v[52:55]
	v_mfma_f32_16x16x32_bf16 v[44:47], v[156:159], v[194:197], v[44:47]
	v_mfma_f32_16x16x32_bf16 v[36:39], v[148:151], v[202:205], v[36:39]
	v_mfma_f32_16x16x32_bf16 v[28:31], v[156:159], v[202:205], v[28:31]
	v_mfma_f32_16x16x32_bf16 v[20:23], v[148:151], v[210:213], v[20:23]
	v_mfma_f32_16x16x32_bf16 v[12:15], v[156:159], v[210:213], v[12:15]
	v_mfma_f32_16x16x32_bf16 v[60:63], v[152:155], v[190:193], v[60:63]
	v_mfma_f32_16x16x32_bf16 v[56:59], v[166:169], v[190:193], v[56:59]
	v_mfma_f32_16x16x32_bf16 v[52:55], v[152:155], v[198:201], v[52:55]
	v_mfma_f32_16x16x32_bf16 v[44:47], v[166:169], v[198:201], v[44:47]
	v_mfma_f32_16x16x32_bf16 v[36:39], v[152:155], v[206:209], v[36:39]
	v_mfma_f32_16x16x32_bf16 v[28:31], v[166:169], v[206:209], v[28:31]
	v_mfma_f32_16x16x32_bf16 v[20:23], v[152:155], v[214:217], v[20:23]
	v_mfma_f32_16x16x32_bf16 v[12:15], v[166:169], v[214:217], v[12:15]
	v_mfma_f32_16x16x32_bf16 v[48:51], v[170:173], v[186:189], v[48:51]
	v_mfma_f32_16x16x32_bf16 v[40:43], v[178:181], v[186:189], v[40:43]
	v_mfma_f32_16x16x32_bf16 v[32:35], v[170:173], v[194:197], v[32:35]
	v_mfma_f32_16x16x32_bf16 v[24:27], v[178:181], v[194:197], v[24:27]
	v_mfma_f32_16x16x32_bf16 v[16:19], v[170:173], v[202:205], v[16:19]
	v_mfma_f32_16x16x32_bf16 v[8:11], v[178:181], v[202:205], v[8:11]
	v_mfma_f32_16x16x32_bf16 v[4:7], v[170:173], v[210:213], v[4:7]
	v_mfma_f32_16x16x32_bf16 v[0:3], v[178:181], v[210:213], v[0:3]
	v_mfma_f32_16x16x32_bf16 v[48:51], v[174:177], v[190:193], v[48:51]
	v_mfma_f32_16x16x32_bf16 v[40:43], v[182:185], v[190:193], v[40:43]
	v_mfma_f32_16x16x32_bf16 v[32:35], v[174:177], v[198:201], v[32:35]
	v_mfma_f32_16x16x32_bf16 v[24:27], v[182:185], v[198:201], v[24:27]
	v_mfma_f32_16x16x32_bf16 v[16:19], v[174:177], v[206:209], v[16:19]
	v_mfma_f32_16x16x32_bf16 v[8:11], v[182:185], v[206:209], v[8:11]
	v_mfma_f32_16x16x32_bf16 v[4:7], v[174:177], v[214:217], v[4:7]
	v_mfma_f32_16x16x32_bf16 v[0:3], v[182:185], v[214:217], v[0:3]
	s_setprio 1
	s_barrier
	s_movk_i32 s50, 0x100
	s_andn2_b64 vcc, exec, s[46:47]
	s_mov_b64 s[48:49], -1
	s_mov_b64 s[46:47], 0
	s_cbranch_vccz .LBB0_1262
	s_and_b64 vcc, exec, s[10:11]
	s_cbranch_vccz .LBB0_1265
	s_barrier

; #define PG8_STAGE(bufoff, gbase, voff) do { _Pragma("unroll") for (int _i = 0; _i < 2; ++_i) \
;         __builtin_amdgcn_global_load_lds((const unsigned*)((const char*)(gbase) + (voff)[_i]), (PG8_LAS unsigned*)(lds + (bufoff) + ldsw + _i * 8192), 16, 0, 0); } while (0)
; #define PG8_LDA(dst, b, h) do { _Pragma("unroll") for (int m = 0; m < 4; ++m) _Pragma("unroll") for (int k = 0; k < 2; ++k) dst[m][k] = *(const PG8_LAS bf16x8*)(lds + PG8_SA(b, h) + aoff + m * 2048 + k * 1024); } while (0)
; #define PG8_LDB(dst, b, h) do { _Pragma("unroll") for (int n = 0; n < 2; ++n) _Pragma("unroll") for (int k = 0; k < 2; ++k) dst[n][k] = *(const PG8_LAS bf16x8*)(lds + PG8_SB(b, h) + boff + n * 2048 + k * 1024); } while (0)
; #define PG8_MMA(ai, bj, At, Bt) do { __builtin_amdgcn_s_setprio(1); _Pragma("unroll") for (int m = 0; m < 4; ++m) _Pragma("unroll") for (int n = 0; n < 2; ++n) _Pragma("unroll") for (int k = 0; k < 2; ++k) \
;         acc[ai][bj][m][n] = __builtin_amdgcn_mfma_f32_16x16x32_bf16(Bt[n][k], At[m][k], acc[ai][bj][m][n], 0, 0, 0); __builtin_amdgcn_s_setprio(0); } while (0)
; #define PG8_WAIT_V(n) asm volatile("s_waitcnt vmcnt(" #n ")" ::: "memory")
; #define PG8_WAIT_L(n) asm volatile("s_waitcnt lgkmcnt(" #n ")" ::: "memory")
; template <class Epi, class Sched, bool ALIGN_EPI = false, bool SP2 = false>
; __device__ __forceinline__ void gemm_phase(PG8_LAS unsigned char* lds, const Gemm g, const Sched& S, const Epi& E) {
;     ...
;             const bool last = (t == nt - 2);
;             const char* a1 = cA + (size_t)(t + 1) * kstep;
;             const char* a2 = last ? nA : cA + (size_t)(t + 2) * kstep; const char* b2 = last ? nB : cB + (size_t)(t + 2) * kstep;
;             const char* a3 = a2 + kstep; const char* b3 = b2 + kstep;
;             if (last && has_next) S.a_ready(nxt);
;             if constexpr (SP2) {
;             PG8_LDB(B0, 0, 0); PG8_LDB(B1, 0, 1); PG8_SCHED; PG8_LDA(At, 0, 0); PG8_STAGE(PG8_SA(1, 1), a1 + hstepA, voffA);
;             PG8_WAIT_V(8); PG8_WAIT_L(0); PG8_BAR; PG8_MMA(0, 0, At, B0); PG8_MMA(0, 1, At, B1); PG8_BAR; PG8_SCHED;
;             PG8_LDA(At, 0, 1); PG8_STAGE(PG8_SB(0, 0), b2, voffB); PG8_STAGE(PG8_SB(0, 1), b2 + hstepB, voffB); PG8_STAGE(PG8_SA(0, 0), a2, voffA);
;             PG8_WAIT_V(8); PG8_WAIT_L(0); PG8_BAR; PG8_MMA(1, 0, At, B0); PG8_MMA(1, 1, At, B1); PG8_BAR; PG8_SCHED;
.LBB0_1333:
	ds_read_b128 v[144:147], v153
	ds_read_b128 v[156:159], v153 offset:1024
	ds_read_b128 v[166:169], v153 offset:2048
	ds_read_b128 v[170:173], v153 offset:3072
	ds_read_b128 v[174:177], v154
	ds_read_b128 v[178:181], v154 offset:1024
	ds_read_b128 v[182:185], v154 offset:2048
	ds_read_b128 v[186:189], v154 offset:3072
	s_add_u32 s46, s44, 0xfff80080
	s_addc_u32 s47, s45, -1
	s_cmp_eq_u32 s62, 28
	s_cselect_b32 s49, s37, s47
	s_cselect_b32 s48, s58, s46
	s_cselect_b32 s47, s23, s61
	s_cselect_b32 s46, s59, s60
	s_add_i32 m0, s30, 0xc000
	ds_read_b128 v[190:193], v155
	ds_read_b128 v[194:197], v155 offset:1024
	ds_read_b128 v[198:201], v155 offset:2048
	ds_read_b128 v[202:205], v155 offset:3072
	ds_read_b128 v[206:209], v155 offset:4096
	ds_read_b128 v[210:213], v155 offset:5120
	ds_read_b128 v[214:217], v155 offset:6144
	ds_read_b128 v[218:221], v155 offset:7168
	global_load_lds_dwordx4 v136, s[44:45]
	s_add_i32 m0, s30, 0xe000
	s_nop 0
	global_load_lds_dwordx4 v138, s[44:45]
	s_waitcnt vmcnt(8)
	s_waitcnt lgkmcnt(0)
	s_barrier
	s_setprio 0
	s_waitcnt lgkmcnt(0)
	v_mfma_f32_16x16x32_bf16 v[124:127], v[144:147], v[190:193], v[124:127]
	v_mfma_f32_16x16x32_bf16 v[120:123], v[166:169], v[190:193], v[120:123]
	v_mfma_f32_16x16x32_bf16 v[108:111], v[144:147], v[198:201], v[108:111]
	v_mfma_f32_16x16x32_bf16 v[104:107], v[166:169], v[198:201], v[104:107]
	v_mfma_f32_16x16x32_bf16 v[92:95], v[144:147], v[206:209], v[92:95]
	v_mfma_f32_16x16x32_bf16 v[88:91], v[166:169], v[206:209], v[88:91]
	v_mfma_f32_16x16x32_bf16 v[76:79], v[144:147], v[214:217], v[76:79]
	v_mfma_f32_16x16x32_bf16 v[72:75], v[166:169], v[214:217], v[72:75]
	v_mfma_f32_16x16x32_bf16 v[124:127], v[156:159], v[194:197], v[124:127]
	v_mfma_f32_16x16x32_bf16 v[120:123], v[170:173], v[194:197], v[120:123]
	v_mfma_f32_16x16x32_bf16 v[108:111], v[156:159], v[202:205], v[108:111]
	v_mfma_f32_16x16x32_bf16 v[104:107], v[170:173], v[202:205], v[104:107]
	v_mfma_f32_16x16x32_bf16 v[92:95], v[156:159], v[210:213], v[92:95]
	v_mfma_f32_16x16x32_bf16 v[88:91], v[170:173], v[210:213], v[88:91]
	v_mfma_f32_16x16x32_bf16 v[76:79], v[156:159], v[218:221], v[76:79]
	v_mfma_f32_16x16x32_bf16 v[72:75], v[170:173], v[218:221], v[72:75]
	v_mfma_f32_16x16x32_bf16 v[116:119], v[174:177], v[190:193], v[116:119]
	v_mfma_f32_16x16x32_bf16 v[112:115], v[182:185], v[190:193], v[112:115]
	v_mfma_f32_16x16x32_bf16 v[100:103], v[174:177], v[198:201], v[100:103]
	v_mfma_f32_16x16x32_bf16 v[96:99], v[182:185], v[198:201], v[96:99]
	v_mfma_f32_16x16x32_bf16 v[84:87], v[174:177], v[206:209], v[84:87]
	v_mfma_f32_16x16x32_bf16 v[80:83], v[182:185], v[206:209], v[80:83]
	v_mfma_f32_16x16x32_bf16 v[68:71], v[174:177], v[214:217], v[68:71]
	v_mfma_f32_16x16x32_bf16 v[64:67], v[182:185], v[214:217], v[64:67]
	v_mfma_f32_16x16x32_bf16 v[116:119], v[178:181], v[194:197], v[116:119]
	v_mfma_f32_16x16x32_bf16 v[112:115], v[186:189], v[194:197], v[112:115]
	v_mfma_f32_16x16x32_bf16 v[100:103], v[178:181], v[202:205], v[100:103]
	v_mfma_f32_16x16x32_bf16 v[96:99], v[186:189], v[202:205], v[96:99]
	v_mfma_f32_16x16x32_bf16 v[84:87], v[178:181], v[210:213], v[84:87]
	v_mfma_f32_16x16x32_bf16 v[80:83], v[186:189], v[210:213], v[80:83]
	v_mfma_f32_16x16x32_bf16 v[68:71], v[178:181], v[218:221], v[68:71]
	v_mfma_f32_16x16x32_bf16 v[64:67], v[186:189], v[218:221], v[64:67]
	s_setprio 1
	s_barrier
	s_add_i32 s63, s51, s28
	v_lshl_add_u64 v[148:149], s[46:47], 0, v[132:133]
	s_mov_b32 m0, s63
	ds_read_b128 v[190:193], v155 offset:16384
	ds_read_b128 v[194:197], v155 offset:17408
	ds_read_b128 v[198:201], v155 offset:18432
	ds_read_b128 v[202:205], v155 offset:19456
	ds_read_b128 v[206:209], v155 offset:20480
	ds_read_b128 v[210:213], v155 offset:21504
	ds_read_b128 v[214:217], v155 offset:22528
	ds_read_b128 v[218:221], v155 offset:23552
	global_load_lds_dwordx4 v132, s[46:47]
	s_add_i32 m0, s63, 0x2000
	s_add_u32 s64, s46, 0x80000
	v_lshl_add_u64 v[160:161], s[46:47], 0, v[128:129]
	s_addc_u32 s65, s47, 0
	s_add_i32 s63, s52, s28
	global_load_lds_dwordx4 v128, s[46:47]
	s_mov_b32 m0, s63
	v_lshl_add_u64 v[224:225], s[48:49], 0, v[130:131]
	global_load_lds_dwordx4 v132, s[64:65]
	s_add_i32 m0, s63, 0x2000
	s_nop 0
	global_load_lds_dwordx4 v128, s[64:65]
	v_lshl_add_u64 v[222:223], s[48:49], 0, v[134:135]
	s_mov_b32 m0, s30
	s_nop 0
	global_load_lds_dwordx4 v134, s[48:49]
	s_mov_b32 m0, s31
	s_nop 0
	global_load_lds_dwordx4 v130, s[48:49]
	s_waitcnt vmcnt(8)
	s_waitcnt lgkmcnt(0)
	s_barrier
	s_setprio 0
	s_waitcnt lgkmcnt(0)
	v_mfma_f32_16x16x32_bf16 v[60:63], v[144:147], v[190:193], v[60:63]
	v_mfma_f32_16x16x32_bf16 v[56:59], v[166:169], v[190:193], v[56:59]
	v_mfma_f32_16x16x32_bf16 v[44:47], v[144:147], v[198:201], v[44:47]
	v_mfma_f32_16x16x32_bf16 v[40:43], v[166:169], v[198:201], v[40:43]
	v_mfma_f32_16x16x32_bf16 v[28:31], v[144:147], v[206:209], v[28:31]
	v_mfma_f32_16x16x32_bf16 v[24:27], v[166:169], v[206:209], v[24:27]
	v_mfma_f32_16x16x32_bf16 v[12:15], v[144:147], v[214:217], v[12:15]
	v_mfma_f32_16x16x32_bf16 v[8:11], v[166:169], v[214:217], v[8:11]
	v_mfma_f32_16x16x32_bf16 v[60:63], v[156:159], v[194:197], v[60:63]
	v_mfma_f32_16x16x32_bf16 v[56:59], v[170:173], v[194:197], v[56:59]
	v_mfma_f32_16x16x32_bf16 v[44:47], v[156:159], v[202:205], v[44:47]
	v_mfma_f32_16x16x32_bf16 v[40:43], v[170:173], v[202:205], v[40:43]
	v_mfma_f32_16x16x32_bf16 v[28:31], v[156:159], v[210:213], v[28:31]
	v_mfma_f32_16x16x32_bf16 v[24:27], v[170:173], v[210:213], v[24:27]
	v_mfma_f32_16x16x32_bf16 v[12:15], v[156:159], v[218:221], v[12:15]
	v_mfma_f32_16x16x32_bf16 v[8:11], v[170:173], v[218:221], v[8:11]
	v_mfma_f32_16x16x32_bf16 v[52:55], v[174:177], v[190:193], v[52:55]
	v_mfma_f32_16x16x32_bf16 v[48:51], v[182:185], v[190:193], v[48:51]
	v_mfma_f32_16x16x32_bf16 v[36:39], v[174:177], v[198:201], v[36:39]
	v_mfma_f32_16x16x32_bf16 v[32:35], v[182:185], v[198:201], v[32:35]
	v_mfma_f32_16x16x32_bf16 v[20:23], v[174:177], v[206:209], v[20:23]
	v_mfma_f32_16x16x32_bf16 v[16:19], v[182:185], v[206:209], v[16:19]
	v_mfma_f32_16x16x32_bf16 v[4:7], v[174:177], v[214:217], v[4:7]
	v_mfma_f32_16x16x32_bf16 v[0:3], v[182:185], v[214:217], v[0:3]
	v_mfma_f32_16x16x32_bf16 v[52:55], v[178:181], v[194:197], v[52:55]
	v_mfma_f32_16x16x32_bf16 v[48:51], v[186:189], v[194:197], v[48:51]
	v_mfma_f32_16x16x32_bf16 v[36:39], v[178:181], v[202:205], v[36:39]
	v_mfma_f32_16x16x32_bf16 v[32:35], v[186:189], v[202:205], v[32:35]
	v_mfma_f32_16x16x32_bf16 v[20:23], v[178:181], v[210:213], v[20:23]
	v_mfma_f32_16x16x32_bf16 v[16:19], v[186:189], v[210:213], v[16:19]
	v_mfma_f32_16x16x32_bf16 v[4:7], v[178:181], v[218:221], v[4:7]
	v_mfma_f32_16x16x32_bf16 v[0:3], v[186:189], v[218:221], v[0:3]
	s_setprio 1
	s_barrier
; #define PG8_STAGE(bufoff, gbase, voff) do { _Pragma("unroll") for (int _i = 0; _i < 2; ++_i) \
;         __builtin_amdgcn_global_load_lds((const unsigned*)((const char*)(gbase) + (voff)[_i]), (PG8_LAS unsigned*)(lds + (bufoff) + ldsw + _i * 8192), 16, 0, 0); } while (0)
; #define PG8_LDA(dst, b, h) do { _Pragma("unroll") for (int m = 0; m < 4; ++m) _Pragma("unroll") for (int k = 0; k < 2; ++k) dst[m][k] = *(const PG8_LAS bf16x8*)(lds + PG8_SA(b, h) + aoff + m * 2048 + k * 1024); } while (0)
; #define PG8_LDB(dst, b, h) do { _Pragma("unroll") for (int n = 0; n < 2; ++n) _Pragma("unroll") for (int k = 0; k < 2; ++k) dst[n][k] = *(const PG8_LAS bf16x8*)(lds + PG8_SB(b, h) + boff + n * 2048 + k * 1024); } while (0)
; #define PG8_MMA(ai, bj, At, Bt) do { __builtin_amdgcn_s_setprio(1); _Pragma("unroll") for (int m = 0; m < 4; ++m) _Pragma("unroll") for (int n = 0; n < 2; ++n) _Pragma("unroll") for (int k = 0; k < 2; ++k) \
;         acc[ai][bj][m][n] = __builtin_amdgcn_mfma_f32_16x16x32_bf16(Bt[n][k], At[m][k], acc[ai][bj][m][n], 0, 0, 0); __builtin_amdgcn_s_setprio(0); } while (0)
; #define PG8_WAIT_V(n) asm volatile("s_waitcnt vmcnt(" #n ")" ::: "memory")
; #define PG8_WAIT_L(n) asm volatile("s_waitcnt lgkmcnt(" #n ")" ::: "memory")
; #define PG8_BAR __builtin_amdgcn_s_barrier()
; #define PG8_SCHED __builtin_amdgcn_sched_barrier(0)
; template <class Epi, class Sched, bool ALIGN_EPI = false, bool SP2 = false>
; __device__ __forceinline__ void gemm_phase(PG8_LAS unsigned char* lds, const Gemm g, const Sched& S, const Epi& E) {
;     ...
;             PG8_LDB(B0, 1, 0); PG8_LDB(B1, 1, 1); PG8_SCHED; PG8_LDA(At, 1, 0); PG8_STAGE(PG8_SA(0, 1), a2 + hstepA, voffA);
;             PG8_WAIT_V(8); PG8_WAIT_L(0); PG8_BAR; PG8_MMA(0, 0, At, B0); PG8_MMA(0, 1, At, B1); PG8_BAR; PG8_SCHED;
;             PG8_LDA(At, 1, 1); PG8_STAGE(PG8_SB(1, 0), b3, voffB); PG8_STAGE(PG8_SB(1, 1), b3 + hstepB, voffB); PG8_STAGE(PG8_SA(1, 0), a3, voffA);
;             PG8_WAIT_V(8); PG8_WAIT_L(0); PG8_BAR; PG8_MMA(1, 0, At, B0); PG8_MMA(1, 1, At, B1); PG8_BAR; PG8_SCHED;
	s_add_i32 s63, 0, 0x18000
	v_add_u32_e32 v163, s63, v151
	s_add_i32 s64, 0, 0x1c000
	ds_read_b128 v[144:147], v163
	ds_read_b128 v[156:159], v163 offset:1024
	ds_read_b128 v[166:169], v163 offset:2048
	ds_read_b128 v[170:173], v163 offset:3072
	v_add_u32_e32 v163, s64, v151
	ds_read_b128 v[174:177], v163
	ds_read_b128 v[178:181], v163 offset:1024
	ds_read_b128 v[182:185], v163 offset:2048
	ds_read_b128 v[186:189], v163 offset:3072
	s_add_u32 s48, s48, 0x80000
	s_addc_u32 s49, s49, 0
	s_mov_b32 m0, s33
	ds_read_b128 v[190:193], v155 offset:32768
	ds_read_b128 v[194:197], v155 offset:33792
	ds_read_b128 v[198:201], v155 offset:34816
	ds_read_b128 v[202:205], v155 offset:35840
	ds_read_b128 v[206:209], v155 offset:36864
	ds_read_b128 v[210:213], v155 offset:37888
	ds_read_b128 v[214:217], v155 offset:38912
	ds_read_b128 v[218:221], v155 offset:39936
	global_load_lds_dwordx4 v134, s[48:49]
	s_mov_b32 m0, s34
	s_nop 0
	global_load_lds_dwordx4 v130, s[48:49]
	s_waitcnt vmcnt(8)
	s_waitcnt lgkmcnt(0)
	s_barrier
	s_setprio 0
	s_waitcnt lgkmcnt(0)
	v_mfma_f32_16x16x32_bf16 v[124:127], v[144:147], v[190:193], v[124:127]
	v_mfma_f32_16x16x32_bf16 v[120:123], v[166:169], v[190:193], v[120:123]
	v_mfma_f32_16x16x32_bf16 v[108:111], v[144:147], v[198:201], v[108:111]
	v_mfma_f32_16x16x32_bf16 v[104:107], v[166:169], v[198:201], v[104:107]
	v_mfma_f32_16x16x32_bf16 v[92:95], v[144:147], v[206:209], v[92:95]
	v_mfma_f32_16x16x32_bf16 v[88:91], v[166:169], v[206:209], v[88:91]
	v_mfma_f32_16x16x32_bf16 v[76:79], v[144:147], v[214:217], v[76:79]
	v_mfma_f32_16x16x32_bf16 v[72:75], v[166:169], v[214:217], v[72:75]
	v_mfma_f32_16x16x32_bf16 v[124:127], v[156:159], v[194:197], v[124:127]
	v_mfma_f32_16x16x32_bf16 v[120:123], v[170:173], v[194:197], v[120:123]
	v_mfma_f32_16x16x32_bf16 v[108:111], v[156:159], v[202:205], v[108:111]
	v_mfma_f32_16x16x32_bf16 v[104:107], v[170:173], v[202:205], v[104:107]
	v_mfma_f32_16x16x32_bf16 v[92:95], v[156:159], v[210:213], v[92:95]
	v_mfma_f32_16x16x32_bf16 v[88:91], v[170:173], v[210:213], v[88:91]
	v_mfma_f32_16x16x32_bf16 v[76:79], v[156:159], v[218:221], v[76:79]
	v_mfma_f32_16x16x32_bf16 v[72:75], v[170:173], v[218:221], v[72:75]
	v_mfma_f32_16x16x32_bf16 v[116:119], v[174:177], v[190:193], v[116:119]
	v_mfma_f32_16x16x32_bf16 v[112:115], v[182:185], v[190:193], v[112:115]
	v_mfma_f32_16x16x32_bf16 v[100:103], v[174:177], v[198:201], v[100:103]
	v_mfma_f32_16x16x32_bf16 v[96:99], v[182:185], v[198:201], v[96:99]
	v_mfma_f32_16x16x32_bf16 v[84:87], v[174:177], v[206:209], v[84:87]
	v_mfma_f32_16x16x32_bf16 v[80:83], v[182:185], v[206:209], v[80:83]
	v_mfma_f32_16x16x32_bf16 v[68:71], v[174:177], v[214:217], v[68:71]
	v_mfma_f32_16x16x32_bf16 v[64:67], v[182:185], v[214:217], v[64:67]
	v_mfma_f32_16x16x32_bf16 v[116:119], v[178:181], v[194:197], v[116:119]
	v_mfma_f32_16x16x32_bf16 v[112:115], v[186:189], v[194:197], v[112:115]
	v_mfma_f32_16x16x32_bf16 v[100:103], v[178:181], v[202:205], v[100:103]
	v_mfma_f32_16x16x32_bf16 v[96:99], v[186:189], v[202:205], v[96:99]
	v_mfma_f32_16x16x32_bf16 v[84:87], v[178:181], v[210:213], v[84:87]
	v_mfma_f32_16x16x32_bf16 v[80:83], v[186:189], v[210:213], v[80:83]
	v_mfma_f32_16x16x32_bf16 v[68:71], v[178:181], v[218:221], v[68:71]
	v_mfma_f32_16x16x32_bf16 v[64:67], v[186:189], v[218:221], v[64:67]
	s_setprio 1
	s_barrier
	s_add_i32 s48, s63, s28
	v_lshl_add_u64 v[148:149], v[148:149], 0, s[10:11]
	s_mov_b32 m0, s48
	ds_read_b128 v[190:193], v155 offset:49152
	ds_read_b128 v[194:197], v155 offset:50176
	ds_read_b128 v[198:201], v155 offset:51200
	ds_read_b128 v[202:205], v155 offset:52224
	ds_read_b128 v[206:209], v155 offset:53248
	ds_read_b128 v[210:213], v155 offset:54272
	ds_read_b128 v[214:217], v155 offset:55296
	ds_read_b128 v[218:221], v155 offset:56320
	global_load_lds_dwordx4 v[148:149], off
	s_add_i32 m0, s48, 0x2000
	s_add_u32 s46, s46, 0x80080
	v_lshl_add_u64 v[148:149], v[160:161], 0, s[10:11]
	s_addc_u32 s47, s47, 0
	s_add_i32 s48, s64, s28
	global_load_lds_dwordx4 v[148:149], off
	s_mov_b32 m0, s48
	s_nop 0
	global_load_lds_dwordx4 v132, s[46:47]
	s_add_i32 m0, s48, 0x2000
	s_nop 0
	global_load_lds_dwordx4 v128, s[46:47]
	v_lshl_add_u64 v[148:149], v[222:223], 0, s[10:11]
	s_mov_b32 m0, s43
	s_nop 0
	global_load_lds_dwordx4 v[148:149], off
	v_lshl_add_u64 v[148:149], v[224:225], 0, s[10:11]
	s_mov_b32 m0, s50
	s_nop 0
	global_load_lds_dwordx4 v[148:149], off
	s_waitcnt vmcnt(8)
	s_waitcnt lgkmcnt(0)
	s_barrier
	s_setprio 0
	s_waitcnt lgkmcnt(0)
	v_mfma_f32_16x16x32_bf16 v[60:63], v[144:147], v[190:193], v[60:63]
	v_mfma_f32_16x16x32_bf16 v[56:59], v[166:169], v[190:193], v[56:59]
	v_mfma_f32_16x16x32_bf16 v[44:47], v[144:147], v[198:201], v[44:47]
	v_mfma_f32_16x16x32_bf16 v[40:43], v[166:169], v[198:201], v[40:43]
	v_mfma_f32_16x16x32_bf16 v[28:31], v[144:147], v[206:209], v[28:31]
	v_mfma_f32_16x16x32_bf16 v[24:27], v[166:169], v[206:209], v[24:27]
	v_mfma_f32_16x16x32_bf16 v[12:15], v[144:147], v[214:217], v[12:15]
	v_mfma_f32_16x16x32_bf16 v[8:11], v[166:169], v[214:217], v[8:11]
	v_mfma_f32_16x16x32_bf16 v[60:63], v[156:159], v[194:197], v[60:63]
	v_mfma_f32_16x16x32_bf16 v[56:59], v[170:173], v[194:197], v[56:59]
	v_mfma_f32_16x16x32_bf16 v[44:47], v[156:159], v[202:205], v[44:47]
	v_mfma_f32_16x16x32_bf16 v[40:43], v[170:173], v[202:205], v[40:43]
	v_mfma_f32_16x16x32_bf16 v[28:31], v[156:159], v[210:213], v[28:31]
	v_mfma_f32_16x16x32_bf16 v[24:27], v[170:173], v[210:213], v[24:27]
	v_mfma_f32_16x16x32_bf16 v[12:15], v[156:159], v[218:221], v[12:15]
	v_mfma_f32_16x16x32_bf16 v[8:11], v[170:173], v[218:221], v[8:11]
	v_mfma_f32_16x16x32_bf16 v[52:55], v[174:177], v[190:193], v[52:55]
	v_mfma_f32_16x16x32_bf16 v[48:51], v[182:185], v[190:193], v[48:51]
	v_mfma_f32_16x16x32_bf16 v[36:39], v[174:177], v[198:201], v[36:39]
	v_mfma_f32_16x16x32_bf16 v[32:35], v[182:185], v[198:201], v[32:35]
	v_mfma_f32_16x16x32_bf16 v[20:23], v[174:177], v[206:209], v[20:23]
	v_mfma_f32_16x16x32_bf16 v[16:19], v[182:185], v[206:209], v[16:19]
	v_mfma_f32_16x16x32_bf16 v[4:7], v[174:177], v[214:217], v[4:7]
	v_mfma_f32_16x16x32_bf16 v[0:3], v[182:185], v[214:217], v[0:3]
	v_mfma_f32_16x16x32_bf16 v[52:55], v[178:181], v[194:197], v[52:55]
	v_mfma_f32_16x16x32_bf16 v[48:51], v[186:189], v[194:197], v[48:51]
	v_mfma_f32_16x16x32_bf16 v[36:39], v[178:181], v[202:205], v[36:39]
	v_mfma_f32_16x16x32_bf16 v[32:35], v[186:189], v[202:205], v[32:35]
	v_mfma_f32_16x16x32_bf16 v[20:23], v[178:181], v[210:213], v[20:23]
	v_mfma_f32_16x16x32_bf16 v[16:19], v[186:189], v[210:213], v[16:19]
	v_mfma_f32_16x16x32_bf16 v[4:7], v[178:181], v[218:221], v[4:7]
	v_mfma_f32_16x16x32_bf16 v[0:3], v[186:189], v[218:221], v[0:3]
	s_setprio 1
	s_barrier
	s_add_i32 s62, s62, 2
	s_add_u32 s44, s44, 0x100
	s_addc_u32 s45, s45, 0
	s_add_u32 s60, s60, 0x100
	s_addc_u32 s61, s61, 0
	s_cmp_gt_u32 s62, 29
	s_cbranch_scc0 .LBB0_1333
	s_and_b64 vcc, exec, s[14:15]
	s_cbranch_vccz .LBB0_1336
	s_barrier
